# P1 weight-copy stores use the default (write-back) policy instead of nontemporal, now that most workgroups convert after GEMM1 (dirty lines drain under P2)
# baseline (speedup 1.0000x reference)
.LBB0_205:
	s_cmpk_gt_i32 s2, 0x1f7f
	s_mov_b32 s8, 49
	s_cbranch_scc1 .LBB0_218
	s_cmpk_gt_i32 s2, 0x3ff
	s_mov_b64 s[0:1], -1
	s_cbranch_scc0 .LBB0_216
	s_cmpk_gt_u32 s2, 0x5ff
	s_cbranch_scc0 .LBB0_213
	s_lshl_b32 s0, s2, 6
	s_and_b32 s3, s0, 0xfc0
	s_cmpk_gt_u32 s2, 0x9ff
	s_mov_b64 s[0:1], -1
	v_or_b32_e32 v144, s3, v162
	v_or_b32_e32 v146, s3, v164
	v_or_b32_e32 v149, s3, v165
	v_or_b32_e32 v148, s3, v166
	v_or_b32_e32 v152, s3, v167
	v_or_b32_e32 v154, s3, v168
	v_or_b32_e32 v156, s3, v169
	v_or_b32_e32 v172, s3, v170
	s_cbranch_scc0 .LBB0_210
	s_lshl_b32 s0, s2, 1
	s_and_b32 s0, s0, 0x7fffff80
	s_addk_i32 s0, 0xec00
	v_or_b32_e32 v2, s0, v130
	v_readlane_b32 s46, v248, 39
	v_lshlrev_b32_e32 v2, 12, v2
	v_mov_b32_e32 v3, v133
	v_readlane_b32 s47, v248, 40
	s_lshl_b32 s8, s3, 2
	s_nop 0
	v_lshl_add_u64 v[2:3], v[2:3], 2, s[46:47]
	v_lshl_add_u64 v[2:3], v[2:3], 0, s[8:9]
	v_lshl_add_u64 v[58:59], v[2:3], 0, v[132:133]
	v_add_co_u32_e32 v2, vcc, s11, v58
	s_nop 1
	v_addc_co_u32_e32 v3, vcc, 0, v59, vcc
	global_load_dwordx4 v[66:69], v[58:59], off nt
	global_load_dwordx4 v[70:73], v[2:3], off nt
	v_add_co_u32_e32 v2, vcc, s12, v58
	s_nop 1
	v_addc_co_u32_e32 v3, vcc, 0, v59, vcc
	v_add_co_u32_e32 v4, vcc, s13, v58
	s_nop 1
	v_addc_co_u32_e32 v5, vcc, 0, v59, vcc
	global_load_dwordx4 v[74:77], v[2:3], off nt
	global_load_dwordx4 v[78:81], v[4:5], off nt
	v_add_co_u32_e32 v2, vcc, s16, v58
	s_nop 1
	v_addc_co_u32_e32 v3, vcc, 0, v59, vcc
	v_add_co_u32_e32 v4, vcc, s17, v58
	s_nop 1
	v_addc_co_u32_e32 v5, vcc, 0, v59, vcc
	global_load_dwordx4 v[82:85], v[2:3], off nt
	global_load_dwordx4 v[86:89], v[4:5], off nt
	v_add_co_u32_e32 v2, vcc, s18, v58
	s_nop 1
	v_addc_co_u32_e32 v3, vcc, 0, v59, vcc
	v_add_co_u32_e32 v4, vcc, s19, v58
	s_nop 1
	v_addc_co_u32_e32 v5, vcc, 0, v59, vcc
	global_load_dwordx4 v[90:93], v[2:3], off nt
	global_load_dwordx4 v[94:97], v[4:5], off nt
	v_add_co_u32_e32 v2, vcc, s20, v58
	s_nop 1
	v_addc_co_u32_e32 v3, vcc, 0, v59, vcc
	v_add_co_u32_e32 v4, vcc, s21, v58
	s_nop 1
	v_addc_co_u32_e32 v5, vcc, 0, v59, vcc
	global_load_dwordx4 v[98:101], v[2:3], off nt
	global_load_dwordx4 v[102:105], v[4:5], off nt
	v_add_co_u32_e32 v2, vcc, s22, v58
	s_nop 1
	v_addc_co_u32_e32 v3, vcc, 0, v59, vcc
	v_add_co_u32_e32 v4, vcc, s23, v58
	s_nop 1
	v_addc_co_u32_e32 v5, vcc, 0, v59, vcc
	global_load_dwordx4 v[106:109], v[2:3], off nt
	global_load_dwordx4 v[110:113], v[4:5], off nt
	v_add_co_u32_e32 v2, vcc, s28, v58
	s_nop 1
	v_addc_co_u32_e32 v3, vcc, 0, v59, vcc
	v_add_co_u32_e32 v4, vcc, s29, v58
	s_nop 1
	v_addc_co_u32_e32 v5, vcc, 0, v59, vcc
	global_load_dwordx4 v[114:117], v[2:3], off nt
	global_load_dwordx4 v[118:121], v[4:5], off nt
	v_add_co_u32_e32 v2, vcc, s34, v58
	s_nop 1
	v_addc_co_u32_e32 v3, vcc, 0, v59, vcc
	v_add_co_u32_e32 v4, vcc, s35, v58
	s_nop 1
	v_addc_co_u32_e32 v5, vcc, 0, v59, vcc
	global_load_dwordx4 v[122:125], v[2:3], off nt
	global_load_dwordx4 v[126:129], v[4:5], off nt
	v_add_co_u32_e32 v2, vcc, s36, v58
	s_mov_b32 s1, s9
	s_nop 0
	v_addc_co_u32_e32 v3, vcc, 0, v59, vcc
	v_add_co_u32_e32 v6, vcc, s37, v58
	s_lshl_b64 s[0:1], s[0:1], 1
	s_nop 0
	v_addc_co_u32_e32 v7, vcc, 0, v59, vcc
	v_add_co_u32_e32 v10, vcc, s38, v58
	global_load_dwordx4 v[2:5], v[2:3], off nt
	s_nop 0
	global_load_dwordx4 v[6:9], v[6:7], off nt
	v_addc_co_u32_e32 v11, vcc, 0, v59, vcc
	v_add_co_u32_e32 v14, vcc, s39, v58
	v_readlane_b32 s8, v248, 33
	s_nop 0
	v_addc_co_u32_e32 v15, vcc, 0, v59, vcc
	v_add_co_u32_e32 v18, vcc, s40, v58
	global_load_dwordx4 v[10:13], v[10:11], off nt
	s_nop 0
	global_load_dwordx4 v[14:17], v[14:15], off nt
	v_addc_co_u32_e32 v19, vcc, 0, v59, vcc
	v_add_co_u32_e32 v22, vcc, s41, v58
	s_add_u32 s0, s8, s0
	s_nop 0
	v_addc_co_u32_e32 v23, vcc, 0, v59, vcc
	v_add_co_u32_e32 v26, vcc, s42, v58
	global_load_dwordx4 v[18:21], v[18:19], off nt
	s_nop 0
	global_load_dwordx4 v[22:25], v[22:23], off nt
	v_addc_co_u32_e32 v27, vcc, 0, v59, vcc
	v_add_co_u32_e32 v30, vcc, s43, v58
	v_readlane_b32 s8, v248, 47
	s_nop 0
	v_addc_co_u32_e32 v31, vcc, 0, v59, vcc
	v_add_co_u32_e32 v34, vcc, s44, v58
	global_load_dwordx4 v[26:29], v[26:27], off nt
	s_nop 0
	global_load_dwordx4 v[30:33], v[30:31], off nt
	v_addc_co_u32_e32 v35, vcc, 0, v59, vcc
	v_add_co_u32_e32 v38, vcc, s45, v58
	s_addc_u32 s1, s8, s1
	s_nop 0
	v_addc_co_u32_e32 v39, vcc, 0, v59, vcc
	v_add_co_u32_e32 v42, vcc, s50, v58
	global_load_dwordx4 v[34:37], v[34:35], off nt
	s_nop 0
	global_load_dwordx4 v[38:41], v[38:39], off nt
	v_addc_co_u32_e32 v43, vcc, 0, v59, vcc
	v_add_co_u32_e32 v46, vcc, s51, v58
	v_mov_b32_e32 v141, v133
	s_nop 0
	v_addc_co_u32_e32 v47, vcc, 0, v59, vcc
	v_add_co_u32_e32 v50, vcc, s74, v58
	global_load_dwordx4 v[42:45], v[42:43], off nt
	s_nop 0
	global_load_dwordx4 v[46:49], v[46:47], off nt
	v_addc_co_u32_e32 v51, vcc, 0, v59, vcc
	v_add_co_u32_e32 v54, vcc, s75, v58
	v_lshl_add_u64 v[142:143], s[0:1], 0, v[140:141]
	s_nop 0
	v_addc_co_u32_e32 v55, vcc, 0, v59, vcc
	v_add_co_u32_e32 v60, vcc, s76, v58
	global_load_dwordx4 v[50:53], v[50:51], off nt
	s_nop 0
	global_load_dwordx4 v[54:57], v[54:55], off nt
	v_addc_co_u32_e32 v61, vcc, 0, v59, vcc
	v_add_co_u32_e32 v62, vcc, s77, v58
	s_nop 1
	v_addc_co_u32_e32 v63, vcc, 0, v59, vcc
	global_load_dwordx4 v[58:61], v[60:61], off nt
	s_nop 0
	global_load_dwordx4 v[62:65], v[62:63], off nt
	s_waitcnt vmcnt(31)
	v_bfe_u32 v145, v66, 16, 1
	v_add3_u32 v66, v66, v145, s78
	s_waitcnt vmcnt(30)
	v_bfe_u32 v145, v70, 16, 1
	v_lshrrev_b32_e32 v66, 16, v66
	v_add3_u32 v70, v70, v145, s78
	v_and_or_b32 v174, v70, s79, v66
	s_waitcnt vmcnt(29)
	v_bfe_u32 v66, v74, 16, 1
	v_add3_u32 v66, v74, v66, s78
	s_waitcnt vmcnt(28)
	v_bfe_u32 v70, v78, 16, 1
	v_lshrrev_b32_e32 v66, 16, v66
	v_add3_u32 v70, v78, v70, s78
	v_and_or_b32 v175, v70, s79, v66
	s_waitcnt vmcnt(27)
	v_bfe_u32 v66, v82, 16, 1
	v_add3_u32 v66, v82, v66, s78
	s_waitcnt vmcnt(26)
	v_bfe_u32 v70, v86, 16, 1
	v_lshrrev_b32_e32 v66, 16, v66
	v_add3_u32 v70, v86, v70, s78
	v_and_or_b32 v176, v70, s79, v66
	s_waitcnt vmcnt(25)
	v_bfe_u32 v66, v90, 16, 1
	v_add3_u32 v66, v90, v66, s78
	s_waitcnt vmcnt(24)
	v_bfe_u32 v70, v94, 16, 1
	v_lshrrev_b32_e32 v66, 16, v66
	v_add3_u32 v70, v94, v70, s78
	v_and_or_b32 v177, v70, s79, v66
	s_waitcnt vmcnt(23)
	v_bfe_u32 v66, v98, 16, 1
	v_add3_u32 v66, v98, v66, s78
	s_waitcnt vmcnt(22)
	v_bfe_u32 v70, v102, 16, 1
	v_lshrrev_b32_e32 v66, 16, v66
	v_add3_u32 v70, v102, v70, s78
	v_and_or_b32 v178, v70, s79, v66
	s_waitcnt vmcnt(21)
	v_bfe_u32 v66, v106, 16, 1
	v_add3_u32 v66, v106, v66, s78
	s_waitcnt vmcnt(20)
	v_bfe_u32 v70, v110, 16, 1
	v_lshrrev_b32_e32 v66, 16, v66
	v_add3_u32 v70, v110, v70, s78
	v_and_or_b32 v179, v70, s79, v66
	s_waitcnt vmcnt(19)
	v_bfe_u32 v66, v114, 16, 1
	v_add3_u32 v66, v114, v66, s78
	s_waitcnt vmcnt(18)
	v_bfe_u32 v70, v118, 16, 1
	v_lshrrev_b32_e32 v66, 16, v66
	v_add3_u32 v70, v118, v70, s78
	v_and_or_b32 v180, v70, s79, v66
	s_waitcnt vmcnt(17)
	v_bfe_u32 v66, v122, 16, 1
	v_add3_u32 v66, v122, v66, s78
	s_waitcnt vmcnt(16)
	v_bfe_u32 v70, v126, 16, 1
	v_lshrrev_b32_e32 v66, 16, v66
	v_add3_u32 v70, v126, v70, s78
	v_and_or_b32 v181, v70, s79, v66
	v_bfe_u32 v66, v67, 16, 1
	v_add3_u32 v66, v67, v66, s78
	v_bfe_u32 v67, v71, 16, 1
	v_lshrrev_b32_e32 v66, 16, v66
	v_add3_u32 v67, v71, v67, s78
	ds_write_b128 v163, v[174:177]
	ds_write_b128 v163, v[178:181] offset:16
	v_and_or_b32 v174, v67, s79, v66
	v_bfe_u32 v66, v75, 16, 1
	v_add3_u32 v66, v75, v66, s78
	v_bfe_u32 v67, v79, 16, 1
	v_lshrrev_b32_e32 v66, 16, v66
	v_add3_u32 v67, v79, v67, s78
	v_and_or_b32 v175, v67, s79, v66
	v_bfe_u32 v66, v83, 16, 1
	v_add3_u32 v66, v83, v66, s78
	v_bfe_u32 v67, v87, 16, 1
	v_lshrrev_b32_e32 v66, 16, v66
	v_add3_u32 v67, v87, v67, s78
	v_and_or_b32 v176, v67, s79, v66
	v_bfe_u32 v66, v91, 16, 1
	v_add3_u32 v66, v91, v66, s78
	v_bfe_u32 v67, v95, 16, 1
	v_lshrrev_b32_e32 v66, 16, v66
	v_add3_u32 v67, v95, v67, s78
	v_and_or_b32 v177, v67, s79, v66
	v_bfe_u32 v66, v99, 16, 1
	v_add3_u32 v66, v99, v66, s78
	v_bfe_u32 v67, v103, 16, 1
	v_lshrrev_b32_e32 v66, 16, v66
	v_add3_u32 v67, v103, v67, s78
	v_and_or_b32 v178, v67, s79, v66
	v_bfe_u32 v66, v107, 16, 1
	v_add3_u32 v66, v107, v66, s78
	v_bfe_u32 v67, v111, 16, 1
	v_lshrrev_b32_e32 v66, 16, v66
	v_add3_u32 v67, v111, v67, s78
	v_and_or_b32 v179, v67, s79, v66
	v_bfe_u32 v66, v115, 16, 1
	v_add3_u32 v66, v115, v66, s78
	v_bfe_u32 v67, v119, 16, 1
	v_lshrrev_b32_e32 v66, 16, v66
	v_add3_u32 v67, v119, v67, s78
	v_and_or_b32 v180, v67, s79, v66
	v_bfe_u32 v66, v123, 16, 1
	v_add3_u32 v66, v123, v66, s78
	v_bfe_u32 v67, v127, 16, 1
	v_lshrrev_b32_e32 v66, 16, v66
	v_add3_u32 v67, v127, v67, s78
	v_and_or_b32 v181, v67, s79, v66
	v_bfe_u32 v66, v68, 16, 1
	v_add3_u32 v66, v68, v66, s78
	v_bfe_u32 v67, v72, 16, 1
	v_lshrrev_b32_e32 v66, 16, v66
	v_add3_u32 v67, v72, v67, s78
	ds_write_b128 v163, v[174:177] offset:144
	ds_write_b128 v163, v[178:181] offset:160
	v_and_or_b32 v174, v67, s79, v66
	v_bfe_u32 v66, v76, 16, 1
	v_add3_u32 v66, v76, v66, s78
	v_bfe_u32 v67, v80, 16, 1
	v_lshrrev_b32_e32 v66, 16, v66
	v_add3_u32 v67, v80, v67, s78
	v_and_or_b32 v175, v67, s79, v66
	v_bfe_u32 v66, v84, 16, 1
	v_add3_u32 v66, v84, v66, s78
	v_bfe_u32 v67, v88, 16, 1
	v_lshrrev_b32_e32 v66, 16, v66
	v_add3_u32 v67, v88, v67, s78
	v_and_or_b32 v176, v67, s79, v66
	v_bfe_u32 v66, v92, 16, 1
	v_add3_u32 v66, v92, v66, s78
	v_bfe_u32 v67, v96, 16, 1
	v_lshrrev_b32_e32 v66, 16, v66
	v_add3_u32 v67, v96, v67, s78
	v_and_or_b32 v177, v67, s79, v66
	v_bfe_u32 v66, v100, 16, 1
	v_add3_u32 v66, v100, v66, s78
	v_bfe_u32 v67, v104, 16, 1
	v_lshrrev_b32_e32 v66, 16, v66
	v_add3_u32 v67, v104, v67, s78
	v_and_or_b32 v178, v67, s79, v66
	v_bfe_u32 v66, v108, 16, 1
	v_add3_u32 v66, v108, v66, s78
	v_bfe_u32 v67, v112, 16, 1
	v_lshrrev_b32_e32 v66, 16, v66
	v_add3_u32 v67, v112, v67, s78
	v_and_or_b32 v179, v67, s79, v66
	v_bfe_u32 v66, v116, 16, 1
	v_add3_u32 v66, v116, v66, s78
	v_bfe_u32 v67, v120, 16, 1
	v_lshrrev_b32_e32 v66, 16, v66
	v_add3_u32 v67, v120, v67, s78
	v_and_or_b32 v180, v67, s79, v66
	v_bfe_u32 v66, v124, 16, 1
	v_add3_u32 v66, v124, v66, s78
	v_bfe_u32 v67, v128, 16, 1
	v_lshrrev_b32_e32 v66, 16, v66
	v_add3_u32 v67, v128, v67, s78
	v_and_or_b32 v181, v67, s79, v66
	v_bfe_u32 v66, v69, 16, 1
	v_add3_u32 v66, v69, v66, s78
	v_bfe_u32 v67, v73, 16, 1
	v_lshrrev_b32_e32 v66, 16, v66
	v_add3_u32 v67, v73, v67, s78
	v_and_or_b32 v66, v67, s79, v66
	v_bfe_u32 v67, v77, 16, 1
	v_add3_u32 v67, v77, v67, s78
	v_bfe_u32 v68, v81, 16, 1
	v_lshrrev_b32_e32 v67, 16, v67
	v_add3_u32 v68, v81, v68, s78
	v_and_or_b32 v67, v68, s79, v67
	v_bfe_u32 v68, v85, 16, 1
	v_add3_u32 v68, v85, v68, s78
	v_bfe_u32 v69, v89, 16, 1
	v_lshrrev_b32_e32 v68, 16, v68
	v_add3_u32 v69, v89, v69, s78
	v_and_or_b32 v68, v69, s79, v68
	v_bfe_u32 v69, v93, 16, 1
	v_add3_u32 v69, v93, v69, s78
	v_bfe_u32 v70, v97, 16, 1
	v_lshrrev_b32_e32 v69, 16, v69
	v_add3_u32 v70, v97, v70, s78
	v_and_or_b32 v69, v70, s79, v69
	v_bfe_u32 v70, v101, 16, 1
	v_add3_u32 v70, v101, v70, s78
	v_bfe_u32 v71, v105, 16, 1
	v_lshrrev_b32_e32 v70, 16, v70
	v_add3_u32 v71, v105, v71, s78
	v_and_or_b32 v70, v71, s79, v70
	v_bfe_u32 v71, v109, 16, 1
	v_add3_u32 v71, v109, v71, s78
	v_bfe_u32 v72, v113, 16, 1
	v_lshrrev_b32_e32 v71, 16, v71
	v_add3_u32 v72, v113, v72, s78
	v_and_or_b32 v71, v72, s79, v71
	v_bfe_u32 v72, v117, 16, 1
	v_add3_u32 v72, v117, v72, s78
	v_bfe_u32 v73, v121, 16, 1
	v_lshrrev_b32_e32 v72, 16, v72
	v_add3_u32 v73, v121, v73, s78
	v_and_or_b32 v72, v73, s79, v72
	v_bfe_u32 v73, v125, 16, 1
	v_add3_u32 v73, v125, v73, s78
	v_bfe_u32 v74, v129, 16, 1
	v_lshrrev_b32_e32 v73, 16, v73
	v_add3_u32 v74, v129, v74, s78
	ds_write_b128 v163, v[174:177] offset:288
	ds_write_b128 v163, v[178:181] offset:304
	v_and_or_b32 v73, v74, s79, v73
	ds_write_b128 v163, v[66:69] offset:432
	ds_write_b128 v163, v[70:73] offset:448
	s_waitcnt lgkmcnt(0)
	ds_read_b128 v[68:71], v171
	ds_read_b128 v[72:75], v171 offset:1152
	v_mul_u32_u24_e32 v66, 0x2b00, v144
	v_lshlrev_b32_e32 v66, 1, v66
	v_mov_b32_e32 v67, v133
	v_lshl_add_u64 v[76:77], v[142:143], 0, v[66:67]
	s_waitcnt lgkmcnt(1)
	global_store_dwordx4 v[76:77], v[68:71], off
	ds_read_b128 v[76:79], v171 offset:3456
	s_nop 0
	v_mul_u32_u24_e32 v68, 0x2b00, v146
	v_lshlrev_b32_e32 v68, 1, v68
	v_mov_b32_e32 v69, v133
	v_lshl_add_u64 v[70:71], v[142:143], 0, v[68:69]
	s_waitcnt lgkmcnt(1)
	global_store_dwordx4 v[70:71], v[72:75], off
	ds_read_b128 v[72:75], v171 offset:2304
	v_mul_u32_u24_e32 v70, 0x2b00, v149
	v_lshlrev_b32_e32 v70, 1, v70
	v_mov_b32_e32 v71, v133
	v_lshl_add_u64 v[80:81], v[142:143], 0, v[70:71]
	s_waitcnt lgkmcnt(0)
	global_store_dwordx4 v[80:81], v[72:75], off
	ds_read_b128 v[80:83], v171 offset:5760
	s_nop 0
	v_mul_u32_u24_e32 v72, 0x2b00, v148
	v_lshlrev_b32_e32 v72, 1, v72
	v_mov_b32_e32 v73, v133
	v_lshl_add_u64 v[74:75], v[142:143], 0, v[72:73]
	global_store_dwordx4 v[74:75], v[76:79], off
	ds_read_b128 v[76:79], v171 offset:4608
	v_mul_u32_u24_e32 v74, 0x2b00, v152
	v_lshlrev_b32_e32 v74, 1, v74
	v_mov_b32_e32 v75, v133
	v_lshl_add_u64 v[84:85], v[142:143], 0, v[74:75]
	s_waitcnt lgkmcnt(0)
	global_store_dwordx4 v[84:85], v[76:79], off
	ds_read_b128 v[84:87], v171 offset:8064
	s_nop 0
	v_mul_u32_u24_e32 v76, 0x2b00, v154
	v_lshlrev_b32_e32 v76, 1, v76
	v_mov_b32_e32 v77, v133
	v_lshl_add_u64 v[78:79], v[142:143], 0, v[76:77]
	global_store_dwordx4 v[78:79], v[80:83], off
	ds_read_b128 v[80:83], v171 offset:6912
	v_mul_u32_u24_e32 v78, 0x2b00, v156
	v_lshlrev_b32_e32 v78, 1, v78
	v_mov_b32_e32 v79, v133
	v_lshl_add_u64 v[88:89], v[142:143], 0, v[78:79]
	s_waitcnt lgkmcnt(0)
	global_store_dwordx4 v[88:89], v[80:83], off
	s_nop 1
	v_mul_u32_u24_e32 v80, 0x2b00, v172
	v_lshlrev_b32_e32 v80, 1, v80
	v_mov_b32_e32 v81, v133
	v_lshl_add_u64 v[82:83], v[142:143], 0, v[80:81]
	global_store_dwordx4 v[82:83], v[84:87], off
	s_waitcnt vmcnt(23)
	v_bfe_u32 v82, v2, 16, 1
	v_add3_u32 v2, v2, v82, s78
	s_waitcnt vmcnt(22)
	v_bfe_u32 v82, v6, 16, 1
	v_lshrrev_b32_e32 v2, 16, v2
	v_add3_u32 v6, v6, v82, s78
	v_and_or_b32 v82, v6, s79, v2
	s_waitcnt vmcnt(21)
	v_bfe_u32 v2, v10, 16, 1
	v_add3_u32 v2, v10, v2, s78
	s_waitcnt vmcnt(20)
	v_bfe_u32 v6, v14, 16, 1
	v_lshrrev_b32_e32 v2, 16, v2
	v_add3_u32 v6, v14, v6, s78
	v_and_or_b32 v83, v6, s79, v2
	s_waitcnt vmcnt(19)
	v_bfe_u32 v2, v18, 16, 1
	v_add3_u32 v2, v18, v2, s78
	s_waitcnt vmcnt(18)
	v_bfe_u32 v6, v22, 16, 1
	v_lshrrev_b32_e32 v2, 16, v2
	v_add3_u32 v6, v22, v6, s78
	v_and_or_b32 v84, v6, s79, v2
	s_waitcnt vmcnt(17)
	v_bfe_u32 v2, v26, 16, 1
	v_add3_u32 v2, v26, v2, s78
	s_waitcnt vmcnt(16)
	v_bfe_u32 v6, v30, 16, 1
	v_lshrrev_b32_e32 v2, 16, v2
	v_add3_u32 v6, v30, v6, s78
	v_and_or_b32 v85, v6, s79, v2
	s_waitcnt vmcnt(15)
	v_bfe_u32 v2, v34, 16, 1
	v_add3_u32 v2, v34, v2, s78
	s_waitcnt vmcnt(14)
	v_bfe_u32 v6, v38, 16, 1
	v_lshrrev_b32_e32 v2, 16, v2
	v_add3_u32 v6, v38, v6, s78
	v_and_or_b32 v86, v6, s79, v2
	s_waitcnt vmcnt(13)
	v_bfe_u32 v2, v42, 16, 1
	v_add3_u32 v2, v42, v2, s78
	s_waitcnt vmcnt(12)
	v_bfe_u32 v6, v46, 16, 1
	v_lshrrev_b32_e32 v2, 16, v2
	v_add3_u32 v6, v46, v6, s78
	v_and_or_b32 v87, v6, s79, v2
	s_waitcnt vmcnt(11)
	v_bfe_u32 v2, v50, 16, 1
	v_add3_u32 v2, v50, v2, s78
	s_waitcnt vmcnt(10)
	v_bfe_u32 v6, v54, 16, 1
	v_lshrrev_b32_e32 v2, 16, v2
	v_add3_u32 v6, v54, v6, s78
	v_and_or_b32 v88, v6, s79, v2
	s_waitcnt vmcnt(9)
	v_bfe_u32 v2, v58, 16, 1
	v_add3_u32 v2, v58, v2, s78
	s_waitcnt vmcnt(8)
	v_bfe_u32 v6, v62, 16, 1
	v_lshrrev_b32_e32 v2, 16, v2
	v_add3_u32 v6, v62, v6, s78
	v_and_or_b32 v89, v6, s79, v2
	v_bfe_u32 v2, v3, 16, 1
	v_add3_u32 v2, v3, v2, s78
	v_bfe_u32 v3, v7, 16, 1
	s_waitcnt lgkmcnt(0)
	v_lshrrev_b32_e32 v2, 16, v2
	v_add3_u32 v3, v7, v3, s78
	ds_write_b128 v163, v[82:85]
	ds_write_b128 v163, v[86:89] offset:16
	v_and_or_b32 v82, v3, s79, v2
	v_bfe_u32 v2, v11, 16, 1
	v_add3_u32 v2, v11, v2, s78
	v_bfe_u32 v3, v15, 16, 1
	v_lshrrev_b32_e32 v2, 16, v2
	v_add3_u32 v3, v15, v3, s78
	v_and_or_b32 v83, v3, s79, v2
	v_bfe_u32 v2, v19, 16, 1
	v_add3_u32 v2, v19, v2, s78
	v_bfe_u32 v3, v23, 16, 1
	v_lshrrev_b32_e32 v2, 16, v2
	v_add3_u32 v3, v23, v3, s78
	v_and_or_b32 v84, v3, s79, v2
	v_bfe_u32 v2, v27, 16, 1
	v_add3_u32 v2, v27, v2, s78
	v_bfe_u32 v3, v31, 16, 1
	v_lshrrev_b32_e32 v2, 16, v2
	v_add3_u32 v3, v31, v3, s78
	v_and_or_b32 v85, v3, s79, v2
	v_bfe_u32 v2, v35, 16, 1
	v_add3_u32 v2, v35, v2, s78
	v_bfe_u32 v3, v39, 16, 1
	v_lshrrev_b32_e32 v2, 16, v2
	v_add3_u32 v3, v39, v3, s78
	v_and_or_b32 v86, v3, s79, v2
	v_bfe_u32 v2, v43, 16, 1
	v_add3_u32 v2, v43, v2, s78
	v_bfe_u32 v3, v47, 16, 1
	v_lshrrev_b32_e32 v2, 16, v2
	v_add3_u32 v3, v47, v3, s78
	v_and_or_b32 v87, v3, s79, v2
	v_bfe_u32 v2, v51, 16, 1
	v_add3_u32 v2, v51, v2, s78
	v_bfe_u32 v3, v55, 16, 1
	v_lshrrev_b32_e32 v2, 16, v2
	v_add3_u32 v3, v55, v3, s78
	v_and_or_b32 v88, v3, s79, v2
	v_bfe_u32 v2, v59, 16, 1
	v_add3_u32 v2, v59, v2, s78
	v_bfe_u32 v3, v63, 16, 1
	v_lshrrev_b32_e32 v2, 16, v2
	v_add3_u32 v3, v63, v3, s78
	v_and_or_b32 v89, v3, s79, v2
	v_bfe_u32 v2, v4, 16, 1
	v_add3_u32 v2, v4, v2, s78
	v_bfe_u32 v3, v8, 16, 1
	v_lshrrev_b32_e32 v2, 16, v2
	v_add3_u32 v3, v8, v3, s78
	ds_write_b128 v163, v[82:85] offset:144
	ds_write_b128 v163, v[86:89] offset:160
	v_and_or_b32 v82, v3, s79, v2
	v_bfe_u32 v2, v12, 16, 1
	v_add3_u32 v2, v12, v2, s78
	v_bfe_u32 v3, v16, 16, 1
	v_lshrrev_b32_e32 v2, 16, v2
	v_add3_u32 v3, v16, v3, s78
	v_and_or_b32 v83, v3, s79, v2
	v_bfe_u32 v2, v20, 16, 1
	v_add3_u32 v2, v20, v2, s78
	v_bfe_u32 v3, v24, 16, 1
	v_lshrrev_b32_e32 v2, 16, v2
	v_add3_u32 v3, v24, v3, s78
	v_and_or_b32 v84, v3, s79, v2
	v_bfe_u32 v2, v28, 16, 1
	v_add3_u32 v2, v28, v2, s78
	v_bfe_u32 v3, v32, 16, 1
	v_lshrrev_b32_e32 v2, 16, v2
	v_add3_u32 v3, v32, v3, s78
	v_and_or_b32 v85, v3, s79, v2
	v_bfe_u32 v2, v36, 16, 1
	v_add3_u32 v2, v36, v2, s78
	v_bfe_u32 v3, v40, 16, 1
	v_lshrrev_b32_e32 v2, 16, v2
	v_add3_u32 v3, v40, v3, s78
	v_and_or_b32 v86, v3, s79, v2
	v_bfe_u32 v2, v44, 16, 1
	v_add3_u32 v2, v44, v2, s78
	v_bfe_u32 v3, v48, 16, 1
	v_lshrrev_b32_e32 v2, 16, v2
	v_add3_u32 v3, v48, v3, s78
	v_and_or_b32 v87, v3, s79, v2
	v_bfe_u32 v2, v52, 16, 1
	v_add3_u32 v2, v52, v2, s78
	v_bfe_u32 v3, v56, 16, 1
	v_lshrrev_b32_e32 v2, 16, v2
	v_add3_u32 v3, v56, v3, s78
	v_and_or_b32 v88, v3, s79, v2
	v_bfe_u32 v2, v60, 16, 1
	v_add3_u32 v2, v60, v2, s78
	v_bfe_u32 v3, v64, 16, 1
	v_lshrrev_b32_e32 v2, 16, v2
	v_add3_u32 v3, v64, v3, s78
	v_and_or_b32 v89, v3, s79, v2
	v_bfe_u32 v2, v5, 16, 1
	v_add3_u32 v2, v5, v2, s78
	v_bfe_u32 v3, v9, 16, 1
	v_lshrrev_b32_e32 v2, 16, v2
	v_add3_u32 v3, v9, v3, s78
	v_and_or_b32 v2, v3, s79, v2
	v_bfe_u32 v3, v13, 16, 1
	v_add3_u32 v3, v13, v3, s78
	v_bfe_u32 v4, v17, 16, 1
	v_lshrrev_b32_e32 v3, 16, v3
	v_add3_u32 v4, v17, v4, s78
	v_and_or_b32 v3, v4, s79, v3
	v_bfe_u32 v4, v21, 16, 1
	v_add3_u32 v4, v21, v4, s78
	v_bfe_u32 v5, v25, 16, 1
	v_lshrrev_b32_e32 v4, 16, v4
	v_add3_u32 v5, v25, v5, s78
	v_and_or_b32 v4, v5, s79, v4
	v_bfe_u32 v5, v29, 16, 1
	v_add3_u32 v5, v29, v5, s78
	v_bfe_u32 v6, v33, 16, 1
	v_lshrrev_b32_e32 v5, 16, v5
	v_add3_u32 v6, v33, v6, s78
	v_and_or_b32 v5, v6, s79, v5
	v_bfe_u32 v6, v37, 16, 1
	v_add3_u32 v6, v37, v6, s78
	v_bfe_u32 v7, v41, 16, 1
	v_lshrrev_b32_e32 v6, 16, v6
	v_add3_u32 v7, v41, v7, s78
	v_and_or_b32 v6, v7, s79, v6
	v_bfe_u32 v7, v45, 16, 1
	v_add3_u32 v7, v45, v7, s78
	v_bfe_u32 v8, v49, 16, 1
	v_lshrrev_b32_e32 v7, 16, v7
	v_add3_u32 v8, v49, v8, s78
	v_and_or_b32 v7, v8, s79, v7
	v_bfe_u32 v8, v53, 16, 1
	v_add3_u32 v8, v53, v8, s78
	v_bfe_u32 v9, v57, 16, 1
	v_lshrrev_b32_e32 v8, 16, v8
	v_add3_u32 v9, v57, v9, s78
	v_and_or_b32 v8, v9, s79, v8
	v_bfe_u32 v9, v61, 16, 1
	v_add3_u32 v9, v61, v9, s78
	v_bfe_u32 v10, v65, 16, 1
	v_lshrrev_b32_e32 v9, 16, v9
	v_add3_u32 v10, v65, v10, s78
	ds_write_b128 v163, v[82:85] offset:288
	ds_write_b128 v163, v[86:89] offset:304
	v_and_or_b32 v9, v10, s79, v9
	ds_write_b128 v163, v[2:5] offset:432
	ds_write_b128 v163, v[6:9] offset:448
	s_waitcnt lgkmcnt(0)
	ds_read_b128 v[2:5], v171
	v_lshl_add_u64 v[6:7], s[0:1], 0, v[66:67]
	v_lshl_add_u64 v[10:11], v[6:7], 0, v[140:141]
	ds_read_b128 v[6:9], v171 offset:1152
	s_waitcnt lgkmcnt(1)
	global_store_dwordx4 v[10:11], v[2:5], off offset:128
	s_nop 1
	v_lshl_add_u64 v[2:3], s[0:1], 0, v[68:69]
	v_lshl_add_u64 v[10:11], v[2:3], 0, v[140:141]
	ds_read_b128 v[2:5], v171 offset:2304
	s_waitcnt lgkmcnt(1)
	global_store_dwordx4 v[10:11], v[6:9], off offset:128
	s_nop 1
	v_lshl_add_u64 v[6:7], s[0:1], 0, v[70:71]
	v_lshl_add_u64 v[10:11], v[6:7], 0, v[140:141]
	ds_read_b128 v[6:9], v171 offset:3456
	s_waitcnt lgkmcnt(1)
	global_store_dwordx4 v[10:11], v[2:5], off offset:128
	s_nop 1
	v_lshl_add_u64 v[2:3], s[0:1], 0, v[72:73]
	v_lshl_add_u64 v[10:11], v[2:3], 0, v[140:141]
	ds_read_b128 v[2:5], v171 offset:4608
	s_waitcnt lgkmcnt(1)
	global_store_dwordx4 v[10:11], v[6:9], off offset:128
	s_nop 1
	v_lshl_add_u64 v[6:7], s[0:1], 0, v[74:75]
	v_lshl_add_u64 v[10:11], v[6:7], 0, v[140:141]
	ds_read_b128 v[6:9], v171 offset:5760
	s_waitcnt lgkmcnt(1)
	global_store_dwordx4 v[10:11], v[2:5], off offset:128
	s_nop 1
	v_lshl_add_u64 v[2:3], s[0:1], 0, v[76:77]
	v_lshl_add_u64 v[10:11], v[2:3], 0, v[140:141]
	ds_read_b128 v[2:5], v171 offset:6912
	s_waitcnt lgkmcnt(1)
	global_store_dwordx4 v[10:11], v[6:9], off offset:128
	ds_read_b128 v[6:9], v171 offset:8064
	v_lshl_add_u64 v[10:11], s[0:1], 0, v[78:79]
	v_lshl_add_u64 v[10:11], v[10:11], 0, v[140:141]
	s_waitcnt lgkmcnt(1)
	global_store_dwordx4 v[10:11], v[2:5], off offset:128
	s_nop 1
	v_lshl_add_u64 v[2:3], s[0:1], 0, v[80:81]
	v_lshl_add_u64 v[2:3], v[2:3], 0, v[140:141]
	s_waitcnt lgkmcnt(0)
	global_store_dwordx4 v[2:3], v[6:9], off offset:128
	s_waitcnt lgkmcnt(0)
	s_mov_b64 s[0:1], 0
.LBB0_210:
	s_andn2_b64 vcc, exec, s[0:1]
	s_mov_b32 s8, 0
	s_cbranch_vccnz .LBB0_212
	s_lshl_b32 s0, s2, 2
	s_and_b32 s0, s0, 0x3f00
	s_addk_i32 s0, 0xe800
	v_or_b32_e32 v2, s0, v130
	v_mov_b32_e32 v3, v133
	v_readlane_b32 s46, v248, 57
	v_lshlrev_b64 v[2:3], 14, v[2:3]
	v_readlane_b32 s47, v248, 58
	s_lshl_b32 s8, s3, 2
	s_nop 0
	v_lshl_add_u64 v[2:3], s[46:47], 0, v[2:3]
	v_lshl_add_u64 v[2:3], v[2:3], 0, s[8:9]
	v_lshl_add_u64 v[142:143], v[2:3], 0, v[132:133]
	v_add_co_u32_e32 v2, vcc, s11, v142
	s_nop 1
	v_addc_co_u32_e32 v3, vcc, 0, v143, vcc
	global_load_dwordx4 v[66:69], v[142:143], off nt
	global_load_dwordx4 v[70:73], v[2:3], off nt
	v_add_co_u32_e32 v2, vcc, s12, v142
	s_nop 1
	v_addc_co_u32_e32 v3, vcc, 0, v143, vcc
	v_add_co_u32_e32 v4, vcc, s13, v142
	s_nop 1
	v_addc_co_u32_e32 v5, vcc, 0, v143, vcc
	global_load_dwordx4 v[74:77], v[2:3], off nt
	global_load_dwordx4 v[78:81], v[4:5], off nt
	v_add_co_u32_e32 v2, vcc, s16, v142
	s_nop 1
	v_addc_co_u32_e32 v3, vcc, 0, v143, vcc
	v_add_co_u32_e32 v4, vcc, s17, v142
	s_nop 1
	v_addc_co_u32_e32 v5, vcc, 0, v143, vcc
	global_load_dwordx4 v[82:85], v[2:3], off nt
	global_load_dwordx4 v[86:89], v[4:5], off nt
	v_add_co_u32_e32 v2, vcc, s18, v142
	s_nop 1
	v_addc_co_u32_e32 v3, vcc, 0, v143, vcc
	v_add_co_u32_e32 v4, vcc, s19, v142
	s_nop 1
	v_addc_co_u32_e32 v5, vcc, 0, v143, vcc
	global_load_dwordx4 v[90:93], v[2:3], off nt
	global_load_dwordx4 v[94:97], v[4:5], off nt
	v_add_co_u32_e32 v2, vcc, s20, v142
	s_nop 1
	v_addc_co_u32_e32 v3, vcc, 0, v143, vcc
	v_add_co_u32_e32 v4, vcc, s21, v142
	s_nop 1
	v_addc_co_u32_e32 v5, vcc, 0, v143, vcc
	global_load_dwordx4 v[98:101], v[2:3], off nt
	global_load_dwordx4 v[102:105], v[4:5], off nt
	v_add_co_u32_e32 v2, vcc, s22, v142
	s_nop 1
	v_addc_co_u32_e32 v3, vcc, 0, v143, vcc
	v_add_co_u32_e32 v4, vcc, s23, v142
	s_nop 1
	v_addc_co_u32_e32 v5, vcc, 0, v143, vcc
	global_load_dwordx4 v[106:109], v[2:3], off nt
	global_load_dwordx4 v[110:113], v[4:5], off nt
	v_add_co_u32_e32 v2, vcc, s28, v142
	s_nop 1
	v_addc_co_u32_e32 v3, vcc, 0, v143, vcc
	v_add_co_u32_e32 v4, vcc, s29, v142
	s_nop 1
	v_addc_co_u32_e32 v5, vcc, 0, v143, vcc
	global_load_dwordx4 v[114:117], v[2:3], off nt
	global_load_dwordx4 v[118:121], v[4:5], off nt
	v_add_co_u32_e32 v2, vcc, s34, v142
	s_nop 1
	v_addc_co_u32_e32 v3, vcc, 0, v143, vcc
	v_add_co_u32_e32 v4, vcc, s35, v142
	s_nop 1
	v_addc_co_u32_e32 v5, vcc, 0, v143, vcc
	global_load_dwordx4 v[122:125], v[2:3], off nt
	global_load_dwordx4 v[126:129], v[4:5], off nt
	v_add_co_u32_e32 v2, vcc, s36, v142
	s_mov_b32 s1, s9
	s_nop 0
	v_addc_co_u32_e32 v3, vcc, 0, v143, vcc
	v_add_co_u32_e32 v6, vcc, s37, v142
	global_load_dwordx4 v[2:5], v[2:3], off nt
	s_nop 0
	v_addc_co_u32_e32 v7, vcc, 0, v143, vcc
	v_add_co_u32_e32 v10, vcc, s38, v142
	global_load_dwordx4 v[6:9], v[6:7], off nt
	s_nop 0
	v_addc_co_u32_e32 v11, vcc, 0, v143, vcc
	v_add_co_u32_e32 v14, vcc, s39, v142
	global_load_dwordx4 v[10:13], v[10:11], off nt
	s_nop 0
	v_addc_co_u32_e32 v15, vcc, 0, v143, vcc
	v_add_co_u32_e32 v18, vcc, s40, v142
	global_load_dwordx4 v[14:17], v[14:15], off nt
	s_nop 0
	v_addc_co_u32_e32 v19, vcc, 0, v143, vcc
	v_add_co_u32_e32 v22, vcc, s41, v142
	global_load_dwordx4 v[18:21], v[18:19], off nt
	s_nop 0
	v_addc_co_u32_e32 v23, vcc, 0, v143, vcc
	v_add_co_u32_e32 v26, vcc, s42, v142
	global_load_dwordx4 v[22:25], v[22:23], off nt
	s_nop 0
	v_addc_co_u32_e32 v27, vcc, 0, v143, vcc
	v_add_co_u32_e32 v30, vcc, s43, v142
	global_load_dwordx4 v[26:29], v[26:27], off nt
	s_nop 0
	v_addc_co_u32_e32 v31, vcc, 0, v143, vcc
	v_add_co_u32_e32 v34, vcc, s44, v142
	global_load_dwordx4 v[30:33], v[30:31], off nt
	s_nop 0
	v_addc_co_u32_e32 v35, vcc, 0, v143, vcc
	v_add_co_u32_e32 v38, vcc, s45, v142
	global_load_dwordx4 v[34:37], v[34:35], off nt
	s_nop 0
	v_addc_co_u32_e32 v39, vcc, 0, v143, vcc
	v_add_co_u32_e32 v42, vcc, s50, v142
	global_load_dwordx4 v[38:41], v[38:39], off nt
	s_nop 0
	v_addc_co_u32_e32 v43, vcc, 0, v143, vcc
	v_add_co_u32_e32 v46, vcc, s51, v142
	global_load_dwordx4 v[42:45], v[42:43], off nt
	s_nop 0
	v_addc_co_u32_e32 v47, vcc, 0, v143, vcc
	v_add_co_u32_e32 v50, vcc, s74, v142
	global_load_dwordx4 v[46:49], v[46:47], off nt
	s_nop 0
	v_addc_co_u32_e32 v51, vcc, 0, v143, vcc
	v_add_co_u32_e32 v54, vcc, s75, v142
	global_load_dwordx4 v[50:53], v[50:51], off nt
	s_nop 0
	v_addc_co_u32_e32 v55, vcc, 0, v143, vcc
	v_add_co_u32_e32 v58, vcc, s76, v142
	global_load_dwordx4 v[54:57], v[54:55], off nt
	s_nop 0
	v_addc_co_u32_e32 v59, vcc, 0, v143, vcc
	v_add_co_u32_e32 v62, vcc, s77, v142
	global_load_dwordx4 v[58:61], v[58:59], off nt
	s_nop 0
	v_addc_co_u32_e32 v63, vcc, 0, v143, vcc
	global_load_dwordx4 v[62:65], v[62:63], off nt
	v_lshl_add_u64 v[158:159], s[0:1], 1, v[134:135]
	s_waitcnt vmcnt(31)
	v_bfe_u32 v141, v66, 16, 1
	v_add3_u32 v66, v66, v141, s78
	s_waitcnt vmcnt(30)
	v_bfe_u32 v141, v70, 16, 1
	v_lshrrev_b32_e32 v66, 16, v66
	v_add3_u32 v70, v70, v141, s78
	v_and_or_b32 v174, v70, s79, v66
	s_waitcnt vmcnt(29)
	v_bfe_u32 v66, v74, 16, 1
	v_add3_u32 v66, v74, v66, s78
	s_waitcnt vmcnt(28)
	v_bfe_u32 v70, v78, 16, 1
	v_lshrrev_b32_e32 v66, 16, v66
	v_add3_u32 v70, v78, v70, s78
	v_and_or_b32 v175, v70, s79, v66
	s_waitcnt vmcnt(27)
	v_bfe_u32 v66, v82, 16, 1
	v_add3_u32 v66, v82, v66, s78
	s_waitcnt vmcnt(26)
	v_bfe_u32 v70, v86, 16, 1
	v_lshrrev_b32_e32 v66, 16, v66
	v_add3_u32 v70, v86, v70, s78
	v_and_or_b32 v176, v70, s79, v66
	s_waitcnt vmcnt(25)
	v_bfe_u32 v66, v90, 16, 1
	v_add3_u32 v66, v90, v66, s78
	s_waitcnt vmcnt(24)
	v_bfe_u32 v70, v94, 16, 1
	v_lshrrev_b32_e32 v66, 16, v66
	v_add3_u32 v70, v94, v70, s78
	v_and_or_b32 v177, v70, s79, v66
	s_waitcnt vmcnt(23)
	v_bfe_u32 v66, v98, 16, 1
	v_add3_u32 v66, v98, v66, s78
	s_waitcnt vmcnt(22)
	v_bfe_u32 v70, v102, 16, 1
	v_lshrrev_b32_e32 v66, 16, v66
	v_add3_u32 v70, v102, v70, s78
	v_and_or_b32 v178, v70, s79, v66
	s_waitcnt vmcnt(21)
	v_bfe_u32 v66, v106, 16, 1
	v_add3_u32 v66, v106, v66, s78
	s_waitcnt vmcnt(20)
	v_bfe_u32 v70, v110, 16, 1
	v_lshrrev_b32_e32 v66, 16, v66
	v_add3_u32 v70, v110, v70, s78
	v_and_or_b32 v179, v70, s79, v66
	s_waitcnt vmcnt(19)
	v_bfe_u32 v66, v114, 16, 1
	v_add3_u32 v66, v114, v66, s78
	s_waitcnt vmcnt(18)
	v_bfe_u32 v70, v118, 16, 1
	v_lshrrev_b32_e32 v66, 16, v66
	v_add3_u32 v70, v118, v70, s78
	v_and_or_b32 v180, v70, s79, v66
	s_waitcnt vmcnt(17)
	v_bfe_u32 v66, v122, 16, 1
	v_add3_u32 v66, v122, v66, s78
	s_waitcnt vmcnt(16)
	v_bfe_u32 v70, v126, 16, 1
	v_lshrrev_b32_e32 v66, 16, v66
	v_add3_u32 v70, v126, v70, s78
	v_and_or_b32 v181, v70, s79, v66
	v_bfe_u32 v66, v67, 16, 1
	v_add3_u32 v66, v67, v66, s78
	v_bfe_u32 v67, v71, 16, 1
	v_lshrrev_b32_e32 v66, 16, v66
	v_add3_u32 v67, v71, v67, s78
	ds_write_b128 v163, v[174:177]
	ds_write_b128 v163, v[178:181] offset:16
	v_and_or_b32 v174, v67, s79, v66
	v_bfe_u32 v66, v75, 16, 1
	v_add3_u32 v66, v75, v66, s78
	v_bfe_u32 v67, v79, 16, 1
	v_lshrrev_b32_e32 v66, 16, v66
	v_add3_u32 v67, v79, v67, s78
	v_and_or_b32 v175, v67, s79, v66
	v_bfe_u32 v66, v83, 16, 1
	v_add3_u32 v66, v83, v66, s78
	v_bfe_u32 v67, v87, 16, 1
	v_lshrrev_b32_e32 v66, 16, v66
	v_add3_u32 v67, v87, v67, s78
	v_and_or_b32 v176, v67, s79, v66
	v_bfe_u32 v66, v91, 16, 1
	v_add3_u32 v66, v91, v66, s78
	v_bfe_u32 v67, v95, 16, 1
	v_lshrrev_b32_e32 v66, 16, v66
	v_add3_u32 v67, v95, v67, s78
	v_and_or_b32 v177, v67, s79, v66
	v_bfe_u32 v66, v99, 16, 1
	v_add3_u32 v66, v99, v66, s78
	v_bfe_u32 v67, v103, 16, 1
	v_lshrrev_b32_e32 v66, 16, v66
	v_add3_u32 v67, v103, v67, s78
	v_and_or_b32 v178, v67, s79, v66
	v_bfe_u32 v66, v107, 16, 1
	v_add3_u32 v66, v107, v66, s78
	v_bfe_u32 v67, v111, 16, 1
	v_lshrrev_b32_e32 v66, 16, v66
	v_add3_u32 v67, v111, v67, s78
	v_and_or_b32 v179, v67, s79, v66
	v_bfe_u32 v66, v115, 16, 1
	v_add3_u32 v66, v115, v66, s78
	v_bfe_u32 v67, v119, 16, 1
	v_lshrrev_b32_e32 v66, 16, v66
	v_add3_u32 v67, v119, v67, s78
	v_and_or_b32 v180, v67, s79, v66
	v_bfe_u32 v66, v123, 16, 1
	v_add3_u32 v66, v123, v66, s78
	v_bfe_u32 v67, v127, 16, 1
	v_lshrrev_b32_e32 v66, 16, v66
	v_add3_u32 v67, v127, v67, s78
	v_and_or_b32 v181, v67, s79, v66
	v_bfe_u32 v66, v68, 16, 1
	v_add3_u32 v66, v68, v66, s78
	v_bfe_u32 v67, v72, 16, 1
	v_lshrrev_b32_e32 v66, 16, v66
	v_add3_u32 v67, v72, v67, s78
	ds_write_b128 v163, v[174:177] offset:144
	ds_write_b128 v163, v[178:181] offset:160
	v_and_or_b32 v174, v67, s79, v66
	v_bfe_u32 v66, v76, 16, 1
	v_add3_u32 v66, v76, v66, s78
	v_bfe_u32 v67, v80, 16, 1
	v_lshrrev_b32_e32 v66, 16, v66
	v_add3_u32 v67, v80, v67, s78
	v_and_or_b32 v175, v67, s79, v66
	v_bfe_u32 v66, v84, 16, 1
	v_add3_u32 v66, v84, v66, s78
	v_bfe_u32 v67, v88, 16, 1
	v_lshrrev_b32_e32 v66, 16, v66
	v_add3_u32 v67, v88, v67, s78
	v_and_or_b32 v176, v67, s79, v66
	v_bfe_u32 v66, v92, 16, 1
	v_add3_u32 v66, v92, v66, s78
	v_bfe_u32 v67, v96, 16, 1
	v_lshrrev_b32_e32 v66, 16, v66
	v_add3_u32 v67, v96, v67, s78
	v_and_or_b32 v177, v67, s79, v66
	v_bfe_u32 v66, v100, 16, 1
	v_add3_u32 v66, v100, v66, s78
	v_bfe_u32 v67, v104, 16, 1
	v_lshrrev_b32_e32 v66, 16, v66
	v_add3_u32 v67, v104, v67, s78
	v_and_or_b32 v178, v67, s79, v66
	v_bfe_u32 v66, v108, 16, 1
	v_add3_u32 v66, v108, v66, s78
	v_bfe_u32 v67, v112, 16, 1
	v_lshrrev_b32_e32 v66, 16, v66
	v_add3_u32 v67, v112, v67, s78
	v_and_or_b32 v179, v67, s79, v66
	v_bfe_u32 v66, v116, 16, 1
	v_add3_u32 v66, v116, v66, s78
	v_bfe_u32 v67, v120, 16, 1
	v_lshrrev_b32_e32 v66, 16, v66
	v_add3_u32 v67, v120, v67, s78
	v_and_or_b32 v180, v67, s79, v66
	v_bfe_u32 v66, v124, 16, 1
	v_add3_u32 v66, v124, v66, s78
	v_bfe_u32 v67, v128, 16, 1
	v_lshrrev_b32_e32 v66, 16, v66
	v_add3_u32 v67, v128, v67, s78
	v_and_or_b32 v181, v67, s79, v66
	v_bfe_u32 v66, v69, 16, 1
	v_add3_u32 v66, v69, v66, s78
	v_bfe_u32 v67, v73, 16, 1
	v_lshrrev_b32_e32 v66, 16, v66
	v_add3_u32 v67, v73, v67, s78
	v_and_or_b32 v66, v67, s79, v66
	v_bfe_u32 v67, v77, 16, 1
	v_add3_u32 v67, v77, v67, s78
	v_bfe_u32 v68, v81, 16, 1
	v_lshrrev_b32_e32 v67, 16, v67
	v_add3_u32 v68, v81, v68, s78
	v_and_or_b32 v67, v68, s79, v67
	v_bfe_u32 v68, v85, 16, 1
	v_add3_u32 v68, v85, v68, s78
	v_bfe_u32 v69, v89, 16, 1
	v_lshrrev_b32_e32 v68, 16, v68
	v_add3_u32 v69, v89, v69, s78
	v_and_or_b32 v68, v69, s79, v68
	v_bfe_u32 v69, v93, 16, 1
	v_add3_u32 v69, v93, v69, s78
	v_bfe_u32 v70, v97, 16, 1
	v_lshrrev_b32_e32 v69, 16, v69
	v_add3_u32 v70, v97, v70, s78
	v_and_or_b32 v69, v70, s79, v69
	v_bfe_u32 v70, v101, 16, 1
	v_add3_u32 v70, v101, v70, s78
	v_bfe_u32 v71, v105, 16, 1
	v_lshrrev_b32_e32 v70, 16, v70
	v_add3_u32 v71, v105, v71, s78
	v_and_or_b32 v70, v71, s79, v70
	v_bfe_u32 v71, v109, 16, 1
	v_add3_u32 v71, v109, v71, s78
	v_bfe_u32 v72, v113, 16, 1
	v_lshrrev_b32_e32 v71, 16, v71
	v_add3_u32 v72, v113, v72, s78
	v_and_or_b32 v71, v72, s79, v71
	v_bfe_u32 v72, v117, 16, 1
	v_add3_u32 v72, v117, v72, s78
	v_bfe_u32 v73, v121, 16, 1
	v_lshrrev_b32_e32 v72, 16, v72
	v_add3_u32 v73, v121, v73, s78
	v_and_or_b32 v72, v73, s79, v72
	v_bfe_u32 v73, v125, 16, 1
	v_add3_u32 v73, v125, v73, s78
	v_bfe_u32 v74, v129, 16, 1
	v_lshrrev_b32_e32 v73, 16, v73
	v_add3_u32 v74, v129, v74, s78
	ds_write_b128 v163, v[174:177] offset:288
	ds_write_b128 v163, v[178:181] offset:304
	v_and_or_b32 v73, v74, s79, v73
	ds_write_b128 v163, v[66:69] offset:432
	ds_write_b128 v163, v[70:73] offset:448
	s_waitcnt lgkmcnt(0)
	ds_read_b128 v[66:69], v171
	v_lshlrev_b32_e32 v70, 13, v144
	v_mov_b32_e32 v71, v133
	v_lshl_add_u64 v[144:145], v[158:159], 0, v[70:71]
	ds_read_b128 v[70:73], v171 offset:1152
	s_waitcnt lgkmcnt(1)
	global_store_dwordx4 v[144:145], v[66:69], off
	s_nop 1
	v_lshlrev_b32_e32 v66, 13, v146
	v_mov_b32_e32 v67, v133
	v_lshl_add_u64 v[146:147], v[158:159], 0, v[66:67]
	ds_read_b128 v[66:69], v171 offset:2304
	s_waitcnt lgkmcnt(1)
	global_store_dwordx4 v[146:147], v[70:73], off
	s_nop 1
	v_lshlrev_b32_e32 v70, 13, v149
	v_mov_b32_e32 v71, v133
	v_lshl_add_u64 v[150:151], v[158:159], 0, v[70:71]
	ds_read_b128 v[70:73], v171 offset:3456
	s_waitcnt lgkmcnt(1)
	global_store_dwordx4 v[150:151], v[66:69], off
	s_nop 1
	v_lshlrev_b32_e32 v66, 13, v148
	v_mov_b32_e32 v67, v133
	v_lshl_add_u64 v[148:149], v[158:159], 0, v[66:67]
	ds_read_b128 v[66:69], v171 offset:4608
	s_waitcnt lgkmcnt(1)
	global_store_dwordx4 v[148:149], v[70:73], off
	s_nop 1
	v_lshlrev_b32_e32 v70, 13, v152
	v_mov_b32_e32 v71, v133
	v_lshl_add_u64 v[152:153], v[158:159], 0, v[70:71]
	ds_read_b128 v[70:73], v171 offset:5760
	s_waitcnt lgkmcnt(1)
	global_store_dwordx4 v[152:153], v[66:69], off
	s_nop 1
	v_lshlrev_b32_e32 v66, 13, v154
	v_mov_b32_e32 v67, v133
	v_lshl_add_u64 v[154:155], v[158:159], 0, v[66:67]
	ds_read_b128 v[66:69], v171 offset:6912
	s_waitcnt lgkmcnt(1)
	global_store_dwordx4 v[154:155], v[70:73], off
	s_nop 1
	v_lshlrev_b32_e32 v70, 13, v156
	v_mov_b32_e32 v71, v133
	v_lshl_add_u64 v[156:157], v[158:159], 0, v[70:71]
	ds_read_b128 v[70:73], v171 offset:8064
	s_waitcnt lgkmcnt(1)
	global_store_dwordx4 v[156:157], v[66:69], off
	s_nop 1
	v_lshlrev_b32_e32 v66, 13, v172
	v_mov_b32_e32 v67, v133
	v_lshl_add_u64 v[158:159], v[158:159], 0, v[66:67]
	v_add_co_u32_e32 v66, vcc, s80, v142
	s_waitcnt lgkmcnt(0)
	global_store_dwordx4 v[158:159], v[70:73], off
	v_addc_co_u32_e32 v67, vcc, 0, v143, vcc
	s_nop 0
	v_add_co_u32_e32 v70, vcc, s81, v142
	s_waitcnt lgkmcnt(0)
	s_nop 1
	v_addc_co_u32_e32 v71, vcc, 0, v143, vcc
	v_add_co_u32_e32 v74, vcc, s82, v142
	global_load_dwordx4 v[66:69], v[66:67], off nt
	s_nop 0
	global_load_dwordx4 v[70:73], v[70:71], off nt
	v_addc_co_u32_e32 v75, vcc, 0, v143, vcc
	v_add_co_u32_e32 v78, vcc, s83, v142
	s_nop 1
	v_addc_co_u32_e32 v79, vcc, 0, v143, vcc
	v_add_co_u32_e32 v82, vcc, s88, v142
	global_load_dwordx4 v[74:77], v[74:75], off nt
	s_nop 0
	global_load_dwordx4 v[78:81], v[78:79], off nt
	v_addc_co_u32_e32 v83, vcc, 0, v143, vcc
	v_add_co_u32_e32 v86, vcc, s89, v142
	s_nop 1
	v_addc_co_u32_e32 v87, vcc, 0, v143, vcc
	v_add_co_u32_e32 v90, vcc, s90, v142
	global_load_dwordx4 v[82:85], v[82:83], off nt
	s_nop 0
	global_load_dwordx4 v[86:89], v[86:87], off nt
	v_addc_co_u32_e32 v91, vcc, 0, v143, vcc
	v_add_co_u32_e32 v94, vcc, s91, v142
	s_nop 1
	v_addc_co_u32_e32 v95, vcc, 0, v143, vcc
	v_add_co_u32_e32 v98, vcc, s92, v142
	global_load_dwordx4 v[90:93], v[90:91], off nt
	s_nop 0
	global_load_dwordx4 v[94:97], v[94:95], off nt
	v_addc_co_u32_e32 v99, vcc, 0, v143, vcc
	v_add_co_u32_e32 v102, vcc, s93, v142
	s_nop 1
	v_addc_co_u32_e32 v103, vcc, 0, v143, vcc
	v_add_co_u32_e32 v106, vcc, s94, v142
	global_load_dwordx4 v[98:101], v[98:99], off nt
	s_nop 0
	global_load_dwordx4 v[102:105], v[102:103], off nt
	v_addc_co_u32_e32 v107, vcc, 0, v143, vcc
	v_add_co_u32_e32 v110, vcc, s95, v142
	s_nop 1
	v_addc_co_u32_e32 v111, vcc, 0, v143, vcc
	v_add_co_u32_e32 v114, vcc, s96, v142
	global_load_dwordx4 v[106:109], v[106:107], off nt
	s_nop 0
	global_load_dwordx4 v[110:113], v[110:111], off nt
	v_addc_co_u32_e32 v115, vcc, 0, v143, vcc
	v_add_co_u32_e32 v118, vcc, s97, v142
	s_nop 1
	v_addc_co_u32_e32 v119, vcc, 0, v143, vcc
	v_add_co_u32_e32 v122, vcc, s84, v142
	global_load_dwordx4 v[114:117], v[114:115], off nt
	s_nop 0
	global_load_dwordx4 v[118:121], v[118:119], off nt
	v_addc_co_u32_e32 v123, vcc, 0, v143, vcc
	v_add_co_u32_e32 v126, vcc, s85, v142
	s_nop 1
	v_addc_co_u32_e32 v127, vcc, 0, v143, vcc
	global_load_dwordx4 v[122:125], v[122:123], off nt
	s_nop 0
	global_load_dwordx4 v[126:129], v[126:127], off nt
	s_waitcnt vmcnt(39)
	v_bfe_u32 v141, v2, 16, 1
	v_add3_u32 v2, v2, v141, s78
	s_waitcnt vmcnt(38)
	v_bfe_u32 v141, v6, 16, 1
	v_lshrrev_b32_e32 v2, 16, v2
	v_add3_u32 v6, v6, v141, s78
	v_and_or_b32 v172, v6, s79, v2
	s_waitcnt vmcnt(37)
	v_bfe_u32 v2, v10, 16, 1
	v_add3_u32 v2, v10, v2, s78
	s_waitcnt vmcnt(36)
	v_bfe_u32 v6, v14, 16, 1
	v_lshrrev_b32_e32 v2, 16, v2
	v_add3_u32 v6, v14, v6, s78
	v_and_or_b32 v173, v6, s79, v2
	s_waitcnt vmcnt(35)
	v_bfe_u32 v2, v18, 16, 1
	v_add3_u32 v2, v18, v2, s78
	s_waitcnt vmcnt(34)
	v_bfe_u32 v6, v22, 16, 1
	v_lshrrev_b32_e32 v2, 16, v2
	v_add3_u32 v6, v22, v6, s78
	v_and_or_b32 v174, v6, s79, v2
	s_waitcnt vmcnt(33)
	v_bfe_u32 v2, v26, 16, 1
	v_add3_u32 v2, v26, v2, s78
	s_waitcnt vmcnt(32)
	v_bfe_u32 v6, v30, 16, 1
	v_lshrrev_b32_e32 v2, 16, v2
	v_add3_u32 v6, v30, v6, s78
	v_and_or_b32 v175, v6, s79, v2
	s_waitcnt vmcnt(31)
	v_bfe_u32 v2, v34, 16, 1
	v_add3_u32 v2, v34, v2, s78
	s_waitcnt vmcnt(30)
	v_bfe_u32 v6, v38, 16, 1
	v_lshrrev_b32_e32 v2, 16, v2
	v_add3_u32 v6, v38, v6, s78
	v_and_or_b32 v176, v6, s79, v2
	s_waitcnt vmcnt(29)
	v_bfe_u32 v2, v42, 16, 1
	v_add3_u32 v2, v42, v2, s78
	s_waitcnt vmcnt(28)
	v_bfe_u32 v6, v46, 16, 1
	v_lshrrev_b32_e32 v2, 16, v2
	v_add3_u32 v6, v46, v6, s78
	v_and_or_b32 v177, v6, s79, v2
	s_waitcnt vmcnt(27)
	v_bfe_u32 v2, v50, 16, 1
	v_add3_u32 v2, v50, v2, s78
	s_waitcnt vmcnt(26)
	v_bfe_u32 v6, v54, 16, 1
	v_lshrrev_b32_e32 v2, 16, v2
	v_add3_u32 v6, v54, v6, s78
	v_and_or_b32 v178, v6, s79, v2
	s_waitcnt vmcnt(25)
	v_bfe_u32 v2, v58, 16, 1
	v_add3_u32 v2, v58, v2, s78
	s_waitcnt vmcnt(24)
	v_bfe_u32 v6, v62, 16, 1
	v_lshrrev_b32_e32 v2, 16, v2
	v_add3_u32 v6, v62, v6, s78
	v_and_or_b32 v179, v6, s79, v2
	v_bfe_u32 v2, v3, 16, 1
	v_add3_u32 v2, v3, v2, s78
	v_bfe_u32 v3, v7, 16, 1
	v_lshrrev_b32_e32 v2, 16, v2
	v_add3_u32 v3, v7, v3, s78
	ds_write_b128 v163, v[172:175]
	ds_write_b128 v163, v[176:179] offset:16
	v_and_or_b32 v172, v3, s79, v2
	v_bfe_u32 v2, v11, 16, 1
	v_add3_u32 v2, v11, v2, s78
	v_bfe_u32 v3, v15, 16, 1
	v_lshrrev_b32_e32 v2, 16, v2
	v_add3_u32 v3, v15, v3, s78
	v_and_or_b32 v173, v3, s79, v2
	v_bfe_u32 v2, v19, 16, 1
	v_add3_u32 v2, v19, v2, s78
	v_bfe_u32 v3, v23, 16, 1
	v_lshrrev_b32_e32 v2, 16, v2
	v_add3_u32 v3, v23, v3, s78
	v_and_or_b32 v174, v3, s79, v2
	v_bfe_u32 v2, v27, 16, 1
	v_add3_u32 v2, v27, v2, s78
	v_bfe_u32 v3, v31, 16, 1
	v_lshrrev_b32_e32 v2, 16, v2
	v_add3_u32 v3, v31, v3, s78
	v_and_or_b32 v175, v3, s79, v2
	v_bfe_u32 v2, v35, 16, 1
	v_add3_u32 v2, v35, v2, s78
	v_bfe_u32 v3, v39, 16, 1
	v_lshrrev_b32_e32 v2, 16, v2
	v_add3_u32 v3, v39, v3, s78
	v_and_or_b32 v176, v3, s79, v2
	v_bfe_u32 v2, v43, 16, 1
	v_add3_u32 v2, v43, v2, s78
	v_bfe_u32 v3, v47, 16, 1
	v_lshrrev_b32_e32 v2, 16, v2
	v_add3_u32 v3, v47, v3, s78
	v_and_or_b32 v177, v3, s79, v2
	v_bfe_u32 v2, v51, 16, 1
	v_add3_u32 v2, v51, v2, s78
	v_bfe_u32 v3, v55, 16, 1
	v_lshrrev_b32_e32 v2, 16, v2
	v_add3_u32 v3, v55, v3, s78
	v_and_or_b32 v178, v3, s79, v2
	v_bfe_u32 v2, v59, 16, 1
	v_add3_u32 v2, v59, v2, s78
	v_bfe_u32 v3, v63, 16, 1
	v_lshrrev_b32_e32 v2, 16, v2
	v_add3_u32 v3, v63, v3, s78
	v_and_or_b32 v179, v3, s79, v2
	v_bfe_u32 v2, v4, 16, 1
	v_add3_u32 v2, v4, v2, s78
	v_bfe_u32 v3, v8, 16, 1
	v_lshrrev_b32_e32 v2, 16, v2
	v_add3_u32 v3, v8, v3, s78
	ds_write_b128 v163, v[172:175] offset:144
	ds_write_b128 v163, v[176:179] offset:160
	v_and_or_b32 v172, v3, s79, v2
	v_bfe_u32 v2, v12, 16, 1
	v_add3_u32 v2, v12, v2, s78
	v_bfe_u32 v3, v16, 16, 1
	v_lshrrev_b32_e32 v2, 16, v2
	v_add3_u32 v3, v16, v3, s78
	v_and_or_b32 v173, v3, s79, v2
	v_bfe_u32 v2, v20, 16, 1
	v_add3_u32 v2, v20, v2, s78
	v_bfe_u32 v3, v24, 16, 1
	v_lshrrev_b32_e32 v2, 16, v2
	v_add3_u32 v3, v24, v3, s78
	v_and_or_b32 v174, v3, s79, v2
	v_bfe_u32 v2, v28, 16, 1
	v_add3_u32 v2, v28, v2, s78
	v_bfe_u32 v3, v32, 16, 1
	v_lshrrev_b32_e32 v2, 16, v2
	v_add3_u32 v3, v32, v3, s78
	v_and_or_b32 v175, v3, s79, v2
	v_bfe_u32 v2, v36, 16, 1
	v_add3_u32 v2, v36, v2, s78
	v_bfe_u32 v3, v40, 16, 1
	v_lshrrev_b32_e32 v2, 16, v2
	v_add3_u32 v3, v40, v3, s78
	v_and_or_b32 v176, v3, s79, v2
	v_bfe_u32 v2, v44, 16, 1
	v_add3_u32 v2, v44, v2, s78
	v_bfe_u32 v3, v48, 16, 1
	v_lshrrev_b32_e32 v2, 16, v2
	v_add3_u32 v3, v48, v3, s78
	v_and_or_b32 v177, v3, s79, v2
	v_bfe_u32 v2, v52, 16, 1
	v_add3_u32 v2, v52, v2, s78
	v_bfe_u32 v3, v56, 16, 1
	v_lshrrev_b32_e32 v2, 16, v2
	v_add3_u32 v3, v56, v3, s78
	v_and_or_b32 v178, v3, s79, v2
	v_bfe_u32 v2, v60, 16, 1
	v_add3_u32 v2, v60, v2, s78
	v_bfe_u32 v3, v64, 16, 1
	v_lshrrev_b32_e32 v2, 16, v2
	v_add3_u32 v3, v64, v3, s78
	v_and_or_b32 v179, v3, s79, v2
	v_bfe_u32 v2, v5, 16, 1
	v_add3_u32 v2, v5, v2, s78
	v_bfe_u32 v3, v9, 16, 1
	v_lshrrev_b32_e32 v2, 16, v2
	v_add3_u32 v3, v9, v3, s78
	v_and_or_b32 v2, v3, s79, v2
	v_bfe_u32 v3, v13, 16, 1
	v_add3_u32 v3, v13, v3, s78
	v_bfe_u32 v4, v17, 16, 1
	v_lshrrev_b32_e32 v3, 16, v3
	v_add3_u32 v4, v17, v4, s78
	v_and_or_b32 v3, v4, s79, v3
	v_bfe_u32 v4, v21, 16, 1
	v_add3_u32 v4, v21, v4, s78
	v_bfe_u32 v5, v25, 16, 1
	v_lshrrev_b32_e32 v4, 16, v4
	v_add3_u32 v5, v25, v5, s78
	v_and_or_b32 v4, v5, s79, v4
	v_bfe_u32 v5, v29, 16, 1
	v_add3_u32 v5, v29, v5, s78
	v_bfe_u32 v6, v33, 16, 1
	v_lshrrev_b32_e32 v5, 16, v5
	v_add3_u32 v6, v33, v6, s78
	v_and_or_b32 v5, v6, s79, v5
	v_bfe_u32 v6, v37, 16, 1
	v_add3_u32 v6, v37, v6, s78
	v_bfe_u32 v7, v41, 16, 1
	v_lshrrev_b32_e32 v6, 16, v6
	v_add3_u32 v7, v41, v7, s78
	v_and_or_b32 v6, v7, s79, v6
	v_bfe_u32 v7, v45, 16, 1
	v_add3_u32 v7, v45, v7, s78
	v_bfe_u32 v8, v49, 16, 1
	v_lshrrev_b32_e32 v7, 16, v7
	v_add3_u32 v8, v49, v8, s78
	v_and_or_b32 v7, v8, s79, v7
	v_bfe_u32 v8, v53, 16, 1
	v_add3_u32 v8, v53, v8, s78
	v_bfe_u32 v9, v57, 16, 1
	v_lshrrev_b32_e32 v8, 16, v8
	v_add3_u32 v9, v57, v9, s78
	v_and_or_b32 v8, v9, s79, v8
	v_bfe_u32 v9, v61, 16, 1
	v_add3_u32 v9, v61, v9, s78
	v_bfe_u32 v10, v65, 16, 1
	v_lshrrev_b32_e32 v9, 16, v9
	v_add3_u32 v10, v65, v10, s78
	ds_write_b128 v163, v[172:175] offset:288
	ds_write_b128 v163, v[176:179] offset:304
	v_and_or_b32 v9, v10, s79, v9
	ds_write_b128 v163, v[2:5] offset:432
	ds_write_b128 v163, v[6:9] offset:448
	s_waitcnt lgkmcnt(0)
	ds_read_b128 v[2:5], v171
	ds_read_b128 v[6:9], v171 offset:1152
	ds_read_b128 v[10:13], v171 offset:2304
	s_waitcnt lgkmcnt(2)
	global_store_dwordx4 v[144:145], v[2:5], off offset:128
	s_waitcnt lgkmcnt(1)
	global_store_dwordx4 v[146:147], v[6:9], off offset:128
	s_waitcnt lgkmcnt(0)
	global_store_dwordx4 v[150:151], v[10:13], off offset:128
	ds_read_b128 v[2:5], v171 offset:3456
	ds_read_b128 v[6:9], v171 offset:4608
	ds_read_b128 v[10:13], v171 offset:5760
	ds_read_b128 v[14:17], v171 offset:6912
	ds_read_b128 v[18:21], v171 offset:8064
	s_waitcnt lgkmcnt(4)
	global_store_dwordx4 v[148:149], v[2:5], off offset:128
	s_waitcnt lgkmcnt(3)
	global_store_dwordx4 v[152:153], v[6:9], off offset:128
	s_waitcnt lgkmcnt(2)
	global_store_dwordx4 v[154:155], v[10:13], off offset:128
	s_waitcnt lgkmcnt(1)
	global_store_dwordx4 v[156:157], v[14:17], off offset:128
	s_waitcnt lgkmcnt(0)
	global_store_dwordx4 v[158:159], v[18:21], off offset:128
	v_add_co_u32_e32 v2, vcc, s54, v142
	s_waitcnt lgkmcnt(0)
	s_nop 1
	v_addc_co_u32_e32 v3, vcc, 0, v143, vcc
	v_add_co_u32_e32 v6, vcc, s55, v142
	s_nop 1
	v_addc_co_u32_e32 v7, vcc, 0, v143, vcc
	v_add_co_u32_e32 v10, vcc, s72, v142
	global_load_dwordx4 v[2:5], v[2:3], off nt
	s_nop 0
	global_load_dwordx4 v[6:9], v[6:7], off nt
	v_addc_co_u32_e32 v11, vcc, 0, v143, vcc
	v_add_co_u32_e32 v14, vcc, s73, v142
	s_nop 1
	v_addc_co_u32_e32 v15, vcc, 0, v143, vcc
	v_add_co_u32_e32 v18, vcc, s86, v142
	global_load_dwordx4 v[10:13], v[10:11], off nt
	s_nop 0
	global_load_dwordx4 v[14:17], v[14:15], off nt
	v_addc_co_u32_e32 v19, vcc, 0, v143, vcc
	v_add_co_u32_e32 v22, vcc, s87, v142
	s_nop 1
	v_addc_co_u32_e32 v23, vcc, 0, v143, vcc
	v_add_co_u32_e32 v26, vcc, s64, v142
	global_load_dwordx4 v[18:21], v[18:19], off nt
	s_nop 0
	global_load_dwordx4 v[22:25], v[22:23], off nt
	v_addc_co_u32_e32 v27, vcc, 0, v143, vcc
	v_add_co_u32_e32 v30, vcc, s65, v142
	s_nop 1
	v_addc_co_u32_e32 v31, vcc, 0, v143, vcc
	v_add_co_u32_e32 v34, vcc, s70, v142
	global_load_dwordx4 v[26:29], v[26:27], off nt
	s_nop 0
	global_load_dwordx4 v[30:33], v[30:31], off nt
	v_addc_co_u32_e32 v35, vcc, 0, v143, vcc
	v_add_co_u32_e32 v38, vcc, s71, v142
	s_nop 1
	v_addc_co_u32_e32 v39, vcc, 0, v143, vcc
	v_add_co_u32_e32 v42, vcc, s66, v142
	global_load_dwordx4 v[34:37], v[34:35], off nt
	s_nop 0
	global_load_dwordx4 v[38:41], v[38:39], off nt
	v_addc_co_u32_e32 v43, vcc, 0, v143, vcc
	v_add_co_u32_e32 v46, vcc, s67, v142
	s_nop 1
	v_addc_co_u32_e32 v47, vcc, 0, v143, vcc
	v_add_co_u32_e32 v50, vcc, s52, v142
	global_load_dwordx4 v[42:45], v[42:43], off nt
	s_nop 0
	global_load_dwordx4 v[46:49], v[46:47], off nt
	v_addc_co_u32_e32 v51, vcc, 0, v143, vcc
	v_add_co_u32_e32 v54, vcc, s53, v142
	s_nop 1
	v_addc_co_u32_e32 v55, vcc, 0, v143, vcc
	v_add_co_u32_e32 v58, vcc, s62, v142
	global_load_dwordx4 v[50:53], v[50:51], off nt
	s_nop 0
	global_load_dwordx4 v[54:57], v[54:55], off nt
	v_addc_co_u32_e32 v59, vcc, 0, v143, vcc
	v_add_co_u32_e32 v62, vcc, s63, v142
	s_nop 1
	v_addc_co_u32_e32 v63, vcc, 0, v143, vcc
	global_load_dwordx4 v[58:61], v[58:59], off nt
	s_nop 0
	global_load_dwordx4 v[62:65], v[62:63], off nt
	s_waitcnt vmcnt(39)
	v_bfe_u32 v141, v66, 16, 1
	v_add3_u32 v66, v66, v141, s78
	s_waitcnt vmcnt(38)
	v_bfe_u32 v141, v70, 16, 1
	v_lshrrev_b32_e32 v66, 16, v66
	v_add3_u32 v70, v70, v141, s78
	v_and_or_b32 v172, v70, s79, v66
	s_waitcnt vmcnt(37)
	v_bfe_u32 v66, v74, 16, 1
	v_add3_u32 v66, v74, v66, s78
	s_waitcnt vmcnt(36)
	v_bfe_u32 v70, v78, 16, 1
	v_lshrrev_b32_e32 v66, 16, v66
	v_add3_u32 v70, v78, v70, s78
	v_and_or_b32 v173, v70, s79, v66
	s_waitcnt vmcnt(35)
	v_bfe_u32 v66, v82, 16, 1
	v_add3_u32 v66, v82, v66, s78
	s_waitcnt vmcnt(34)
	v_bfe_u32 v70, v86, 16, 1
	v_lshrrev_b32_e32 v66, 16, v66
	v_add3_u32 v70, v86, v70, s78
	v_and_or_b32 v174, v70, s79, v66
	s_waitcnt vmcnt(33)
	v_bfe_u32 v66, v90, 16, 1
	v_add3_u32 v66, v90, v66, s78
	s_waitcnt vmcnt(32)
	v_bfe_u32 v70, v94, 16, 1
	v_lshrrev_b32_e32 v66, 16, v66
	v_add3_u32 v70, v94, v70, s78
	v_and_or_b32 v175, v70, s79, v66
	s_waitcnt vmcnt(31)
	v_bfe_u32 v66, v98, 16, 1
	v_add3_u32 v66, v98, v66, s78
	s_waitcnt vmcnt(30)
	v_bfe_u32 v70, v102, 16, 1
	v_lshrrev_b32_e32 v66, 16, v66
	v_add3_u32 v70, v102, v70, s78
	v_and_or_b32 v176, v70, s79, v66
	s_waitcnt vmcnt(29)
	v_bfe_u32 v66, v106, 16, 1
	v_add3_u32 v66, v106, v66, s78
	s_waitcnt vmcnt(28)
	v_bfe_u32 v70, v110, 16, 1
	v_lshrrev_b32_e32 v66, 16, v66
	v_add3_u32 v70, v110, v70, s78
	v_and_or_b32 v177, v70, s79, v66
	s_waitcnt vmcnt(27)
	v_bfe_u32 v66, v114, 16, 1
	v_add3_u32 v66, v114, v66, s78
	s_waitcnt vmcnt(26)
	v_bfe_u32 v70, v118, 16, 1
	v_lshrrev_b32_e32 v66, 16, v66
	v_add3_u32 v70, v118, v70, s78
	v_and_or_b32 v178, v70, s79, v66
	s_waitcnt vmcnt(25)
	v_bfe_u32 v66, v122, 16, 1
	v_add3_u32 v66, v122, v66, s78
	s_waitcnt vmcnt(24)
	v_bfe_u32 v70, v126, 16, 1
	v_lshrrev_b32_e32 v66, 16, v66
	v_add3_u32 v70, v126, v70, s78
	v_and_or_b32 v179, v70, s79, v66
	v_bfe_u32 v66, v67, 16, 1
	v_add3_u32 v66, v67, v66, s78
	v_bfe_u32 v67, v71, 16, 1
	v_lshrrev_b32_e32 v66, 16, v66
	v_add3_u32 v67, v71, v67, s78
	ds_write_b128 v163, v[172:175]
	ds_write_b128 v163, v[176:179] offset:16
	v_and_or_b32 v172, v67, s79, v66
	v_bfe_u32 v66, v75, 16, 1
	v_add3_u32 v66, v75, v66, s78
	v_bfe_u32 v67, v79, 16, 1
	v_lshrrev_b32_e32 v66, 16, v66
	v_add3_u32 v67, v79, v67, s78
	v_and_or_b32 v173, v67, s79, v66
	v_bfe_u32 v66, v83, 16, 1
	v_add3_u32 v66, v83, v66, s78
	v_bfe_u32 v67, v87, 16, 1
	v_lshrrev_b32_e32 v66, 16, v66
	v_add3_u32 v67, v87, v67, s78
	v_and_or_b32 v174, v67, s79, v66
	v_bfe_u32 v66, v91, 16, 1
	v_add3_u32 v66, v91, v66, s78
	v_bfe_u32 v67, v95, 16, 1
	v_lshrrev_b32_e32 v66, 16, v66
	v_add3_u32 v67, v95, v67, s78
	v_and_or_b32 v175, v67, s79, v66
	v_bfe_u32 v66, v99, 16, 1
	v_add3_u32 v66, v99, v66, s78
	v_bfe_u32 v67, v103, 16, 1
	v_lshrrev_b32_e32 v66, 16, v66
	v_add3_u32 v67, v103, v67, s78
	v_and_or_b32 v176, v67, s79, v66
	v_bfe_u32 v66, v107, 16, 1
	v_add3_u32 v66, v107, v66, s78
	v_bfe_u32 v67, v111, 16, 1
	v_lshrrev_b32_e32 v66, 16, v66
	v_add3_u32 v67, v111, v67, s78
	v_and_or_b32 v177, v67, s79, v66
	v_bfe_u32 v66, v115, 16, 1
	v_add3_u32 v66, v115, v66, s78
	v_bfe_u32 v67, v119, 16, 1
	v_lshrrev_b32_e32 v66, 16, v66
	v_add3_u32 v67, v119, v67, s78
	v_and_or_b32 v178, v67, s79, v66
	v_bfe_u32 v66, v123, 16, 1
	v_add3_u32 v66, v123, v66, s78
	v_bfe_u32 v67, v127, 16, 1
	v_lshrrev_b32_e32 v66, 16, v66
	v_add3_u32 v67, v127, v67, s78
	v_and_or_b32 v179, v67, s79, v66
	v_bfe_u32 v66, v68, 16, 1
	v_add3_u32 v66, v68, v66, s78
	v_bfe_u32 v67, v72, 16, 1
	v_lshrrev_b32_e32 v66, 16, v66
	v_add3_u32 v67, v72, v67, s78
	ds_write_b128 v163, v[172:175] offset:144
	ds_write_b128 v163, v[176:179] offset:160
	v_and_or_b32 v172, v67, s79, v66
	v_bfe_u32 v66, v76, 16, 1
	v_add3_u32 v66, v76, v66, s78
	v_bfe_u32 v67, v80, 16, 1
	v_lshrrev_b32_e32 v66, 16, v66
	v_add3_u32 v67, v80, v67, s78
	v_and_or_b32 v173, v67, s79, v66
	v_bfe_u32 v66, v84, 16, 1
	v_add3_u32 v66, v84, v66, s78
	v_bfe_u32 v67, v88, 16, 1
	v_lshrrev_b32_e32 v66, 16, v66
	v_add3_u32 v67, v88, v67, s78
	v_and_or_b32 v174, v67, s79, v66
	v_bfe_u32 v66, v92, 16, 1
	v_add3_u32 v66, v92, v66, s78
	v_bfe_u32 v67, v96, 16, 1
	v_lshrrev_b32_e32 v66, 16, v66
	v_add3_u32 v67, v96, v67, s78
	v_and_or_b32 v175, v67, s79, v66
	v_bfe_u32 v66, v100, 16, 1
	v_add3_u32 v66, v100, v66, s78
	v_bfe_u32 v67, v104, 16, 1
	v_lshrrev_b32_e32 v66, 16, v66
	v_add3_u32 v67, v104, v67, s78
	v_and_or_b32 v176, v67, s79, v66
	v_bfe_u32 v66, v108, 16, 1
	v_add3_u32 v66, v108, v66, s78
	v_bfe_u32 v67, v112, 16, 1
	v_lshrrev_b32_e32 v66, 16, v66
	v_add3_u32 v67, v112, v67, s78
	v_and_or_b32 v177, v67, s79, v66
	v_bfe_u32 v66, v116, 16, 1
	v_add3_u32 v66, v116, v66, s78
	v_bfe_u32 v67, v120, 16, 1
	v_lshrrev_b32_e32 v66, 16, v66
	v_add3_u32 v67, v120, v67, s78
	v_and_or_b32 v178, v67, s79, v66
	v_bfe_u32 v66, v124, 16, 1
	v_add3_u32 v66, v124, v66, s78
	v_bfe_u32 v67, v128, 16, 1
	v_lshrrev_b32_e32 v66, 16, v66
	v_add3_u32 v67, v128, v67, s78
	v_and_or_b32 v179, v67, s79, v66
	v_bfe_u32 v66, v69, 16, 1
	v_add3_u32 v66, v69, v66, s78
	v_bfe_u32 v67, v73, 16, 1
	v_lshrrev_b32_e32 v66, 16, v66
	v_add3_u32 v67, v73, v67, s78
	v_and_or_b32 v66, v67, s79, v66
	v_bfe_u32 v67, v77, 16, 1
	v_add3_u32 v67, v77, v67, s78
	v_bfe_u32 v68, v81, 16, 1
	v_lshrrev_b32_e32 v67, 16, v67
	v_add3_u32 v68, v81, v68, s78
	v_and_or_b32 v67, v68, s79, v67
	v_bfe_u32 v68, v85, 16, 1
	v_add3_u32 v68, v85, v68, s78
	v_bfe_u32 v69, v89, 16, 1
	v_lshrrev_b32_e32 v68, 16, v68
	v_add3_u32 v69, v89, v69, s78
	v_and_or_b32 v68, v69, s79, v68
	v_bfe_u32 v69, v93, 16, 1
	v_add3_u32 v69, v93, v69, s78
	v_bfe_u32 v70, v97, 16, 1
	v_lshrrev_b32_e32 v69, 16, v69
	v_add3_u32 v70, v97, v70, s78
	v_and_or_b32 v69, v70, s79, v69
	v_bfe_u32 v70, v101, 16, 1
	v_add3_u32 v70, v101, v70, s78
	v_bfe_u32 v71, v105, 16, 1
	v_lshrrev_b32_e32 v70, 16, v70
	v_add3_u32 v71, v105, v71, s78
	v_and_or_b32 v70, v71, s79, v70
	v_bfe_u32 v71, v109, 16, 1
	v_add3_u32 v71, v109, v71, s78
	v_bfe_u32 v72, v113, 16, 1
	v_lshrrev_b32_e32 v71, 16, v71
	v_add3_u32 v72, v113, v72, s78
	v_and_or_b32 v71, v72, s79, v71
	v_bfe_u32 v72, v117, 16, 1
	v_add3_u32 v72, v117, v72, s78
	v_bfe_u32 v73, v121, 16, 1
	v_lshrrev_b32_e32 v72, 16, v72
	v_add3_u32 v73, v121, v73, s78
	v_and_or_b32 v72, v73, s79, v72
	v_bfe_u32 v73, v125, 16, 1
	v_add3_u32 v73, v125, v73, s78
	v_bfe_u32 v74, v129, 16, 1
	v_lshrrev_b32_e32 v73, 16, v73
	v_add3_u32 v74, v129, v74, s78
	ds_write_b128 v163, v[172:175] offset:288
	ds_write_b128 v163, v[176:179] offset:304
	v_and_or_b32 v73, v74, s79, v73
	ds_write_b128 v163, v[66:69] offset:432
	ds_write_b128 v163, v[70:73] offset:448
	s_waitcnt lgkmcnt(0)
	ds_read_b128 v[66:69], v171
	ds_read_b128 v[70:73], v171 offset:1152
	ds_read_b128 v[74:77], v171 offset:2304
	s_waitcnt lgkmcnt(2)
	global_store_dwordx4 v[144:145], v[66:69], off offset:256
	s_waitcnt lgkmcnt(1)
	global_store_dwordx4 v[146:147], v[70:73], off offset:256
	s_waitcnt lgkmcnt(0)
	global_store_dwordx4 v[150:151], v[74:77], off offset:256
	ds_read_b128 v[66:69], v171 offset:3456
	ds_read_b128 v[70:73], v171 offset:4608
	ds_read_b128 v[74:77], v171 offset:5760
	ds_read_b128 v[78:81], v171 offset:6912
	ds_read_b128 v[82:85], v171 offset:8064
	s_waitcnt lgkmcnt(4)
	global_store_dwordx4 v[148:149], v[66:69], off offset:256
	s_waitcnt lgkmcnt(3)
	global_store_dwordx4 v[152:153], v[70:73], off offset:256
	s_waitcnt lgkmcnt(2)
	global_store_dwordx4 v[154:155], v[74:77], off offset:256
	s_waitcnt lgkmcnt(1)
	global_store_dwordx4 v[156:157], v[78:81], off offset:256
	s_waitcnt lgkmcnt(0)
	global_store_dwordx4 v[158:159], v[82:85], off offset:256
	s_waitcnt vmcnt(23)
	v_bfe_u32 v66, v2, 16, 1
	v_add3_u32 v2, v2, v66, s78
	s_waitcnt vmcnt(22)
	v_bfe_u32 v66, v6, 16, 1
	v_lshrrev_b32_e32 v2, 16, v2
	v_add3_u32 v6, v6, v66, s78
	v_and_or_b32 v66, v6, s79, v2
	s_waitcnt vmcnt(21)
	v_bfe_u32 v2, v10, 16, 1
	v_add3_u32 v2, v10, v2, s78
	s_waitcnt vmcnt(20)
	v_bfe_u32 v6, v14, 16, 1
	v_lshrrev_b32_e32 v2, 16, v2
	v_add3_u32 v6, v14, v6, s78
	v_and_or_b32 v67, v6, s79, v2
	s_waitcnt vmcnt(19)
	v_bfe_u32 v2, v18, 16, 1
	v_add3_u32 v2, v18, v2, s78
	s_waitcnt vmcnt(18)
	v_bfe_u32 v6, v22, 16, 1
	v_lshrrev_b32_e32 v2, 16, v2
	v_add3_u32 v6, v22, v6, s78
	v_and_or_b32 v68, v6, s79, v2
	s_waitcnt vmcnt(17)
	v_bfe_u32 v2, v26, 16, 1
	v_add3_u32 v2, v26, v2, s78
	s_waitcnt vmcnt(16)
	v_bfe_u32 v6, v30, 16, 1
	v_lshrrev_b32_e32 v2, 16, v2
	v_add3_u32 v6, v30, v6, s78
	v_and_or_b32 v69, v6, s79, v2
	s_waitcnt vmcnt(15)
	v_bfe_u32 v2, v34, 16, 1
	v_add3_u32 v2, v34, v2, s78
	s_waitcnt vmcnt(14)
	v_bfe_u32 v6, v38, 16, 1
	v_lshrrev_b32_e32 v2, 16, v2
	v_add3_u32 v6, v38, v6, s78
	v_and_or_b32 v70, v6, s79, v2
	s_waitcnt vmcnt(13)
	v_bfe_u32 v2, v42, 16, 1
	v_add3_u32 v2, v42, v2, s78
	s_waitcnt vmcnt(12)
	v_bfe_u32 v6, v46, 16, 1
	v_lshrrev_b32_e32 v2, 16, v2
	v_add3_u32 v6, v46, v6, s78
	v_and_or_b32 v71, v6, s79, v2
	s_waitcnt vmcnt(11)
	v_bfe_u32 v2, v50, 16, 1
	v_add3_u32 v2, v50, v2, s78
	s_waitcnt vmcnt(10)
	v_bfe_u32 v6, v54, 16, 1
	v_lshrrev_b32_e32 v2, 16, v2
	v_add3_u32 v6, v54, v6, s78
	v_and_or_b32 v72, v6, s79, v2
	s_waitcnt vmcnt(9)
	v_bfe_u32 v2, v58, 16, 1
	v_add3_u32 v2, v58, v2, s78
	s_waitcnt vmcnt(8)
	v_bfe_u32 v6, v62, 16, 1
	v_lshrrev_b32_e32 v2, 16, v2
	v_add3_u32 v6, v62, v6, s78
	v_and_or_b32 v73, v6, s79, v2
	v_bfe_u32 v2, v3, 16, 1
	v_add3_u32 v2, v3, v2, s78
	v_bfe_u32 v3, v7, 16, 1
	s_waitcnt lgkmcnt(0)
	v_lshrrev_b32_e32 v2, 16, v2
	v_add3_u32 v3, v7, v3, s78
	ds_write_b128 v163, v[66:69]
	ds_write_b128 v163, v[70:73] offset:16
	v_and_or_b32 v66, v3, s79, v2
	v_bfe_u32 v2, v11, 16, 1
	v_add3_u32 v2, v11, v2, s78
	v_bfe_u32 v3, v15, 16, 1
	v_lshrrev_b32_e32 v2, 16, v2
	v_add3_u32 v3, v15, v3, s78
	v_and_or_b32 v67, v3, s79, v2
	v_bfe_u32 v2, v19, 16, 1
	v_add3_u32 v2, v19, v2, s78
	v_bfe_u32 v3, v23, 16, 1
	v_lshrrev_b32_e32 v2, 16, v2
	v_add3_u32 v3, v23, v3, s78
	v_and_or_b32 v68, v3, s79, v2
	v_bfe_u32 v2, v27, 16, 1
	v_add3_u32 v2, v27, v2, s78
	v_bfe_u32 v3, v31, 16, 1
	v_lshrrev_b32_e32 v2, 16, v2
	v_add3_u32 v3, v31, v3, s78
	v_and_or_b32 v69, v3, s79, v2
	v_bfe_u32 v2, v35, 16, 1
	v_add3_u32 v2, v35, v2, s78
	v_bfe_u32 v3, v39, 16, 1
	v_lshrrev_b32_e32 v2, 16, v2
	v_add3_u32 v3, v39, v3, s78
	v_and_or_b32 v70, v3, s79, v2
	v_bfe_u32 v2, v43, 16, 1
	v_add3_u32 v2, v43, v2, s78
	v_bfe_u32 v3, v47, 16, 1
	v_lshrrev_b32_e32 v2, 16, v2
	v_add3_u32 v3, v47, v3, s78
	v_and_or_b32 v71, v3, s79, v2
	v_bfe_u32 v2, v51, 16, 1
	v_add3_u32 v2, v51, v2, s78
	v_bfe_u32 v3, v55, 16, 1
	v_lshrrev_b32_e32 v2, 16, v2
	v_add3_u32 v3, v55, v3, s78
	v_and_or_b32 v72, v3, s79, v2
	v_bfe_u32 v2, v59, 16, 1
	v_add3_u32 v2, v59, v2, s78
	v_bfe_u32 v3, v63, 16, 1
	v_lshrrev_b32_e32 v2, 16, v2
	v_add3_u32 v3, v63, v3, s78
	v_and_or_b32 v73, v3, s79, v2
	v_bfe_u32 v2, v4, 16, 1
	v_add3_u32 v2, v4, v2, s78
	v_bfe_u32 v3, v8, 16, 1
	v_lshrrev_b32_e32 v2, 16, v2
	v_add3_u32 v3, v8, v3, s78
	ds_write_b128 v163, v[66:69] offset:144
	ds_write_b128 v163, v[70:73] offset:160
	v_and_or_b32 v66, v3, s79, v2
	v_bfe_u32 v2, v12, 16, 1
	v_add3_u32 v2, v12, v2, s78
	v_bfe_u32 v3, v16, 16, 1
	v_lshrrev_b32_e32 v2, 16, v2
	v_add3_u32 v3, v16, v3, s78
	v_and_or_b32 v67, v3, s79, v2
	v_bfe_u32 v2, v20, 16, 1
	v_add3_u32 v2, v20, v2, s78
	v_bfe_u32 v3, v24, 16, 1
	v_lshrrev_b32_e32 v2, 16, v2
	v_add3_u32 v3, v24, v3, s78
	v_and_or_b32 v68, v3, s79, v2
	v_bfe_u32 v2, v28, 16, 1
	v_add3_u32 v2, v28, v2, s78
	v_bfe_u32 v3, v32, 16, 1
	v_lshrrev_b32_e32 v2, 16, v2
	v_add3_u32 v3, v32, v3, s78
	v_and_or_b32 v69, v3, s79, v2
	v_bfe_u32 v2, v36, 16, 1
	v_add3_u32 v2, v36, v2, s78
	v_bfe_u32 v3, v40, 16, 1
	v_lshrrev_b32_e32 v2, 16, v2
	v_add3_u32 v3, v40, v3, s78
	v_and_or_b32 v70, v3, s79, v2
	v_bfe_u32 v2, v44, 16, 1
	v_add3_u32 v2, v44, v2, s78
	v_bfe_u32 v3, v48, 16, 1
	v_lshrrev_b32_e32 v2, 16, v2
	v_add3_u32 v3, v48, v3, s78
	v_and_or_b32 v71, v3, s79, v2
	v_bfe_u32 v2, v52, 16, 1
	v_add3_u32 v2, v52, v2, s78
	v_bfe_u32 v3, v56, 16, 1
	v_lshrrev_b32_e32 v2, 16, v2
	v_add3_u32 v3, v56, v3, s78
	v_and_or_b32 v72, v3, s79, v2
	v_bfe_u32 v2, v60, 16, 1
	v_add3_u32 v2, v60, v2, s78
	v_bfe_u32 v3, v64, 16, 1
	v_lshrrev_b32_e32 v2, 16, v2
	v_add3_u32 v3, v64, v3, s78
	v_and_or_b32 v73, v3, s79, v2
	v_bfe_u32 v2, v5, 16, 1
	v_add3_u32 v2, v5, v2, s78
	v_bfe_u32 v3, v9, 16, 1
	v_lshrrev_b32_e32 v2, 16, v2
	v_add3_u32 v3, v9, v3, s78
	v_and_or_b32 v2, v3, s79, v2
	v_bfe_u32 v3, v13, 16, 1
	v_add3_u32 v3, v13, v3, s78
	v_bfe_u32 v4, v17, 16, 1
	v_lshrrev_b32_e32 v3, 16, v3
	v_add3_u32 v4, v17, v4, s78
	v_and_or_b32 v3, v4, s79, v3
	v_bfe_u32 v4, v21, 16, 1
	v_add3_u32 v4, v21, v4, s78
	v_bfe_u32 v5, v25, 16, 1
	v_lshrrev_b32_e32 v4, 16, v4
	v_add3_u32 v5, v25, v5, s78
	v_and_or_b32 v4, v5, s79, v4
	v_bfe_u32 v5, v29, 16, 1
	v_add3_u32 v5, v29, v5, s78
	v_bfe_u32 v6, v33, 16, 1
	v_lshrrev_b32_e32 v5, 16, v5
	v_add3_u32 v6, v33, v6, s78
	v_and_or_b32 v5, v6, s79, v5
	v_bfe_u32 v6, v37, 16, 1
	v_add3_u32 v6, v37, v6, s78
	v_bfe_u32 v7, v41, 16, 1
	v_lshrrev_b32_e32 v6, 16, v6
	v_add3_u32 v7, v41, v7, s78
	v_and_or_b32 v6, v7, s79, v6
	v_bfe_u32 v7, v45, 16, 1
	v_add3_u32 v7, v45, v7, s78
	v_bfe_u32 v8, v49, 16, 1
	v_lshrrev_b32_e32 v7, 16, v7
	v_add3_u32 v8, v49, v8, s78
	v_and_or_b32 v7, v8, s79, v7
	v_bfe_u32 v8, v53, 16, 1
	v_add3_u32 v8, v53, v8, s78
	v_bfe_u32 v9, v57, 16, 1
	v_lshrrev_b32_e32 v8, 16, v8
	v_add3_u32 v9, v57, v9, s78
	v_and_or_b32 v8, v9, s79, v8
	v_bfe_u32 v9, v61, 16, 1
	v_add3_u32 v9, v61, v9, s78
	v_bfe_u32 v10, v65, 16, 1
	v_lshrrev_b32_e32 v9, 16, v9
	v_add3_u32 v10, v65, v10, s78
	ds_write_b128 v163, v[66:69] offset:288
	ds_write_b128 v163, v[70:73] offset:304
	v_and_or_b32 v9, v10, s79, v9
	ds_write_b128 v163, v[2:5] offset:432
	ds_write_b128 v163, v[6:9] offset:448
	s_waitcnt lgkmcnt(0)
	ds_read_b128 v[2:5], v171
	ds_read_b128 v[6:9], v171 offset:1152
	ds_read_b128 v[10:13], v171 offset:2304
	s_waitcnt lgkmcnt(2)
	global_store_dwordx4 v[144:145], v[2:5], off offset:384
	s_waitcnt lgkmcnt(1)
	global_store_dwordx4 v[146:147], v[6:9], off offset:384
	s_waitcnt lgkmcnt(0)
	global_store_dwordx4 v[150:151], v[10:13], off offset:384
	ds_read_b128 v[2:5], v171 offset:3456
	ds_read_b128 v[6:9], v171 offset:4608
	ds_read_b128 v[10:13], v171 offset:5760
	ds_read_b128 v[14:17], v171 offset:6912
	ds_read_b128 v[18:21], v171 offset:8064
	s_waitcnt lgkmcnt(4)
	global_store_dwordx4 v[148:149], v[2:5], off offset:384
	s_waitcnt lgkmcnt(3)
	global_store_dwordx4 v[152:153], v[6:9], off offset:384
	s_waitcnt lgkmcnt(2)
	global_store_dwordx4 v[154:155], v[10:13], off offset:384
	s_waitcnt lgkmcnt(1)
	global_store_dwordx4 v[156:157], v[14:17], off offset:384
	s_waitcnt lgkmcnt(0)
	global_store_dwordx4 v[158:159], v[18:21], off offset:384
	s_waitcnt lgkmcnt(0)
	s_mov_b32 s8, 51

.LBB0_213:
	s_andn2_b64 vcc, exec, s[0:1]
	s_cbranch_vccnz .LBB0_215
	s_lshl_b32 s0, s2, 6
	s_and_b32 s3, s0, 0xfc0
	s_lshl_b32 s0, s2, 2
	s_and_b32 s0, s0, 0x1f00
	s_addk_i32 s0, 0xf000
	v_or_b32_e32 v2, s0, v130
	v_mov_b32_e32 v3, v133
	v_readlane_b32 s46, v248, 35
	v_lshlrev_b64 v[2:3], 14, v[2:3]
	v_readlane_b32 s47, v248, 36
	s_lshl_b32 s8, s3, 2
	s_nop 0
	v_lshl_add_u64 v[2:3], s[46:47], 0, v[2:3]
	v_lshl_add_u64 v[2:3], v[2:3], 0, s[8:9]
	v_lshl_add_u64 v[142:143], v[2:3], 0, v[132:133]
	v_add_co_u32_e32 v2, vcc, s11, v142
	s_nop 1
	v_addc_co_u32_e32 v3, vcc, 0, v143, vcc
	global_load_dwordx4 v[66:69], v[142:143], off nt
	global_load_dwordx4 v[70:73], v[2:3], off nt
	v_add_co_u32_e32 v2, vcc, s12, v142
	s_nop 1
	v_addc_co_u32_e32 v3, vcc, 0, v143, vcc
	v_add_co_u32_e32 v4, vcc, s13, v142
	s_nop 1
	v_addc_co_u32_e32 v5, vcc, 0, v143, vcc
	global_load_dwordx4 v[74:77], v[2:3], off nt
	global_load_dwordx4 v[78:81], v[4:5], off nt
	v_add_co_u32_e32 v2, vcc, s16, v142
	s_nop 1
	v_addc_co_u32_e32 v3, vcc, 0, v143, vcc
	v_add_co_u32_e32 v4, vcc, s17, v142
	s_nop 1
	v_addc_co_u32_e32 v5, vcc, 0, v143, vcc
	global_load_dwordx4 v[82:85], v[2:3], off nt
	global_load_dwordx4 v[86:89], v[4:5], off nt
	v_add_co_u32_e32 v2, vcc, s18, v142
	s_nop 1
	v_addc_co_u32_e32 v3, vcc, 0, v143, vcc
	v_add_co_u32_e32 v4, vcc, s19, v142
	s_nop 1
	v_addc_co_u32_e32 v5, vcc, 0, v143, vcc
	global_load_dwordx4 v[90:93], v[2:3], off nt
	global_load_dwordx4 v[94:97], v[4:5], off nt
	v_add_co_u32_e32 v2, vcc, s20, v142
	s_nop 1
	v_addc_co_u32_e32 v3, vcc, 0, v143, vcc
	v_add_co_u32_e32 v4, vcc, s21, v142
	s_nop 1
	v_addc_co_u32_e32 v5, vcc, 0, v143, vcc
	global_load_dwordx4 v[98:101], v[2:3], off nt
	global_load_dwordx4 v[102:105], v[4:5], off nt
	v_add_co_u32_e32 v2, vcc, s22, v142
	s_nop 1
	v_addc_co_u32_e32 v3, vcc, 0, v143, vcc
	v_add_co_u32_e32 v4, vcc, s23, v142
	s_nop 1
	v_addc_co_u32_e32 v5, vcc, 0, v143, vcc
	global_load_dwordx4 v[106:109], v[2:3], off nt
	global_load_dwordx4 v[110:113], v[4:5], off nt
	v_add_co_u32_e32 v2, vcc, s28, v142
	s_nop 1
	v_addc_co_u32_e32 v3, vcc, 0, v143, vcc
	v_add_co_u32_e32 v4, vcc, s29, v142
	s_nop 1
	v_addc_co_u32_e32 v5, vcc, 0, v143, vcc
	global_load_dwordx4 v[114:117], v[2:3], off nt
	global_load_dwordx4 v[118:121], v[4:5], off nt
	v_add_co_u32_e32 v2, vcc, s34, v142
	s_nop 1
	v_addc_co_u32_e32 v3, vcc, 0, v143, vcc
	v_add_co_u32_e32 v4, vcc, s35, v142
	s_nop 1
	v_addc_co_u32_e32 v5, vcc, 0, v143, vcc
	global_load_dwordx4 v[122:125], v[2:3], off nt
	global_load_dwordx4 v[126:129], v[4:5], off nt
	v_add_co_u32_e32 v2, vcc, s36, v142
	s_mov_b32 s1, s9
	s_nop 0
	v_addc_co_u32_e32 v3, vcc, 0, v143, vcc
	v_add_co_u32_e32 v6, vcc, s37, v142
	global_load_dwordx4 v[2:5], v[2:3], off nt
	s_nop 0
	v_addc_co_u32_e32 v7, vcc, 0, v143, vcc
	v_add_co_u32_e32 v10, vcc, s38, v142
	global_load_dwordx4 v[6:9], v[6:7], off nt
	s_nop 0
	v_addc_co_u32_e32 v11, vcc, 0, v143, vcc
	v_add_co_u32_e32 v14, vcc, s39, v142
	global_load_dwordx4 v[10:13], v[10:11], off nt
	s_nop 0
	v_addc_co_u32_e32 v15, vcc, 0, v143, vcc
	v_add_co_u32_e32 v18, vcc, s40, v142
	global_load_dwordx4 v[14:17], v[14:15], off nt
	s_nop 0
	v_addc_co_u32_e32 v19, vcc, 0, v143, vcc
	v_add_co_u32_e32 v22, vcc, s41, v142
	global_load_dwordx4 v[18:21], v[18:19], off nt
	s_nop 0
	v_addc_co_u32_e32 v23, vcc, 0, v143, vcc
	v_add_co_u32_e32 v26, vcc, s42, v142
	global_load_dwordx4 v[22:25], v[22:23], off nt
	s_nop 0
	v_addc_co_u32_e32 v27, vcc, 0, v143, vcc
	v_add_co_u32_e32 v30, vcc, s43, v142
	global_load_dwordx4 v[26:29], v[26:27], off nt
	s_nop 0
	v_addc_co_u32_e32 v31, vcc, 0, v143, vcc
	v_add_co_u32_e32 v34, vcc, s44, v142
	global_load_dwordx4 v[30:33], v[30:31], off nt
	s_nop 0
	v_addc_co_u32_e32 v35, vcc, 0, v143, vcc
	v_add_co_u32_e32 v38, vcc, s45, v142
	global_load_dwordx4 v[34:37], v[34:35], off nt
	s_nop 0
	v_addc_co_u32_e32 v39, vcc, 0, v143, vcc
	v_add_co_u32_e32 v42, vcc, s50, v142
	global_load_dwordx4 v[38:41], v[38:39], off nt
	s_nop 0
	v_addc_co_u32_e32 v43, vcc, 0, v143, vcc
	v_add_co_u32_e32 v46, vcc, s51, v142
	global_load_dwordx4 v[42:45], v[42:43], off nt
	s_nop 0
	v_addc_co_u32_e32 v47, vcc, 0, v143, vcc
	v_add_co_u32_e32 v50, vcc, s74, v142
	global_load_dwordx4 v[46:49], v[46:47], off nt
	s_nop 0
	v_addc_co_u32_e32 v51, vcc, 0, v143, vcc
	v_add_co_u32_e32 v54, vcc, s75, v142
	global_load_dwordx4 v[50:53], v[50:51], off nt
	s_nop 0
	v_addc_co_u32_e32 v55, vcc, 0, v143, vcc
	v_add_co_u32_e32 v58, vcc, s76, v142
	global_load_dwordx4 v[54:57], v[54:55], off nt
	s_nop 0
	v_addc_co_u32_e32 v59, vcc, 0, v143, vcc
	v_add_co_u32_e32 v62, vcc, s77, v142
	global_load_dwordx4 v[58:61], v[58:59], off nt
	s_nop 0
	v_addc_co_u32_e32 v63, vcc, 0, v143, vcc
	global_load_dwordx4 v[62:65], v[62:63], off nt
	v_lshl_add_u64 v[158:159], s[0:1], 1, v[136:137]
	s_waitcnt vmcnt(31)
	v_bfe_u32 v141, v66, 16, 1
	v_add3_u32 v66, v66, v141, s78
	s_waitcnt vmcnt(30)
	v_bfe_u32 v141, v70, 16, 1
	v_lshrrev_b32_e32 v66, 16, v66
	v_add3_u32 v70, v70, v141, s78
	v_and_or_b32 v144, v70, s79, v66
	s_waitcnt vmcnt(29)
	v_bfe_u32 v66, v74, 16, 1
	v_add3_u32 v66, v74, v66, s78
	s_waitcnt vmcnt(28)
	v_bfe_u32 v70, v78, 16, 1
	v_lshrrev_b32_e32 v66, 16, v66
	v_add3_u32 v70, v78, v70, s78
	v_and_or_b32 v145, v70, s79, v66
	s_waitcnt vmcnt(27)
	v_bfe_u32 v66, v82, 16, 1
	v_add3_u32 v66, v82, v66, s78
	s_waitcnt vmcnt(26)
	v_bfe_u32 v70, v86, 16, 1
	v_lshrrev_b32_e32 v66, 16, v66
	v_add3_u32 v70, v86, v70, s78
	v_and_or_b32 v146, v70, s79, v66
	s_waitcnt vmcnt(25)
	v_bfe_u32 v66, v90, 16, 1
	v_add3_u32 v66, v90, v66, s78
	s_waitcnt vmcnt(24)
	v_bfe_u32 v70, v94, 16, 1
	v_lshrrev_b32_e32 v66, 16, v66
	v_add3_u32 v70, v94, v70, s78
	v_and_or_b32 v147, v70, s79, v66
	s_waitcnt vmcnt(23)
	v_bfe_u32 v66, v98, 16, 1
	v_add3_u32 v66, v98, v66, s78
	s_waitcnt vmcnt(22)
	v_bfe_u32 v70, v102, 16, 1
	v_lshrrev_b32_e32 v66, 16, v66
	v_add3_u32 v70, v102, v70, s78
	v_and_or_b32 v148, v70, s79, v66
	s_waitcnt vmcnt(21)
	v_bfe_u32 v66, v106, 16, 1
	v_add3_u32 v66, v106, v66, s78
	s_waitcnt vmcnt(20)
	v_bfe_u32 v70, v110, 16, 1
	v_lshrrev_b32_e32 v66, 16, v66
	v_add3_u32 v70, v110, v70, s78
	v_and_or_b32 v149, v70, s79, v66
	s_waitcnt vmcnt(19)
	v_bfe_u32 v66, v114, 16, 1
	v_add3_u32 v66, v114, v66, s78
	s_waitcnt vmcnt(18)
	v_bfe_u32 v70, v118, 16, 1
	v_lshrrev_b32_e32 v66, 16, v66
	v_add3_u32 v70, v118, v70, s78
	v_and_or_b32 v150, v70, s79, v66
	s_waitcnt vmcnt(17)
	v_bfe_u32 v66, v122, 16, 1
	v_add3_u32 v66, v122, v66, s78
	s_waitcnt vmcnt(16)
	v_bfe_u32 v70, v126, 16, 1
	v_lshrrev_b32_e32 v66, 16, v66
	v_add3_u32 v70, v126, v70, s78
	v_and_or_b32 v151, v70, s79, v66
	v_bfe_u32 v66, v67, 16, 1
	v_add3_u32 v66, v67, v66, s78
	v_bfe_u32 v67, v71, 16, 1
	v_lshrrev_b32_e32 v66, 16, v66
	v_add3_u32 v67, v71, v67, s78
	ds_write_b128 v163, v[144:147]
	ds_write_b128 v163, v[148:151] offset:16
	v_and_or_b32 v144, v67, s79, v66
	v_bfe_u32 v66, v75, 16, 1
	v_add3_u32 v66, v75, v66, s78
	v_bfe_u32 v67, v79, 16, 1
	v_lshrrev_b32_e32 v66, 16, v66
	v_add3_u32 v67, v79, v67, s78
	v_and_or_b32 v145, v67, s79, v66
	v_bfe_u32 v66, v83, 16, 1
	v_add3_u32 v66, v83, v66, s78
	v_bfe_u32 v67, v87, 16, 1
	v_lshrrev_b32_e32 v66, 16, v66
	v_add3_u32 v67, v87, v67, s78
	v_and_or_b32 v146, v67, s79, v66
	v_bfe_u32 v66, v91, 16, 1
	v_add3_u32 v66, v91, v66, s78
	v_bfe_u32 v67, v95, 16, 1
	v_lshrrev_b32_e32 v66, 16, v66
	v_add3_u32 v67, v95, v67, s78
	v_and_or_b32 v147, v67, s79, v66
	v_bfe_u32 v66, v99, 16, 1
	v_add3_u32 v66, v99, v66, s78
	v_bfe_u32 v67, v103, 16, 1
	v_lshrrev_b32_e32 v66, 16, v66
	v_add3_u32 v67, v103, v67, s78
	v_and_or_b32 v148, v67, s79, v66
	v_bfe_u32 v66, v107, 16, 1
	v_add3_u32 v66, v107, v66, s78
	v_bfe_u32 v67, v111, 16, 1
	v_lshrrev_b32_e32 v66, 16, v66
	v_add3_u32 v67, v111, v67, s78
	v_and_or_b32 v149, v67, s79, v66
	v_bfe_u32 v66, v115, 16, 1
	v_add3_u32 v66, v115, v66, s78
	v_bfe_u32 v67, v119, 16, 1
	v_lshrrev_b32_e32 v66, 16, v66
	v_add3_u32 v67, v119, v67, s78
	v_and_or_b32 v150, v67, s79, v66
	v_bfe_u32 v66, v123, 16, 1
	v_add3_u32 v66, v123, v66, s78
	v_bfe_u32 v67, v127, 16, 1
	v_lshrrev_b32_e32 v66, 16, v66
	v_add3_u32 v67, v127, v67, s78
	v_and_or_b32 v151, v67, s79, v66
	v_bfe_u32 v66, v68, 16, 1
	v_add3_u32 v66, v68, v66, s78
	v_bfe_u32 v67, v72, 16, 1
	v_lshrrev_b32_e32 v66, 16, v66
	v_add3_u32 v67, v72, v67, s78
	ds_write_b128 v163, v[144:147] offset:144
	ds_write_b128 v163, v[148:151] offset:160
	v_and_or_b32 v144, v67, s79, v66
	v_bfe_u32 v66, v76, 16, 1
	v_add3_u32 v66, v76, v66, s78
	v_bfe_u32 v67, v80, 16, 1
	v_lshrrev_b32_e32 v66, 16, v66
	v_add3_u32 v67, v80, v67, s78
	v_and_or_b32 v145, v67, s79, v66
	v_bfe_u32 v66, v84, 16, 1
	v_add3_u32 v66, v84, v66, s78
	v_bfe_u32 v67, v88, 16, 1
	v_lshrrev_b32_e32 v66, 16, v66
	v_add3_u32 v67, v88, v67, s78
	v_and_or_b32 v146, v67, s79, v66
	v_bfe_u32 v66, v92, 16, 1
	v_add3_u32 v66, v92, v66, s78
	v_bfe_u32 v67, v96, 16, 1
	v_lshrrev_b32_e32 v66, 16, v66
	v_add3_u32 v67, v96, v67, s78
	v_and_or_b32 v147, v67, s79, v66
	v_bfe_u32 v66, v100, 16, 1
	v_add3_u32 v66, v100, v66, s78
	v_bfe_u32 v67, v104, 16, 1
	v_lshrrev_b32_e32 v66, 16, v66
	v_add3_u32 v67, v104, v67, s78
	v_and_or_b32 v148, v67, s79, v66
	v_bfe_u32 v66, v108, 16, 1
	v_add3_u32 v66, v108, v66, s78
	v_bfe_u32 v67, v112, 16, 1
	v_lshrrev_b32_e32 v66, 16, v66
	v_add3_u32 v67, v112, v67, s78
	v_and_or_b32 v149, v67, s79, v66
	v_bfe_u32 v66, v116, 16, 1
	v_add3_u32 v66, v116, v66, s78
	v_bfe_u32 v67, v120, 16, 1
	v_lshrrev_b32_e32 v66, 16, v66
	v_add3_u32 v67, v120, v67, s78
	v_and_or_b32 v150, v67, s79, v66
	v_bfe_u32 v66, v124, 16, 1
	v_add3_u32 v66, v124, v66, s78
	v_bfe_u32 v67, v128, 16, 1
	v_lshrrev_b32_e32 v66, 16, v66
	v_add3_u32 v67, v128, v67, s78
	v_and_or_b32 v151, v67, s79, v66
	v_bfe_u32 v66, v69, 16, 1
	v_add3_u32 v66, v69, v66, s78
	v_bfe_u32 v67, v73, 16, 1
	v_lshrrev_b32_e32 v66, 16, v66
	v_add3_u32 v67, v73, v67, s78
	v_and_or_b32 v66, v67, s79, v66
	v_bfe_u32 v67, v77, 16, 1
	v_add3_u32 v67, v77, v67, s78
	v_bfe_u32 v68, v81, 16, 1
	v_lshrrev_b32_e32 v67, 16, v67
	v_add3_u32 v68, v81, v68, s78
	v_and_or_b32 v67, v68, s79, v67
	v_bfe_u32 v68, v85, 16, 1
	v_add3_u32 v68, v85, v68, s78
	v_bfe_u32 v69, v89, 16, 1
	v_lshrrev_b32_e32 v68, 16, v68
	v_add3_u32 v69, v89, v69, s78
	v_and_or_b32 v68, v69, s79, v68
	v_bfe_u32 v69, v93, 16, 1
	v_add3_u32 v69, v93, v69, s78
	v_bfe_u32 v70, v97, 16, 1
	v_lshrrev_b32_e32 v69, 16, v69
	v_add3_u32 v70, v97, v70, s78
	v_and_or_b32 v69, v70, s79, v69
	v_bfe_u32 v70, v101, 16, 1
	v_add3_u32 v70, v101, v70, s78
	v_bfe_u32 v71, v105, 16, 1
	v_lshrrev_b32_e32 v70, 16, v70
	v_add3_u32 v71, v105, v71, s78
	v_and_or_b32 v70, v71, s79, v70
	v_bfe_u32 v71, v109, 16, 1
	v_add3_u32 v71, v109, v71, s78
	v_bfe_u32 v72, v113, 16, 1
	v_lshrrev_b32_e32 v71, 16, v71
	v_add3_u32 v72, v113, v72, s78
	v_and_or_b32 v71, v72, s79, v71
	v_bfe_u32 v72, v117, 16, 1
	v_add3_u32 v72, v117, v72, s78
	v_bfe_u32 v73, v121, 16, 1
	v_lshrrev_b32_e32 v72, 16, v72
	v_add3_u32 v73, v121, v73, s78
	v_and_or_b32 v72, v73, s79, v72
	v_bfe_u32 v73, v125, 16, 1
	v_add3_u32 v73, v125, v73, s78
	v_bfe_u32 v74, v129, 16, 1
	v_lshrrev_b32_e32 v73, 16, v73
	v_add3_u32 v74, v129, v74, s78
	ds_write_b128 v163, v[144:147] offset:288
	ds_write_b128 v163, v[148:151] offset:304
	v_and_or_b32 v73, v74, s79, v73
	ds_write_b128 v163, v[66:69] offset:432
	ds_write_b128 v163, v[70:73] offset:448
	s_waitcnt lgkmcnt(0)
	ds_read_b128 v[66:69], v171
	v_or_b32_e32 v70, s3, v162
	v_lshlrev_b32_e32 v70, 12, v70
	v_mov_b32_e32 v71, v133
	v_lshl_add_u64 v[144:145], v[158:159], 0, v[70:71]
	ds_read_b128 v[70:73], v171 offset:1152
	s_waitcnt lgkmcnt(1)
	global_store_dwordx4 v[144:145], v[66:69], off
	s_nop 1
	v_or_b32_e32 v66, s3, v164
	v_lshlrev_b32_e32 v66, 12, v66
	v_mov_b32_e32 v67, v133
	v_lshl_add_u64 v[146:147], v[158:159], 0, v[66:67]
	ds_read_b128 v[66:69], v171 offset:2304
	s_waitcnt lgkmcnt(1)
	global_store_dwordx4 v[146:147], v[70:73], off
	s_nop 1
	v_or_b32_e32 v70, s3, v165
	v_lshlrev_b32_e32 v70, 12, v70
	v_mov_b32_e32 v71, v133
	v_lshl_add_u64 v[150:151], v[158:159], 0, v[70:71]
	ds_read_b128 v[70:73], v171 offset:3456
	s_waitcnt lgkmcnt(1)
	global_store_dwordx4 v[150:151], v[66:69], off
	s_nop 1
	v_or_b32_e32 v66, s3, v166
	v_lshlrev_b32_e32 v66, 12, v66
	v_mov_b32_e32 v67, v133
	v_lshl_add_u64 v[148:149], v[158:159], 0, v[66:67]
	ds_read_b128 v[66:69], v171 offset:4608
	s_waitcnt lgkmcnt(1)
	global_store_dwordx4 v[148:149], v[70:73], off
	s_nop 1
	v_or_b32_e32 v70, s3, v167
	v_lshlrev_b32_e32 v70, 12, v70
	v_mov_b32_e32 v71, v133
	v_lshl_add_u64 v[152:153], v[158:159], 0, v[70:71]
	ds_read_b128 v[70:73], v171 offset:5760
	s_waitcnt lgkmcnt(1)
	global_store_dwordx4 v[152:153], v[66:69], off
	s_nop 1
	v_or_b32_e32 v66, s3, v168
	v_lshlrev_b32_e32 v66, 12, v66
	v_mov_b32_e32 v67, v133
	v_lshl_add_u64 v[154:155], v[158:159], 0, v[66:67]
	ds_read_b128 v[66:69], v171 offset:6912
	s_waitcnt lgkmcnt(1)
	global_store_dwordx4 v[154:155], v[70:73], off
	s_nop 1
	v_or_b32_e32 v70, s3, v169
	v_lshlrev_b32_e32 v70, 12, v70
	v_mov_b32_e32 v71, v133
	v_lshl_add_u64 v[156:157], v[158:159], 0, v[70:71]
	ds_read_b128 v[70:73], v171 offset:8064
	s_waitcnt lgkmcnt(1)
	global_store_dwordx4 v[156:157], v[66:69], off
	s_nop 1
	v_or_b32_e32 v66, s3, v170
	v_lshlrev_b32_e32 v66, 12, v66
	v_mov_b32_e32 v67, v133
	v_lshl_add_u64 v[158:159], v[158:159], 0, v[66:67]
	v_add_co_u32_e32 v66, vcc, s80, v142
	s_waitcnt lgkmcnt(0)
	global_store_dwordx4 v[158:159], v[70:73], off
	v_addc_co_u32_e32 v67, vcc, 0, v143, vcc
	s_nop 0
	v_add_co_u32_e32 v70, vcc, s81, v142
	s_waitcnt lgkmcnt(0)
	s_nop 1
	v_addc_co_u32_e32 v71, vcc, 0, v143, vcc
	v_add_co_u32_e32 v74, vcc, s82, v142
	global_load_dwordx4 v[66:69], v[66:67], off nt
	s_nop 0
	global_load_dwordx4 v[70:73], v[70:71], off nt
	v_addc_co_u32_e32 v75, vcc, 0, v143, vcc
	v_add_co_u32_e32 v78, vcc, s83, v142
	s_nop 1
	v_addc_co_u32_e32 v79, vcc, 0, v143, vcc
	v_add_co_u32_e32 v82, vcc, s88, v142
	global_load_dwordx4 v[74:77], v[74:75], off nt
	s_nop 0
	global_load_dwordx4 v[78:81], v[78:79], off nt
	v_addc_co_u32_e32 v83, vcc, 0, v143, vcc
	v_add_co_u32_e32 v86, vcc, s89, v142
	s_nop 1
	v_addc_co_u32_e32 v87, vcc, 0, v143, vcc
	v_add_co_u32_e32 v90, vcc, s90, v142
	global_load_dwordx4 v[82:85], v[82:83], off nt
	s_nop 0
	global_load_dwordx4 v[86:89], v[86:87], off nt
	v_addc_co_u32_e32 v91, vcc, 0, v143, vcc
	v_add_co_u32_e32 v94, vcc, s91, v142
	s_nop 1
	v_addc_co_u32_e32 v95, vcc, 0, v143, vcc
	v_add_co_u32_e32 v98, vcc, s92, v142
	global_load_dwordx4 v[90:93], v[90:91], off nt
	s_nop 0
	global_load_dwordx4 v[94:97], v[94:95], off nt
	v_addc_co_u32_e32 v99, vcc, 0, v143, vcc
	v_add_co_u32_e32 v102, vcc, s93, v142
	s_nop 1
	v_addc_co_u32_e32 v103, vcc, 0, v143, vcc
	v_add_co_u32_e32 v106, vcc, s94, v142
	global_load_dwordx4 v[98:101], v[98:99], off nt
	s_nop 0
	global_load_dwordx4 v[102:105], v[102:103], off nt
	v_addc_co_u32_e32 v107, vcc, 0, v143, vcc
	v_add_co_u32_e32 v110, vcc, s95, v142
	s_nop 1
	v_addc_co_u32_e32 v111, vcc, 0, v143, vcc
	v_add_co_u32_e32 v114, vcc, s96, v142
	global_load_dwordx4 v[106:109], v[106:107], off nt
	s_nop 0
	global_load_dwordx4 v[110:113], v[110:111], off nt
	v_addc_co_u32_e32 v115, vcc, 0, v143, vcc
	v_add_co_u32_e32 v118, vcc, s97, v142
	s_nop 1
	v_addc_co_u32_e32 v119, vcc, 0, v143, vcc
	v_add_co_u32_e32 v122, vcc, s84, v142
	global_load_dwordx4 v[114:117], v[114:115], off nt
	s_nop 0
	global_load_dwordx4 v[118:121], v[118:119], off nt
	v_addc_co_u32_e32 v123, vcc, 0, v143, vcc
	v_add_co_u32_e32 v126, vcc, s85, v142
	s_nop 1
	v_addc_co_u32_e32 v127, vcc, 0, v143, vcc
	global_load_dwordx4 v[122:125], v[122:123], off nt
	s_nop 0
	global_load_dwordx4 v[126:129], v[126:127], off nt
	s_waitcnt vmcnt(39)
	v_bfe_u32 v141, v2, 16, 1
	v_add3_u32 v2, v2, v141, s78
	s_waitcnt vmcnt(38)
	v_bfe_u32 v141, v6, 16, 1
	v_lshrrev_b32_e32 v2, 16, v2
	v_add3_u32 v6, v6, v141, s78
	v_and_or_b32 v172, v6, s79, v2
	s_waitcnt vmcnt(37)
	v_bfe_u32 v2, v10, 16, 1
	v_add3_u32 v2, v10, v2, s78
	s_waitcnt vmcnt(36)
	v_bfe_u32 v6, v14, 16, 1
	v_lshrrev_b32_e32 v2, 16, v2
	v_add3_u32 v6, v14, v6, s78
	v_and_or_b32 v173, v6, s79, v2
	s_waitcnt vmcnt(35)
	v_bfe_u32 v2, v18, 16, 1
	v_add3_u32 v2, v18, v2, s78
	s_waitcnt vmcnt(34)
	v_bfe_u32 v6, v22, 16, 1
	v_lshrrev_b32_e32 v2, 16, v2
	v_add3_u32 v6, v22, v6, s78
	v_and_or_b32 v174, v6, s79, v2
	s_waitcnt vmcnt(33)
	v_bfe_u32 v2, v26, 16, 1
	v_add3_u32 v2, v26, v2, s78
	s_waitcnt vmcnt(32)
	v_bfe_u32 v6, v30, 16, 1
	v_lshrrev_b32_e32 v2, 16, v2
	v_add3_u32 v6, v30, v6, s78
	v_and_or_b32 v175, v6, s79, v2
	s_waitcnt vmcnt(31)
	v_bfe_u32 v2, v34, 16, 1
	v_add3_u32 v2, v34, v2, s78
	s_waitcnt vmcnt(30)
	v_bfe_u32 v6, v38, 16, 1
	v_lshrrev_b32_e32 v2, 16, v2
	v_add3_u32 v6, v38, v6, s78
	v_and_or_b32 v176, v6, s79, v2
	s_waitcnt vmcnt(29)
	v_bfe_u32 v2, v42, 16, 1
	v_add3_u32 v2, v42, v2, s78
	s_waitcnt vmcnt(28)
	v_bfe_u32 v6, v46, 16, 1
	v_lshrrev_b32_e32 v2, 16, v2
	v_add3_u32 v6, v46, v6, s78
	v_and_or_b32 v177, v6, s79, v2
	s_waitcnt vmcnt(27)
	v_bfe_u32 v2, v50, 16, 1
	v_add3_u32 v2, v50, v2, s78
	s_waitcnt vmcnt(26)
	v_bfe_u32 v6, v54, 16, 1
	v_lshrrev_b32_e32 v2, 16, v2
	v_add3_u32 v6, v54, v6, s78
	v_and_or_b32 v178, v6, s79, v2
	s_waitcnt vmcnt(25)
	v_bfe_u32 v2, v58, 16, 1
	v_add3_u32 v2, v58, v2, s78
	s_waitcnt vmcnt(24)
	v_bfe_u32 v6, v62, 16, 1
	v_lshrrev_b32_e32 v2, 16, v2
	v_add3_u32 v6, v62, v6, s78
	v_and_or_b32 v179, v6, s79, v2
	v_bfe_u32 v2, v3, 16, 1
	v_add3_u32 v2, v3, v2, s78
	v_bfe_u32 v3, v7, 16, 1
	v_lshrrev_b32_e32 v2, 16, v2
	v_add3_u32 v3, v7, v3, s78
	ds_write_b128 v163, v[172:175]
	ds_write_b128 v163, v[176:179] offset:16
	v_and_or_b32 v172, v3, s79, v2
	v_bfe_u32 v2, v11, 16, 1
	v_add3_u32 v2, v11, v2, s78
	v_bfe_u32 v3, v15, 16, 1
	v_lshrrev_b32_e32 v2, 16, v2
	v_add3_u32 v3, v15, v3, s78
	v_and_or_b32 v173, v3, s79, v2
	v_bfe_u32 v2, v19, 16, 1
	v_add3_u32 v2, v19, v2, s78
	v_bfe_u32 v3, v23, 16, 1
	v_lshrrev_b32_e32 v2, 16, v2
	v_add3_u32 v3, v23, v3, s78
	v_and_or_b32 v174, v3, s79, v2
	v_bfe_u32 v2, v27, 16, 1
	v_add3_u32 v2, v27, v2, s78
	v_bfe_u32 v3, v31, 16, 1
	v_lshrrev_b32_e32 v2, 16, v2
	v_add3_u32 v3, v31, v3, s78
	v_and_or_b32 v175, v3, s79, v2
	v_bfe_u32 v2, v35, 16, 1
	v_add3_u32 v2, v35, v2, s78
	v_bfe_u32 v3, v39, 16, 1
	v_lshrrev_b32_e32 v2, 16, v2
	v_add3_u32 v3, v39, v3, s78
	v_and_or_b32 v176, v3, s79, v2
	v_bfe_u32 v2, v43, 16, 1
	v_add3_u32 v2, v43, v2, s78
	v_bfe_u32 v3, v47, 16, 1
	v_lshrrev_b32_e32 v2, 16, v2
	v_add3_u32 v3, v47, v3, s78
	v_and_or_b32 v177, v3, s79, v2
	v_bfe_u32 v2, v51, 16, 1
	v_add3_u32 v2, v51, v2, s78
	v_bfe_u32 v3, v55, 16, 1
	v_lshrrev_b32_e32 v2, 16, v2
	v_add3_u32 v3, v55, v3, s78
	v_and_or_b32 v178, v3, s79, v2
	v_bfe_u32 v2, v59, 16, 1
	v_add3_u32 v2, v59, v2, s78
	v_bfe_u32 v3, v63, 16, 1
	v_lshrrev_b32_e32 v2, 16, v2
	v_add3_u32 v3, v63, v3, s78
	v_and_or_b32 v179, v3, s79, v2
	v_bfe_u32 v2, v4, 16, 1
	v_add3_u32 v2, v4, v2, s78
	v_bfe_u32 v3, v8, 16, 1
	v_lshrrev_b32_e32 v2, 16, v2
	v_add3_u32 v3, v8, v3, s78
	ds_write_b128 v163, v[172:175] offset:144
	ds_write_b128 v163, v[176:179] offset:160
	v_and_or_b32 v172, v3, s79, v2
	v_bfe_u32 v2, v12, 16, 1
	v_add3_u32 v2, v12, v2, s78
	v_bfe_u32 v3, v16, 16, 1
	v_lshrrev_b32_e32 v2, 16, v2
	v_add3_u32 v3, v16, v3, s78
	v_and_or_b32 v173, v3, s79, v2
	v_bfe_u32 v2, v20, 16, 1
	v_add3_u32 v2, v20, v2, s78
	v_bfe_u32 v3, v24, 16, 1
	v_lshrrev_b32_e32 v2, 16, v2
	v_add3_u32 v3, v24, v3, s78
	v_and_or_b32 v174, v3, s79, v2
	v_bfe_u32 v2, v28, 16, 1
	v_add3_u32 v2, v28, v2, s78
	v_bfe_u32 v3, v32, 16, 1
	v_lshrrev_b32_e32 v2, 16, v2
	v_add3_u32 v3, v32, v3, s78
	v_and_or_b32 v175, v3, s79, v2
	v_bfe_u32 v2, v36, 16, 1
	v_add3_u32 v2, v36, v2, s78
	v_bfe_u32 v3, v40, 16, 1
	v_lshrrev_b32_e32 v2, 16, v2
	v_add3_u32 v3, v40, v3, s78
	v_and_or_b32 v176, v3, s79, v2
	v_bfe_u32 v2, v44, 16, 1
	v_add3_u32 v2, v44, v2, s78
	v_bfe_u32 v3, v48, 16, 1
	v_lshrrev_b32_e32 v2, 16, v2
	v_add3_u32 v3, v48, v3, s78
	v_and_or_b32 v177, v3, s79, v2
	v_bfe_u32 v2, v52, 16, 1
	v_add3_u32 v2, v52, v2, s78
	v_bfe_u32 v3, v56, 16, 1
	v_lshrrev_b32_e32 v2, 16, v2
	v_add3_u32 v3, v56, v3, s78
	v_and_or_b32 v178, v3, s79, v2
	v_bfe_u32 v2, v60, 16, 1
	v_add3_u32 v2, v60, v2, s78
	v_bfe_u32 v3, v64, 16, 1
	v_lshrrev_b32_e32 v2, 16, v2
	v_add3_u32 v3, v64, v3, s78
	v_and_or_b32 v179, v3, s79, v2
	v_bfe_u32 v2, v5, 16, 1
	v_add3_u32 v2, v5, v2, s78
	v_bfe_u32 v3, v9, 16, 1
	v_lshrrev_b32_e32 v2, 16, v2
	v_add3_u32 v3, v9, v3, s78
	v_and_or_b32 v2, v3, s79, v2
	v_bfe_u32 v3, v13, 16, 1
	v_add3_u32 v3, v13, v3, s78
	v_bfe_u32 v4, v17, 16, 1
	v_lshrrev_b32_e32 v3, 16, v3
	v_add3_u32 v4, v17, v4, s78
	v_and_or_b32 v3, v4, s79, v3
	v_bfe_u32 v4, v21, 16, 1
	v_add3_u32 v4, v21, v4, s78
	v_bfe_u32 v5, v25, 16, 1
	v_lshrrev_b32_e32 v4, 16, v4
	v_add3_u32 v5, v25, v5, s78
	v_and_or_b32 v4, v5, s79, v4
	v_bfe_u32 v5, v29, 16, 1
	v_add3_u32 v5, v29, v5, s78
	v_bfe_u32 v6, v33, 16, 1
	v_lshrrev_b32_e32 v5, 16, v5
	v_add3_u32 v6, v33, v6, s78
	v_and_or_b32 v5, v6, s79, v5
	v_bfe_u32 v6, v37, 16, 1
	v_add3_u32 v6, v37, v6, s78
	v_bfe_u32 v7, v41, 16, 1
	v_lshrrev_b32_e32 v6, 16, v6
	v_add3_u32 v7, v41, v7, s78
	v_and_or_b32 v6, v7, s79, v6
	v_bfe_u32 v7, v45, 16, 1
	v_add3_u32 v7, v45, v7, s78
	v_bfe_u32 v8, v49, 16, 1
	v_lshrrev_b32_e32 v7, 16, v7
	v_add3_u32 v8, v49, v8, s78
	v_and_or_b32 v7, v8, s79, v7
	v_bfe_u32 v8, v53, 16, 1
	v_add3_u32 v8, v53, v8, s78
	v_bfe_u32 v9, v57, 16, 1
	v_lshrrev_b32_e32 v8, 16, v8
	v_add3_u32 v9, v57, v9, s78
	v_and_or_b32 v8, v9, s79, v8
	v_bfe_u32 v9, v61, 16, 1
	v_add3_u32 v9, v61, v9, s78
	v_bfe_u32 v10, v65, 16, 1
	v_lshrrev_b32_e32 v9, 16, v9
	v_add3_u32 v10, v65, v10, s78
	ds_write_b128 v163, v[172:175] offset:288
	ds_write_b128 v163, v[176:179] offset:304
	v_and_or_b32 v9, v10, s79, v9
	ds_write_b128 v163, v[2:5] offset:432
	ds_write_b128 v163, v[6:9] offset:448
	s_waitcnt lgkmcnt(0)
	ds_read_b128 v[2:5], v171
	ds_read_b128 v[6:9], v171 offset:1152
	ds_read_b128 v[10:13], v171 offset:2304
	s_waitcnt lgkmcnt(2)
	global_store_dwordx4 v[144:145], v[2:5], off offset:128
	s_waitcnt lgkmcnt(1)
	global_store_dwordx4 v[146:147], v[6:9], off offset:128
	s_waitcnt lgkmcnt(0)
	global_store_dwordx4 v[150:151], v[10:13], off offset:128
	ds_read_b128 v[2:5], v171 offset:3456
	ds_read_b128 v[6:9], v171 offset:4608
	ds_read_b128 v[10:13], v171 offset:5760
	ds_read_b128 v[14:17], v171 offset:6912
	ds_read_b128 v[18:21], v171 offset:8064
	s_waitcnt lgkmcnt(4)
	global_store_dwordx4 v[148:149], v[2:5], off offset:128
	s_waitcnt lgkmcnt(3)
	global_store_dwordx4 v[152:153], v[6:9], off offset:128
	s_waitcnt lgkmcnt(2)
	global_store_dwordx4 v[154:155], v[10:13], off offset:128
	s_waitcnt lgkmcnt(1)
	global_store_dwordx4 v[156:157], v[14:17], off offset:128
	s_waitcnt lgkmcnt(0)
	global_store_dwordx4 v[158:159], v[18:21], off offset:128
	v_add_co_u32_e32 v2, vcc, s54, v142
	s_waitcnt lgkmcnt(0)
	s_nop 1
	v_addc_co_u32_e32 v3, vcc, 0, v143, vcc
	v_add_co_u32_e32 v6, vcc, s55, v142
	s_nop 1
	v_addc_co_u32_e32 v7, vcc, 0, v143, vcc
	v_add_co_u32_e32 v10, vcc, s72, v142
	global_load_dwordx4 v[2:5], v[2:3], off nt
	s_nop 0
	global_load_dwordx4 v[6:9], v[6:7], off nt
	v_addc_co_u32_e32 v11, vcc, 0, v143, vcc
	v_add_co_u32_e32 v14, vcc, s73, v142
	s_nop 1
	v_addc_co_u32_e32 v15, vcc, 0, v143, vcc
	v_add_co_u32_e32 v18, vcc, s86, v142
	global_load_dwordx4 v[10:13], v[10:11], off nt
	s_nop 0
	global_load_dwordx4 v[14:17], v[14:15], off nt
	v_addc_co_u32_e32 v19, vcc, 0, v143, vcc
	v_add_co_u32_e32 v22, vcc, s87, v142
	s_nop 1
	v_addc_co_u32_e32 v23, vcc, 0, v143, vcc
	v_add_co_u32_e32 v26, vcc, s64, v142
	global_load_dwordx4 v[18:21], v[18:19], off nt
	s_nop 0
	global_load_dwordx4 v[22:25], v[22:23], off nt
	v_addc_co_u32_e32 v27, vcc, 0, v143, vcc
	v_add_co_u32_e32 v30, vcc, s65, v142
	s_nop 1
	v_addc_co_u32_e32 v31, vcc, 0, v143, vcc
	v_add_co_u32_e32 v34, vcc, s70, v142
	global_load_dwordx4 v[26:29], v[26:27], off nt
	s_nop 0
	global_load_dwordx4 v[30:33], v[30:31], off nt
	v_addc_co_u32_e32 v35, vcc, 0, v143, vcc
	v_add_co_u32_e32 v38, vcc, s71, v142
	s_nop 1
	v_addc_co_u32_e32 v39, vcc, 0, v143, vcc
	v_add_co_u32_e32 v42, vcc, s66, v142
	global_load_dwordx4 v[34:37], v[34:35], off nt
	s_nop 0
	global_load_dwordx4 v[38:41], v[38:39], off nt
	v_addc_co_u32_e32 v43, vcc, 0, v143, vcc
	v_add_co_u32_e32 v46, vcc, s67, v142
	s_nop 1
	v_addc_co_u32_e32 v47, vcc, 0, v143, vcc
	v_add_co_u32_e32 v50, vcc, s52, v142
	global_load_dwordx4 v[42:45], v[42:43], off nt
	s_nop 0
	global_load_dwordx4 v[46:49], v[46:47], off nt
	v_addc_co_u32_e32 v51, vcc, 0, v143, vcc
	v_add_co_u32_e32 v54, vcc, s53, v142
	s_nop 1
	v_addc_co_u32_e32 v55, vcc, 0, v143, vcc
	v_add_co_u32_e32 v58, vcc, s62, v142
	global_load_dwordx4 v[50:53], v[50:51], off nt
	s_nop 0
	global_load_dwordx4 v[54:57], v[54:55], off nt
	v_addc_co_u32_e32 v59, vcc, 0, v143, vcc
	v_add_co_u32_e32 v62, vcc, s63, v142
	s_nop 1
	v_addc_co_u32_e32 v63, vcc, 0, v143, vcc
	global_load_dwordx4 v[58:61], v[58:59], off nt
	s_nop 0
	global_load_dwordx4 v[62:65], v[62:63], off nt
	s_waitcnt vmcnt(39)
	v_bfe_u32 v141, v66, 16, 1
	v_add3_u32 v66, v66, v141, s78
	s_waitcnt vmcnt(38)
	v_bfe_u32 v141, v70, 16, 1
	v_lshrrev_b32_e32 v66, 16, v66
	v_add3_u32 v70, v70, v141, s78
	v_and_or_b32 v172, v70, s79, v66
	s_waitcnt vmcnt(37)
	v_bfe_u32 v66, v74, 16, 1
	v_add3_u32 v66, v74, v66, s78
	s_waitcnt vmcnt(36)
	v_bfe_u32 v70, v78, 16, 1
	v_lshrrev_b32_e32 v66, 16, v66
	v_add3_u32 v70, v78, v70, s78
	v_and_or_b32 v173, v70, s79, v66
	s_waitcnt vmcnt(35)
	v_bfe_u32 v66, v82, 16, 1
	v_add3_u32 v66, v82, v66, s78
	s_waitcnt vmcnt(34)
	v_bfe_u32 v70, v86, 16, 1
	v_lshrrev_b32_e32 v66, 16, v66
	v_add3_u32 v70, v86, v70, s78
	v_and_or_b32 v174, v70, s79, v66
	s_waitcnt vmcnt(33)
	v_bfe_u32 v66, v90, 16, 1
	v_add3_u32 v66, v90, v66, s78
	s_waitcnt vmcnt(32)
	v_bfe_u32 v70, v94, 16, 1
	v_lshrrev_b32_e32 v66, 16, v66
	v_add3_u32 v70, v94, v70, s78
	v_and_or_b32 v175, v70, s79, v66
	s_waitcnt vmcnt(31)
	v_bfe_u32 v66, v98, 16, 1
	v_add3_u32 v66, v98, v66, s78
	s_waitcnt vmcnt(30)
	v_bfe_u32 v70, v102, 16, 1
	v_lshrrev_b32_e32 v66, 16, v66
	v_add3_u32 v70, v102, v70, s78
	v_and_or_b32 v176, v70, s79, v66
	s_waitcnt vmcnt(29)
	v_bfe_u32 v66, v106, 16, 1
	v_add3_u32 v66, v106, v66, s78
	s_waitcnt vmcnt(28)
	v_bfe_u32 v70, v110, 16, 1
	v_lshrrev_b32_e32 v66, 16, v66
	v_add3_u32 v70, v110, v70, s78
	v_and_or_b32 v177, v70, s79, v66
	s_waitcnt vmcnt(27)
	v_bfe_u32 v66, v114, 16, 1
	v_add3_u32 v66, v114, v66, s78
	s_waitcnt vmcnt(26)
	v_bfe_u32 v70, v118, 16, 1
	v_lshrrev_b32_e32 v66, 16, v66
	v_add3_u32 v70, v118, v70, s78
	v_and_or_b32 v178, v70, s79, v66
	s_waitcnt vmcnt(25)
	v_bfe_u32 v66, v122, 16, 1
	v_add3_u32 v66, v122, v66, s78
	s_waitcnt vmcnt(24)
	v_bfe_u32 v70, v126, 16, 1
	v_lshrrev_b32_e32 v66, 16, v66
	v_add3_u32 v70, v126, v70, s78
	v_and_or_b32 v179, v70, s79, v66
	v_bfe_u32 v66, v67, 16, 1
	v_add3_u32 v66, v67, v66, s78
	v_bfe_u32 v67, v71, 16, 1
	v_lshrrev_b32_e32 v66, 16, v66
	v_add3_u32 v67, v71, v67, s78
	ds_write_b128 v163, v[172:175]
	ds_write_b128 v163, v[176:179] offset:16
	v_and_or_b32 v172, v67, s79, v66
	v_bfe_u32 v66, v75, 16, 1
	v_add3_u32 v66, v75, v66, s78
	v_bfe_u32 v67, v79, 16, 1
	v_lshrrev_b32_e32 v66, 16, v66
	v_add3_u32 v67, v79, v67, s78
	v_and_or_b32 v173, v67, s79, v66
	v_bfe_u32 v66, v83, 16, 1
	v_add3_u32 v66, v83, v66, s78
	v_bfe_u32 v67, v87, 16, 1
	v_lshrrev_b32_e32 v66, 16, v66
	v_add3_u32 v67, v87, v67, s78
	v_and_or_b32 v174, v67, s79, v66
	v_bfe_u32 v66, v91, 16, 1
	v_add3_u32 v66, v91, v66, s78
	v_bfe_u32 v67, v95, 16, 1
	v_lshrrev_b32_e32 v66, 16, v66
	v_add3_u32 v67, v95, v67, s78
	v_and_or_b32 v175, v67, s79, v66
	v_bfe_u32 v66, v99, 16, 1
	v_add3_u32 v66, v99, v66, s78
	v_bfe_u32 v67, v103, 16, 1
	v_lshrrev_b32_e32 v66, 16, v66
	v_add3_u32 v67, v103, v67, s78
	v_and_or_b32 v176, v67, s79, v66
	v_bfe_u32 v66, v107, 16, 1
	v_add3_u32 v66, v107, v66, s78
	v_bfe_u32 v67, v111, 16, 1
	v_lshrrev_b32_e32 v66, 16, v66
	v_add3_u32 v67, v111, v67, s78
	v_and_or_b32 v177, v67, s79, v66
	v_bfe_u32 v66, v115, 16, 1
	v_add3_u32 v66, v115, v66, s78
	v_bfe_u32 v67, v119, 16, 1
	v_lshrrev_b32_e32 v66, 16, v66
	v_add3_u32 v67, v119, v67, s78
	v_and_or_b32 v178, v67, s79, v66
	v_bfe_u32 v66, v123, 16, 1
	v_add3_u32 v66, v123, v66, s78
	v_bfe_u32 v67, v127, 16, 1
	v_lshrrev_b32_e32 v66, 16, v66
	v_add3_u32 v67, v127, v67, s78
	v_and_or_b32 v179, v67, s79, v66
	v_bfe_u32 v66, v68, 16, 1
	v_add3_u32 v66, v68, v66, s78
	v_bfe_u32 v67, v72, 16, 1
	v_lshrrev_b32_e32 v66, 16, v66
	v_add3_u32 v67, v72, v67, s78
	ds_write_b128 v163, v[172:175] offset:144
	ds_write_b128 v163, v[176:179] offset:160
	v_and_or_b32 v172, v67, s79, v66
	v_bfe_u32 v66, v76, 16, 1
	v_add3_u32 v66, v76, v66, s78
	v_bfe_u32 v67, v80, 16, 1
	v_lshrrev_b32_e32 v66, 16, v66
	v_add3_u32 v67, v80, v67, s78
	v_and_or_b32 v173, v67, s79, v66
	v_bfe_u32 v66, v84, 16, 1
	v_add3_u32 v66, v84, v66, s78
	v_bfe_u32 v67, v88, 16, 1
	v_lshrrev_b32_e32 v66, 16, v66
	v_add3_u32 v67, v88, v67, s78
	v_and_or_b32 v174, v67, s79, v66
	v_bfe_u32 v66, v92, 16, 1
	v_add3_u32 v66, v92, v66, s78
	v_bfe_u32 v67, v96, 16, 1
	v_lshrrev_b32_e32 v66, 16, v66
	v_add3_u32 v67, v96, v67, s78
	v_and_or_b32 v175, v67, s79, v66
	v_bfe_u32 v66, v100, 16, 1
	v_add3_u32 v66, v100, v66, s78
	v_bfe_u32 v67, v104, 16, 1
	v_lshrrev_b32_e32 v66, 16, v66
	v_add3_u32 v67, v104, v67, s78
	v_and_or_b32 v176, v67, s79, v66
	v_bfe_u32 v66, v108, 16, 1
	v_add3_u32 v66, v108, v66, s78
	v_bfe_u32 v67, v112, 16, 1
	v_lshrrev_b32_e32 v66, 16, v66
	v_add3_u32 v67, v112, v67, s78
	v_and_or_b32 v177, v67, s79, v66
	v_bfe_u32 v66, v116, 16, 1
	v_add3_u32 v66, v116, v66, s78
	v_bfe_u32 v67, v120, 16, 1
	v_lshrrev_b32_e32 v66, 16, v66
	v_add3_u32 v67, v120, v67, s78
	v_and_or_b32 v178, v67, s79, v66
	v_bfe_u32 v66, v124, 16, 1
	v_add3_u32 v66, v124, v66, s78
	v_bfe_u32 v67, v128, 16, 1
	v_lshrrev_b32_e32 v66, 16, v66
	v_add3_u32 v67, v128, v67, s78
	v_and_or_b32 v179, v67, s79, v66
	v_bfe_u32 v66, v69, 16, 1
	v_add3_u32 v66, v69, v66, s78
	v_bfe_u32 v67, v73, 16, 1
	v_lshrrev_b32_e32 v66, 16, v66
	v_add3_u32 v67, v73, v67, s78
	v_and_or_b32 v66, v67, s79, v66
	v_bfe_u32 v67, v77, 16, 1
	v_add3_u32 v67, v77, v67, s78
	v_bfe_u32 v68, v81, 16, 1
	v_lshrrev_b32_e32 v67, 16, v67
	v_add3_u32 v68, v81, v68, s78
	v_and_or_b32 v67, v68, s79, v67
	v_bfe_u32 v68, v85, 16, 1
	v_add3_u32 v68, v85, v68, s78
	v_bfe_u32 v69, v89, 16, 1
	v_lshrrev_b32_e32 v68, 16, v68
	v_add3_u32 v69, v89, v69, s78
	v_and_or_b32 v68, v69, s79, v68
	v_bfe_u32 v69, v93, 16, 1
	v_add3_u32 v69, v93, v69, s78
	v_bfe_u32 v70, v97, 16, 1
	v_lshrrev_b32_e32 v69, 16, v69
	v_add3_u32 v70, v97, v70, s78
	v_and_or_b32 v69, v70, s79, v69
	v_bfe_u32 v70, v101, 16, 1
	v_add3_u32 v70, v101, v70, s78
	v_bfe_u32 v71, v105, 16, 1
	v_lshrrev_b32_e32 v70, 16, v70
	v_add3_u32 v71, v105, v71, s78
	v_and_or_b32 v70, v71, s79, v70
	v_bfe_u32 v71, v109, 16, 1
	v_add3_u32 v71, v109, v71, s78
	v_bfe_u32 v72, v113, 16, 1
	v_lshrrev_b32_e32 v71, 16, v71
	v_add3_u32 v72, v113, v72, s78
	v_and_or_b32 v71, v72, s79, v71
	v_bfe_u32 v72, v117, 16, 1
	v_add3_u32 v72, v117, v72, s78
	v_bfe_u32 v73, v121, 16, 1
	v_lshrrev_b32_e32 v72, 16, v72
	v_add3_u32 v73, v121, v73, s78
	v_and_or_b32 v72, v73, s79, v72
	v_bfe_u32 v73, v125, 16, 1
	v_add3_u32 v73, v125, v73, s78
	v_bfe_u32 v74, v129, 16, 1
	v_lshrrev_b32_e32 v73, 16, v73
	v_add3_u32 v74, v129, v74, s78
	ds_write_b128 v163, v[172:175] offset:288
	ds_write_b128 v163, v[176:179] offset:304
	v_and_or_b32 v73, v74, s79, v73
	ds_write_b128 v163, v[66:69] offset:432
	ds_write_b128 v163, v[70:73] offset:448
	s_waitcnt lgkmcnt(0)
	ds_read_b128 v[66:69], v171
	ds_read_b128 v[70:73], v171 offset:1152
	ds_read_b128 v[74:77], v171 offset:2304
	s_waitcnt lgkmcnt(2)
	global_store_dwordx4 v[144:145], v[66:69], off offset:256
	s_waitcnt lgkmcnt(1)
	global_store_dwordx4 v[146:147], v[70:73], off offset:256
	s_waitcnt lgkmcnt(0)
	global_store_dwordx4 v[150:151], v[74:77], off offset:256
	ds_read_b128 v[66:69], v171 offset:3456
	ds_read_b128 v[70:73], v171 offset:4608
	ds_read_b128 v[74:77], v171 offset:5760
	ds_read_b128 v[78:81], v171 offset:6912
	ds_read_b128 v[82:85], v171 offset:8064
	s_waitcnt lgkmcnt(4)
	global_store_dwordx4 v[148:149], v[66:69], off offset:256
	s_waitcnt lgkmcnt(3)
	global_store_dwordx4 v[152:153], v[70:73], off offset:256
	s_waitcnt lgkmcnt(2)
	global_store_dwordx4 v[154:155], v[74:77], off offset:256
	s_waitcnt lgkmcnt(1)
	global_store_dwordx4 v[156:157], v[78:81], off offset:256
	s_waitcnt lgkmcnt(0)
	global_store_dwordx4 v[158:159], v[82:85], off offset:256
	s_waitcnt vmcnt(23)
	v_bfe_u32 v66, v2, 16, 1
	v_add3_u32 v2, v2, v66, s78
	s_waitcnt vmcnt(22)
	v_bfe_u32 v66, v6, 16, 1
	v_lshrrev_b32_e32 v2, 16, v2
	v_add3_u32 v6, v6, v66, s78
	v_and_or_b32 v66, v6, s79, v2
	s_waitcnt vmcnt(21)
	v_bfe_u32 v2, v10, 16, 1
	v_add3_u32 v2, v10, v2, s78
	s_waitcnt vmcnt(20)
	v_bfe_u32 v6, v14, 16, 1
	v_lshrrev_b32_e32 v2, 16, v2
	v_add3_u32 v6, v14, v6, s78
	v_and_or_b32 v67, v6, s79, v2
	s_waitcnt vmcnt(19)
	v_bfe_u32 v2, v18, 16, 1
	v_add3_u32 v2, v18, v2, s78
	s_waitcnt vmcnt(18)
	v_bfe_u32 v6, v22, 16, 1
	v_lshrrev_b32_e32 v2, 16, v2
	v_add3_u32 v6, v22, v6, s78
	v_and_or_b32 v68, v6, s79, v2
	s_waitcnt vmcnt(17)
	v_bfe_u32 v2, v26, 16, 1
	v_add3_u32 v2, v26, v2, s78
	s_waitcnt vmcnt(16)
	v_bfe_u32 v6, v30, 16, 1
	v_lshrrev_b32_e32 v2, 16, v2
	v_add3_u32 v6, v30, v6, s78
	v_and_or_b32 v69, v6, s79, v2
	s_waitcnt vmcnt(15)
	v_bfe_u32 v2, v34, 16, 1
	v_add3_u32 v2, v34, v2, s78
	s_waitcnt vmcnt(14)
	v_bfe_u32 v6, v38, 16, 1
	v_lshrrev_b32_e32 v2, 16, v2
	v_add3_u32 v6, v38, v6, s78
	v_and_or_b32 v70, v6, s79, v2
	s_waitcnt vmcnt(13)
	v_bfe_u32 v2, v42, 16, 1
	v_add3_u32 v2, v42, v2, s78
	s_waitcnt vmcnt(12)
	v_bfe_u32 v6, v46, 16, 1
	v_lshrrev_b32_e32 v2, 16, v2
	v_add3_u32 v6, v46, v6, s78
	v_and_or_b32 v71, v6, s79, v2
	s_waitcnt vmcnt(11)
	v_bfe_u32 v2, v50, 16, 1
	v_add3_u32 v2, v50, v2, s78
	s_waitcnt vmcnt(10)
	v_bfe_u32 v6, v54, 16, 1
	v_lshrrev_b32_e32 v2, 16, v2
	v_add3_u32 v6, v54, v6, s78
	v_and_or_b32 v72, v6, s79, v2
	s_waitcnt vmcnt(9)
	v_bfe_u32 v2, v58, 16, 1
	v_add3_u32 v2, v58, v2, s78
	s_waitcnt vmcnt(8)
	v_bfe_u32 v6, v62, 16, 1
	v_lshrrev_b32_e32 v2, 16, v2
	v_add3_u32 v6, v62, v6, s78
	v_and_or_b32 v73, v6, s79, v2
	v_bfe_u32 v2, v3, 16, 1
	v_add3_u32 v2, v3, v2, s78
	v_bfe_u32 v3, v7, 16, 1
	s_waitcnt lgkmcnt(0)
	v_lshrrev_b32_e32 v2, 16, v2
	v_add3_u32 v3, v7, v3, s78
	ds_write_b128 v163, v[66:69]
	ds_write_b128 v163, v[70:73] offset:16
	v_and_or_b32 v66, v3, s79, v2
	v_bfe_u32 v2, v11, 16, 1
	v_add3_u32 v2, v11, v2, s78
	v_bfe_u32 v3, v15, 16, 1
	v_lshrrev_b32_e32 v2, 16, v2
	v_add3_u32 v3, v15, v3, s78
	v_and_or_b32 v67, v3, s79, v2
	v_bfe_u32 v2, v19, 16, 1
	v_add3_u32 v2, v19, v2, s78
	v_bfe_u32 v3, v23, 16, 1
	v_lshrrev_b32_e32 v2, 16, v2
	v_add3_u32 v3, v23, v3, s78
	v_and_or_b32 v68, v3, s79, v2
	v_bfe_u32 v2, v27, 16, 1
	v_add3_u32 v2, v27, v2, s78
	v_bfe_u32 v3, v31, 16, 1
	v_lshrrev_b32_e32 v2, 16, v2
	v_add3_u32 v3, v31, v3, s78
	v_and_or_b32 v69, v3, s79, v2
	v_bfe_u32 v2, v35, 16, 1
	v_add3_u32 v2, v35, v2, s78
	v_bfe_u32 v3, v39, 16, 1
	v_lshrrev_b32_e32 v2, 16, v2
	v_add3_u32 v3, v39, v3, s78
	v_and_or_b32 v70, v3, s79, v2
	v_bfe_u32 v2, v43, 16, 1
	v_add3_u32 v2, v43, v2, s78
	v_bfe_u32 v3, v47, 16, 1
	v_lshrrev_b32_e32 v2, 16, v2
	v_add3_u32 v3, v47, v3, s78
	v_and_or_b32 v71, v3, s79, v2
	v_bfe_u32 v2, v51, 16, 1
	v_add3_u32 v2, v51, v2, s78
	v_bfe_u32 v3, v55, 16, 1
	v_lshrrev_b32_e32 v2, 16, v2
	v_add3_u32 v3, v55, v3, s78
	v_and_or_b32 v72, v3, s79, v2
	v_bfe_u32 v2, v59, 16, 1
	v_add3_u32 v2, v59, v2, s78
	v_bfe_u32 v3, v63, 16, 1
	v_lshrrev_b32_e32 v2, 16, v2
	v_add3_u32 v3, v63, v3, s78
	v_and_or_b32 v73, v3, s79, v2
	v_bfe_u32 v2, v4, 16, 1
	v_add3_u32 v2, v4, v2, s78
	v_bfe_u32 v3, v8, 16, 1
	v_lshrrev_b32_e32 v2, 16, v2
	v_add3_u32 v3, v8, v3, s78
	ds_write_b128 v163, v[66:69] offset:144
	ds_write_b128 v163, v[70:73] offset:160
	v_and_or_b32 v66, v3, s79, v2
	v_bfe_u32 v2, v12, 16, 1
	v_add3_u32 v2, v12, v2, s78
	v_bfe_u32 v3, v16, 16, 1
	v_lshrrev_b32_e32 v2, 16, v2
	v_add3_u32 v3, v16, v3, s78
	v_and_or_b32 v67, v3, s79, v2
	v_bfe_u32 v2, v20, 16, 1
	v_add3_u32 v2, v20, v2, s78
	v_bfe_u32 v3, v24, 16, 1
	v_lshrrev_b32_e32 v2, 16, v2
	v_add3_u32 v3, v24, v3, s78
	v_and_or_b32 v68, v3, s79, v2
	v_bfe_u32 v2, v28, 16, 1
	v_add3_u32 v2, v28, v2, s78
	v_bfe_u32 v3, v32, 16, 1
	v_lshrrev_b32_e32 v2, 16, v2
	v_add3_u32 v3, v32, v3, s78
	v_and_or_b32 v69, v3, s79, v2
	v_bfe_u32 v2, v36, 16, 1
	v_add3_u32 v2, v36, v2, s78
	v_bfe_u32 v3, v40, 16, 1
	v_lshrrev_b32_e32 v2, 16, v2
	v_add3_u32 v3, v40, v3, s78
	v_and_or_b32 v70, v3, s79, v2
	v_bfe_u32 v2, v44, 16, 1
	v_add3_u32 v2, v44, v2, s78
	v_bfe_u32 v3, v48, 16, 1
	v_lshrrev_b32_e32 v2, 16, v2
	v_add3_u32 v3, v48, v3, s78
	v_and_or_b32 v71, v3, s79, v2
	v_bfe_u32 v2, v52, 16, 1
	v_add3_u32 v2, v52, v2, s78
	v_bfe_u32 v3, v56, 16, 1
	v_lshrrev_b32_e32 v2, 16, v2
	v_add3_u32 v3, v56, v3, s78
	v_and_or_b32 v72, v3, s79, v2
	v_bfe_u32 v2, v60, 16, 1
	v_add3_u32 v2, v60, v2, s78
	v_bfe_u32 v3, v64, 16, 1
	v_lshrrev_b32_e32 v2, 16, v2
	v_add3_u32 v3, v64, v3, s78
	v_and_or_b32 v73, v3, s79, v2
	v_bfe_u32 v2, v5, 16, 1
	v_add3_u32 v2, v5, v2, s78
	v_bfe_u32 v3, v9, 16, 1
	v_lshrrev_b32_e32 v2, 16, v2
	v_add3_u32 v3, v9, v3, s78
	v_and_or_b32 v2, v3, s79, v2
	v_bfe_u32 v3, v13, 16, 1
	v_add3_u32 v3, v13, v3, s78
	v_bfe_u32 v4, v17, 16, 1
	v_lshrrev_b32_e32 v3, 16, v3
	v_add3_u32 v4, v17, v4, s78
	v_and_or_b32 v3, v4, s79, v3
	v_bfe_u32 v4, v21, 16, 1
	v_add3_u32 v4, v21, v4, s78
	v_bfe_u32 v5, v25, 16, 1
	v_lshrrev_b32_e32 v4, 16, v4
	v_add3_u32 v5, v25, v5, s78
	v_and_or_b32 v4, v5, s79, v4
	v_bfe_u32 v5, v29, 16, 1
	v_add3_u32 v5, v29, v5, s78
	v_bfe_u32 v6, v33, 16, 1
	v_lshrrev_b32_e32 v5, 16, v5
	v_add3_u32 v6, v33, v6, s78
	v_and_or_b32 v5, v6, s79, v5
	v_bfe_u32 v6, v37, 16, 1
	v_add3_u32 v6, v37, v6, s78
	v_bfe_u32 v7, v41, 16, 1
	v_lshrrev_b32_e32 v6, 16, v6
	v_add3_u32 v7, v41, v7, s78
	v_and_or_b32 v6, v7, s79, v6
	v_bfe_u32 v7, v45, 16, 1
	v_add3_u32 v7, v45, v7, s78
	v_bfe_u32 v8, v49, 16, 1
	v_lshrrev_b32_e32 v7, 16, v7
	v_add3_u32 v8, v49, v8, s78
	v_and_or_b32 v7, v8, s79, v7
	v_bfe_u32 v8, v53, 16, 1
	v_add3_u32 v8, v53, v8, s78
	v_bfe_u32 v9, v57, 16, 1
	v_lshrrev_b32_e32 v8, 16, v8
	v_add3_u32 v9, v57, v9, s78
	v_and_or_b32 v8, v9, s79, v8
	v_bfe_u32 v9, v61, 16, 1
	v_add3_u32 v9, v61, v9, s78
	v_bfe_u32 v10, v65, 16, 1
	v_lshrrev_b32_e32 v9, 16, v9
	v_add3_u32 v10, v65, v10, s78
	ds_write_b128 v163, v[66:69] offset:288
	ds_write_b128 v163, v[70:73] offset:304
	v_and_or_b32 v9, v10, s79, v9
	ds_write_b128 v163, v[2:5] offset:432
	ds_write_b128 v163, v[6:9] offset:448
	s_waitcnt lgkmcnt(0)
	ds_read_b128 v[2:5], v171
	ds_read_b128 v[6:9], v171 offset:1152
	ds_read_b128 v[10:13], v171 offset:2304
	s_waitcnt lgkmcnt(2)
	global_store_dwordx4 v[144:145], v[2:5], off offset:384
	s_waitcnt lgkmcnt(1)
	global_store_dwordx4 v[146:147], v[6:9], off offset:384
	s_waitcnt lgkmcnt(0)
	global_store_dwordx4 v[150:151], v[10:13], off offset:384
	ds_read_b128 v[2:5], v171 offset:3456
	ds_read_b128 v[6:9], v171 offset:4608
	ds_read_b128 v[10:13], v171 offset:5760
	ds_read_b128 v[14:17], v171 offset:6912
	ds_read_b128 v[18:21], v171 offset:8064
	s_waitcnt lgkmcnt(4)
	global_store_dwordx4 v[148:149], v[2:5], off offset:384
	s_waitcnt lgkmcnt(3)
	global_store_dwordx4 v[152:153], v[6:9], off offset:384
	s_waitcnt lgkmcnt(2)
	global_store_dwordx4 v[154:155], v[10:13], off offset:384
	s_waitcnt lgkmcnt(1)
	global_store_dwordx4 v[156:157], v[14:17], off offset:384
	s_waitcnt lgkmcnt(0)
	global_store_dwordx4 v[158:159], v[18:21], off offset:384
	s_waitcnt lgkmcnt(0)
	s_mov_b32 s8, 51

.LBB0_216:
	s_andn2_b64 vcc, exec, s[0:1]
	s_cbranch_vccnz .LBB0_218
	s_ashr_i32 s0, s2, 31
	s_lshr_b32 s0, s0, 25
	s_add_i32 s0, s2, s0
	s_and_b32 s1, s0, 0xffffff80
	s_sub_i32 s1, s2, s1
	s_lshl_b32 s2, s1, 6
	s_lshl_b32 s3, s1, 5
	s_and_b32 s3, s3, 0xffffff80
	s_and_b32 s8, s2, 64
	s_or_b32 s46, s3, s8
	s_bitcmp0_b32 s1, 1
	s_cselect_b32 vcc_hi, s7, s27
	s_cselect_b32 vcc_lo, s6, s26
	s_lshl_b32 s0, s0, 1
	s_and_b32 s0, s0, 0xffffff00
	v_or_b32_e32 v2, s0, v130
	v_ashrrev_i32_e32 v3, 31, v2
	v_lshlrev_b64 v[2:3], 14, v[2:3]
	v_lshl_add_u64 v[2:3], vcc, 0, v[2:3]
	s_ashr_i32 s47, s46, 31
	v_lshl_add_u64 v[2:3], s[46:47], 2, v[2:3]
	v_lshl_add_u64 v[158:159], v[2:3], 0, v[132:133]
	v_add_co_u32_e32 v2, vcc, s11, v158
	s_nop 1
	v_addc_co_u32_e32 v3, vcc, 0, v159, vcc
	global_load_dwordx4 v[66:69], v[158:159], off nt
	global_load_dwordx4 v[70:73], v[2:3], off nt
	v_add_co_u32_e32 v2, vcc, s12, v158
	s_nop 1
	v_addc_co_u32_e32 v3, vcc, 0, v159, vcc
	v_add_co_u32_e32 v4, vcc, s13, v158
	s_nop 1
	v_addc_co_u32_e32 v5, vcc, 0, v159, vcc
	global_load_dwordx4 v[74:77], v[2:3], off nt
	global_load_dwordx4 v[78:81], v[4:5], off nt
	v_add_co_u32_e32 v2, vcc, s16, v158
	s_nop 1
	v_addc_co_u32_e32 v3, vcc, 0, v159, vcc
	v_add_co_u32_e32 v4, vcc, s17, v158
	s_nop 1
	v_addc_co_u32_e32 v5, vcc, 0, v159, vcc
	global_load_dwordx4 v[82:85], v[2:3], off nt
	global_load_dwordx4 v[86:89], v[4:5], off nt
	v_add_co_u32_e32 v2, vcc, s18, v158
	s_nop 1
	v_addc_co_u32_e32 v3, vcc, 0, v159, vcc
	v_add_co_u32_e32 v4, vcc, s19, v158
	s_nop 1
	v_addc_co_u32_e32 v5, vcc, 0, v159, vcc
	global_load_dwordx4 v[90:93], v[2:3], off nt
	global_load_dwordx4 v[94:97], v[4:5], off nt
	v_add_co_u32_e32 v2, vcc, s20, v158
	s_nop 1
	v_addc_co_u32_e32 v3, vcc, 0, v159, vcc
	v_add_co_u32_e32 v4, vcc, s21, v158
	s_nop 1
	v_addc_co_u32_e32 v5, vcc, 0, v159, vcc
	global_load_dwordx4 v[98:101], v[2:3], off nt
	global_load_dwordx4 v[102:105], v[4:5], off nt
	v_add_co_u32_e32 v2, vcc, s22, v158
	s_nop 1
	v_addc_co_u32_e32 v3, vcc, 0, v159, vcc
	v_add_co_u32_e32 v4, vcc, s23, v158
	s_nop 1
	v_addc_co_u32_e32 v5, vcc, 0, v159, vcc
	global_load_dwordx4 v[106:109], v[2:3], off nt
	global_load_dwordx4 v[110:113], v[4:5], off nt
	v_add_co_u32_e32 v2, vcc, s28, v158
	s_nop 1
	v_addc_co_u32_e32 v3, vcc, 0, v159, vcc
	v_add_co_u32_e32 v4, vcc, s29, v158
	s_nop 1
	v_addc_co_u32_e32 v5, vcc, 0, v159, vcc
	global_load_dwordx4 v[114:117], v[2:3], off nt
	global_load_dwordx4 v[118:121], v[4:5], off nt
	v_add_co_u32_e32 v2, vcc, s34, v158
	s_nop 1
	v_addc_co_u32_e32 v3, vcc, 0, v159, vcc
	v_add_co_u32_e32 v4, vcc, s35, v158
	s_nop 1
	v_addc_co_u32_e32 v5, vcc, 0, v159, vcc
	global_load_dwordx4 v[122:125], v[2:3], off nt
	global_load_dwordx4 v[126:129], v[4:5], off nt
	v_add_co_u32_e32 v2, vcc, s36, v158
	s_ashr_i32 s1, s0, 31
	s_nop 0
	v_addc_co_u32_e32 v3, vcc, 0, v159, vcc
	v_add_co_u32_e32 v6, vcc, s37, v158
	global_load_dwordx4 v[2:5], v[2:3], off nt
	s_nop 0
	v_addc_co_u32_e32 v7, vcc, 0, v159, vcc
	v_add_co_u32_e32 v10, vcc, s38, v158
	global_load_dwordx4 v[6:9], v[6:7], off nt
	s_nop 0
	v_addc_co_u32_e32 v11, vcc, 0, v159, vcc
	v_add_co_u32_e32 v14, vcc, s39, v158
	global_load_dwordx4 v[10:13], v[10:11], off nt
	s_nop 0
	v_addc_co_u32_e32 v15, vcc, 0, v159, vcc
	v_add_co_u32_e32 v18, vcc, s40, v158
	global_load_dwordx4 v[14:17], v[14:15], off nt
	s_nop 0
	v_addc_co_u32_e32 v19, vcc, 0, v159, vcc
	v_add_co_u32_e32 v22, vcc, s41, v158
	global_load_dwordx4 v[18:21], v[18:19], off nt
	s_nop 0
	v_addc_co_u32_e32 v23, vcc, 0, v159, vcc
	v_add_co_u32_e32 v26, vcc, s42, v158
	global_load_dwordx4 v[22:25], v[22:23], off nt
	s_nop 0
	v_addc_co_u32_e32 v27, vcc, 0, v159, vcc
	v_add_co_u32_e32 v30, vcc, s43, v158
	global_load_dwordx4 v[26:29], v[26:27], off nt
	s_nop 0
	v_addc_co_u32_e32 v31, vcc, 0, v159, vcc
	global_load_dwordx4 v[34:37], v[30:31], off nt
	v_add_co_u32_e32 v30, vcc, s44, v158
	v_lshl_add_u64 v[156:157], s[0:1], 1, v[138:139]
	s_nop 0
	v_addc_co_u32_e32 v31, vcc, 0, v159, vcc
	v_add_co_u32_e32 v38, vcc, s45, v158
	global_load_dwordx4 v[30:33], v[30:31], off nt
	s_nop 0
	v_addc_co_u32_e32 v39, vcc, 0, v159, vcc
	v_add_co_u32_e32 v42, vcc, s50, v158
	global_load_dwordx4 v[38:41], v[38:39], off nt
	s_nop 0
	v_addc_co_u32_e32 v43, vcc, 0, v159, vcc
	v_add_co_u32_e32 v46, vcc, s51, v158
	global_load_dwordx4 v[42:45], v[42:43], off nt
	s_nop 0
	v_addc_co_u32_e32 v47, vcc, 0, v159, vcc
	v_add_co_u32_e32 v50, vcc, s74, v158
	global_load_dwordx4 v[46:49], v[46:47], off nt
	s_nop 0
	v_addc_co_u32_e32 v51, vcc, 0, v159, vcc
	v_add_co_u32_e32 v54, vcc, s75, v158
	global_load_dwordx4 v[50:53], v[50:51], off nt
	s_nop 0
	v_addc_co_u32_e32 v55, vcc, 0, v159, vcc
	v_add_co_u32_e32 v58, vcc, s76, v158
	global_load_dwordx4 v[54:57], v[54:55], off nt
	s_nop 0
	v_addc_co_u32_e32 v59, vcc, 0, v159, vcc
	v_add_co_u32_e32 v62, vcc, s77, v158
	global_load_dwordx4 v[58:61], v[58:59], off nt
	s_nop 0
	v_addc_co_u32_e32 v63, vcc, 0, v159, vcc
	global_load_dwordx4 v[62:65], v[62:63], off nt
	s_waitcnt vmcnt(31)
	v_bfe_u32 v141, v66, 16, 1
	v_add3_u32 v66, v66, v141, s78
	s_waitcnt vmcnt(30)
	v_bfe_u32 v141, v70, 16, 1
	v_lshrrev_b32_e32 v66, 16, v66
	v_add3_u32 v70, v70, v141, s78
	v_and_or_b32 v142, v70, s79, v66
	s_waitcnt vmcnt(29)
	v_bfe_u32 v66, v74, 16, 1
	v_add3_u32 v66, v74, v66, s78
	s_waitcnt vmcnt(28)
	v_bfe_u32 v70, v78, 16, 1
	v_lshrrev_b32_e32 v66, 16, v66
	v_add3_u32 v70, v78, v70, s78
	v_and_or_b32 v143, v70, s79, v66
	s_waitcnt vmcnt(27)
	v_bfe_u32 v66, v82, 16, 1
	v_add3_u32 v66, v82, v66, s78
	s_waitcnt vmcnt(26)
	v_bfe_u32 v70, v86, 16, 1
	v_lshrrev_b32_e32 v66, 16, v66
	v_add3_u32 v70, v86, v70, s78
	v_and_or_b32 v144, v70, s79, v66
	s_waitcnt vmcnt(25)
	v_bfe_u32 v66, v90, 16, 1
	v_add3_u32 v66, v90, v66, s78
	s_waitcnt vmcnt(24)
	v_bfe_u32 v70, v94, 16, 1
	v_lshrrev_b32_e32 v66, 16, v66
	v_add3_u32 v70, v94, v70, s78
	v_and_or_b32 v145, v70, s79, v66
	s_waitcnt vmcnt(23)
	v_bfe_u32 v66, v98, 16, 1
	v_add3_u32 v66, v98, v66, s78
	s_waitcnt vmcnt(22)
	v_bfe_u32 v70, v102, 16, 1
	v_lshrrev_b32_e32 v66, 16, v66
	v_add3_u32 v70, v102, v70, s78
	v_and_or_b32 v146, v70, s79, v66
	s_waitcnt vmcnt(21)
	v_bfe_u32 v66, v106, 16, 1
	v_add3_u32 v66, v106, v66, s78
	s_waitcnt vmcnt(20)
	v_bfe_u32 v70, v110, 16, 1
	v_lshrrev_b32_e32 v66, 16, v66
	v_add3_u32 v70, v110, v70, s78
	v_and_or_b32 v147, v70, s79, v66
	s_waitcnt vmcnt(19)
	v_bfe_u32 v66, v114, 16, 1
	v_add3_u32 v66, v114, v66, s78
	s_waitcnt vmcnt(18)
	v_bfe_u32 v70, v118, 16, 1
	v_lshrrev_b32_e32 v66, 16, v66
	v_add3_u32 v70, v118, v70, s78
	v_and_or_b32 v148, v70, s79, v66
	s_waitcnt vmcnt(17)
	v_bfe_u32 v66, v122, 16, 1
	v_add3_u32 v66, v122, v66, s78
	s_waitcnt vmcnt(16)
	v_bfe_u32 v70, v126, 16, 1
	v_lshrrev_b32_e32 v66, 16, v66
	v_add3_u32 v70, v126, v70, s78
	v_and_or_b32 v149, v70, s79, v66
	v_bfe_u32 v66, v67, 16, 1
	v_add3_u32 v66, v67, v66, s78
	v_bfe_u32 v67, v71, 16, 1
	v_lshrrev_b32_e32 v66, 16, v66
	v_add3_u32 v67, v71, v67, s78
	ds_write_b128 v163, v[142:145]
	ds_write_b128 v163, v[146:149] offset:16
	v_and_or_b32 v142, v67, s79, v66
	v_bfe_u32 v66, v75, 16, 1
	v_add3_u32 v66, v75, v66, s78
	v_bfe_u32 v67, v79, 16, 1
	v_lshrrev_b32_e32 v66, 16, v66
	v_add3_u32 v67, v79, v67, s78
	v_and_or_b32 v143, v67, s79, v66
	v_bfe_u32 v66, v83, 16, 1
	v_add3_u32 v66, v83, v66, s78
	v_bfe_u32 v67, v87, 16, 1
	v_lshrrev_b32_e32 v66, 16, v66
	v_add3_u32 v67, v87, v67, s78
	v_and_or_b32 v144, v67, s79, v66
	v_bfe_u32 v66, v91, 16, 1
	v_add3_u32 v66, v91, v66, s78
	v_bfe_u32 v67, v95, 16, 1
	v_lshrrev_b32_e32 v66, 16, v66
	v_add3_u32 v67, v95, v67, s78
	v_and_or_b32 v145, v67, s79, v66
	v_bfe_u32 v66, v99, 16, 1
	v_add3_u32 v66, v99, v66, s78
	v_bfe_u32 v67, v103, 16, 1
	v_lshrrev_b32_e32 v66, 16, v66
	v_add3_u32 v67, v103, v67, s78
	v_and_or_b32 v146, v67, s79, v66
	v_bfe_u32 v66, v107, 16, 1
	v_add3_u32 v66, v107, v66, s78
	v_bfe_u32 v67, v111, 16, 1
	v_lshrrev_b32_e32 v66, 16, v66
	v_add3_u32 v67, v111, v67, s78
	v_and_or_b32 v147, v67, s79, v66
	v_bfe_u32 v66, v115, 16, 1
	v_add3_u32 v66, v115, v66, s78
	v_bfe_u32 v67, v119, 16, 1
	v_lshrrev_b32_e32 v66, 16, v66
	v_add3_u32 v67, v119, v67, s78
	v_and_or_b32 v148, v67, s79, v66
	v_bfe_u32 v66, v123, 16, 1
	v_add3_u32 v66, v123, v66, s78
	v_bfe_u32 v67, v127, 16, 1
	v_lshrrev_b32_e32 v66, 16, v66
	v_add3_u32 v67, v127, v67, s78
	v_and_or_b32 v149, v67, s79, v66
	v_bfe_u32 v66, v68, 16, 1
	v_add3_u32 v66, v68, v66, s78
	v_bfe_u32 v67, v72, 16, 1
	v_lshrrev_b32_e32 v66, 16, v66
	v_add3_u32 v67, v72, v67, s78
	ds_write_b128 v163, v[142:145] offset:144
	ds_write_b128 v163, v[146:149] offset:160
	v_and_or_b32 v142, v67, s79, v66
	v_bfe_u32 v66, v76, 16, 1
	v_add3_u32 v66, v76, v66, s78
	v_bfe_u32 v67, v80, 16, 1
	v_lshrrev_b32_e32 v66, 16, v66
	v_add3_u32 v67, v80, v67, s78
	v_and_or_b32 v143, v67, s79, v66
	v_bfe_u32 v66, v84, 16, 1
	v_add3_u32 v66, v84, v66, s78
	v_bfe_u32 v67, v88, 16, 1
	v_lshrrev_b32_e32 v66, 16, v66
	v_add3_u32 v67, v88, v67, s78
	v_and_or_b32 v144, v67, s79, v66
	v_bfe_u32 v66, v92, 16, 1
	v_add3_u32 v66, v92, v66, s78
	v_bfe_u32 v67, v96, 16, 1
	v_lshrrev_b32_e32 v66, 16, v66
	v_add3_u32 v67, v96, v67, s78
	v_and_or_b32 v145, v67, s79, v66
	v_bfe_u32 v66, v100, 16, 1
	v_add3_u32 v66, v100, v66, s78
	v_bfe_u32 v67, v104, 16, 1
	v_lshrrev_b32_e32 v66, 16, v66
	v_add3_u32 v67, v104, v67, s78
	v_and_or_b32 v146, v67, s79, v66
	v_bfe_u32 v66, v108, 16, 1
	v_add3_u32 v66, v108, v66, s78
	v_bfe_u32 v67, v112, 16, 1
	v_lshrrev_b32_e32 v66, 16, v66
	v_add3_u32 v67, v112, v67, s78
	v_and_or_b32 v147, v67, s79, v66
	v_bfe_u32 v66, v116, 16, 1
	v_add3_u32 v66, v116, v66, s78
	v_bfe_u32 v67, v120, 16, 1
	v_lshrrev_b32_e32 v66, 16, v66
	v_add3_u32 v67, v120, v67, s78
	v_and_or_b32 v148, v67, s79, v66
	v_bfe_u32 v66, v124, 16, 1
	v_add3_u32 v66, v124, v66, s78
	v_bfe_u32 v67, v128, 16, 1
	v_lshrrev_b32_e32 v66, 16, v66
	v_add3_u32 v67, v128, v67, s78
	v_and_or_b32 v149, v67, s79, v66
	v_bfe_u32 v66, v69, 16, 1
	v_add3_u32 v66, v69, v66, s78
	v_bfe_u32 v67, v73, 16, 1
	v_lshrrev_b32_e32 v66, 16, v66
	v_add3_u32 v67, v73, v67, s78
	v_and_or_b32 v66, v67, s79, v66
	v_bfe_u32 v67, v77, 16, 1
	v_add3_u32 v67, v77, v67, s78
	v_bfe_u32 v68, v81, 16, 1
	v_lshrrev_b32_e32 v67, 16, v67
	v_add3_u32 v68, v81, v68, s78
	v_and_or_b32 v67, v68, s79, v67
	v_bfe_u32 v68, v85, 16, 1
	v_add3_u32 v68, v85, v68, s78
	v_bfe_u32 v69, v89, 16, 1
	v_lshrrev_b32_e32 v68, 16, v68
	v_add3_u32 v69, v89, v69, s78
	v_and_or_b32 v68, v69, s79, v68
	v_bfe_u32 v69, v93, 16, 1
	v_add3_u32 v69, v93, v69, s78
	v_bfe_u32 v70, v97, 16, 1
	v_lshrrev_b32_e32 v69, 16, v69
	v_add3_u32 v70, v97, v70, s78
	v_and_or_b32 v69, v70, s79, v69
	v_bfe_u32 v70, v101, 16, 1
	v_add3_u32 v70, v101, v70, s78
	v_bfe_u32 v71, v105, 16, 1
	v_lshrrev_b32_e32 v70, 16, v70
	v_add3_u32 v71, v105, v71, s78
	v_and_or_b32 v70, v71, s79, v70
	v_bfe_u32 v71, v109, 16, 1
	v_add3_u32 v71, v109, v71, s78
	v_bfe_u32 v72, v113, 16, 1
	v_lshrrev_b32_e32 v71, 16, v71
	v_add3_u32 v72, v113, v72, s78
	v_and_or_b32 v71, v72, s79, v71
	v_bfe_u32 v72, v117, 16, 1
	v_add3_u32 v72, v117, v72, s78
	v_bfe_u32 v73, v121, 16, 1
	v_lshrrev_b32_e32 v72, 16, v72
	v_add3_u32 v73, v121, v73, s78
	v_and_or_b32 v72, v73, s79, v72
	v_bfe_u32 v73, v125, 16, 1
	v_add3_u32 v73, v125, v73, s78
	v_bfe_u32 v74, v129, 16, 1
	v_lshrrev_b32_e32 v73, 16, v73
	v_add3_u32 v74, v129, v74, s78
	ds_write_b128 v163, v[142:145] offset:288
	ds_write_b128 v163, v[146:149] offset:304
	v_and_or_b32 v73, v74, s79, v73
	ds_write_b128 v163, v[66:69] offset:432
	ds_write_b128 v163, v[70:73] offset:448
	s_waitcnt lgkmcnt(0)
	ds_read_b128 v[66:69], v171
	v_or_b32_e32 v70, s2, v162
	v_ashrrev_i32_e32 v71, 31, v70
	v_lshlrev_b64 v[70:71], 12, v[70:71]
	v_lshl_add_u64 v[142:143], v[156:157], 0, v[70:71]
	ds_read_b128 v[70:73], v171 offset:1152
	s_waitcnt lgkmcnt(1)
	global_store_dwordx4 v[142:143], v[66:69], off
	s_nop 1
	v_or_b32_e32 v66, s2, v164
	v_ashrrev_i32_e32 v67, 31, v66
	v_lshlrev_b64 v[66:67], 12, v[66:67]
	v_lshl_add_u64 v[144:145], v[156:157], 0, v[66:67]
	ds_read_b128 v[66:69], v171 offset:2304
	s_waitcnt lgkmcnt(1)
	global_store_dwordx4 v[144:145], v[70:73], off
	s_nop 1
	v_or_b32_e32 v70, s2, v165
	v_ashrrev_i32_e32 v71, 31, v70
	v_lshlrev_b64 v[70:71], 12, v[70:71]
	v_lshl_add_u64 v[146:147], v[156:157], 0, v[70:71]
	ds_read_b128 v[70:73], v171 offset:3456
	s_waitcnt lgkmcnt(1)
	global_store_dwordx4 v[146:147], v[66:69], off
	s_nop 1
	v_or_b32_e32 v66, s2, v166
	v_ashrrev_i32_e32 v67, 31, v66
	v_lshlrev_b64 v[66:67], 12, v[66:67]
	v_lshl_add_u64 v[148:149], v[156:157], 0, v[66:67]
	ds_read_b128 v[66:69], v171 offset:4608
	s_waitcnt lgkmcnt(1)
	global_store_dwordx4 v[148:149], v[70:73], off
	s_nop 1
	v_or_b32_e32 v70, s2, v167
	v_ashrrev_i32_e32 v71, 31, v70
	v_lshlrev_b64 v[70:71], 12, v[70:71]
	v_lshl_add_u64 v[150:151], v[156:157], 0, v[70:71]
	ds_read_b128 v[70:73], v171 offset:5760
	s_waitcnt lgkmcnt(1)
	global_store_dwordx4 v[150:151], v[66:69], off
	s_nop 1
	v_or_b32_e32 v66, s2, v168
	v_ashrrev_i32_e32 v67, 31, v66
	v_lshlrev_b64 v[66:67], 12, v[66:67]
	v_lshl_add_u64 v[152:153], v[156:157], 0, v[66:67]
	ds_read_b128 v[66:69], v171 offset:6912
	s_waitcnt lgkmcnt(1)
	global_store_dwordx4 v[152:153], v[70:73], off
	s_nop 1
	v_or_b32_e32 v70, s2, v169
	v_ashrrev_i32_e32 v71, 31, v70
	v_lshlrev_b64 v[70:71], 12, v[70:71]
	v_lshl_add_u64 v[154:155], v[156:157], 0, v[70:71]
	ds_read_b128 v[70:73], v171 offset:8064
	s_waitcnt lgkmcnt(1)
	global_store_dwordx4 v[154:155], v[66:69], off
	s_nop 1
	v_or_b32_e32 v66, s2, v170
	v_ashrrev_i32_e32 v67, 31, v66
	v_lshlrev_b64 v[66:67], 12, v[66:67]
	v_lshl_add_u64 v[156:157], v[156:157], 0, v[66:67]
	v_add_co_u32_e32 v66, vcc, s80, v158
	s_waitcnt lgkmcnt(0)
	global_store_dwordx4 v[156:157], v[70:73], off
	v_addc_co_u32_e32 v67, vcc, 0, v159, vcc
	s_nop 0
	v_add_co_u32_e32 v70, vcc, s81, v158
	s_waitcnt lgkmcnt(0)
	s_nop 1
	v_addc_co_u32_e32 v71, vcc, 0, v159, vcc
	v_add_co_u32_e32 v74, vcc, s82, v158
	global_load_dwordx4 v[66:69], v[66:67], off nt
	s_nop 0
	global_load_dwordx4 v[70:73], v[70:71], off nt
	v_addc_co_u32_e32 v75, vcc, 0, v159, vcc
	v_add_co_u32_e32 v78, vcc, s83, v158
	s_nop 1
	v_addc_co_u32_e32 v79, vcc, 0, v159, vcc
	v_add_co_u32_e32 v82, vcc, s88, v158
	global_load_dwordx4 v[74:77], v[74:75], off nt
	s_nop 0
	global_load_dwordx4 v[78:81], v[78:79], off nt
	v_addc_co_u32_e32 v83, vcc, 0, v159, vcc
	v_add_co_u32_e32 v86, vcc, s89, v158
	s_nop 1
	v_addc_co_u32_e32 v87, vcc, 0, v159, vcc
	v_add_co_u32_e32 v90, vcc, s90, v158
	global_load_dwordx4 v[82:85], v[82:83], off nt
	s_nop 0
	global_load_dwordx4 v[86:89], v[86:87], off nt
	v_addc_co_u32_e32 v91, vcc, 0, v159, vcc
	v_add_co_u32_e32 v94, vcc, s91, v158
	s_nop 1
	v_addc_co_u32_e32 v95, vcc, 0, v159, vcc
	v_add_co_u32_e32 v98, vcc, s92, v158
	global_load_dwordx4 v[90:93], v[90:91], off nt
	s_nop 0
	global_load_dwordx4 v[94:97], v[94:95], off nt
	v_addc_co_u32_e32 v99, vcc, 0, v159, vcc
	v_add_co_u32_e32 v102, vcc, s93, v158
	s_nop 1
	v_addc_co_u32_e32 v103, vcc, 0, v159, vcc
	v_add_co_u32_e32 v106, vcc, s94, v158
	global_load_dwordx4 v[98:101], v[98:99], off nt
	s_nop 0
	global_load_dwordx4 v[102:105], v[102:103], off nt
	v_addc_co_u32_e32 v107, vcc, 0, v159, vcc
	v_add_co_u32_e32 v110, vcc, s95, v158
	s_nop 1
	v_addc_co_u32_e32 v111, vcc, 0, v159, vcc
	v_add_co_u32_e32 v114, vcc, s96, v158
	global_load_dwordx4 v[106:109], v[106:107], off nt
	s_nop 0
	global_load_dwordx4 v[110:113], v[110:111], off nt
	v_addc_co_u32_e32 v115, vcc, 0, v159, vcc
	v_add_co_u32_e32 v118, vcc, s97, v158
	s_nop 1
	v_addc_co_u32_e32 v119, vcc, 0, v159, vcc
	v_add_co_u32_e32 v122, vcc, s84, v158
	global_load_dwordx4 v[114:117], v[114:115], off nt
	s_nop 0
	global_load_dwordx4 v[118:121], v[118:119], off nt
	v_addc_co_u32_e32 v123, vcc, 0, v159, vcc
	v_add_co_u32_e32 v126, vcc, s85, v158
	s_nop 1
	v_addc_co_u32_e32 v127, vcc, 0, v159, vcc
	global_load_dwordx4 v[122:125], v[122:123], off nt
	s_nop 0
	global_load_dwordx4 v[126:129], v[126:127], off nt
	s_waitcnt vmcnt(39)
	v_bfe_u32 v141, v2, 16, 1
	v_add3_u32 v2, v2, v141, s78
	s_waitcnt vmcnt(38)
	v_bfe_u32 v141, v6, 16, 1
	v_lshrrev_b32_e32 v2, 16, v2
	v_add3_u32 v6, v6, v141, s78
	v_and_or_b32 v172, v6, s79, v2
	s_waitcnt vmcnt(37)
	v_bfe_u32 v2, v10, 16, 1
	v_add3_u32 v2, v10, v2, s78
	s_waitcnt vmcnt(36)
	v_bfe_u32 v6, v14, 16, 1
	v_lshrrev_b32_e32 v2, 16, v2
	v_add3_u32 v6, v14, v6, s78
	v_and_or_b32 v173, v6, s79, v2
	s_waitcnt vmcnt(35)
	v_bfe_u32 v2, v18, 16, 1
	v_add3_u32 v2, v18, v2, s78
	s_waitcnt vmcnt(34)
	v_bfe_u32 v6, v22, 16, 1
	v_lshrrev_b32_e32 v2, 16, v2
	v_add3_u32 v6, v22, v6, s78
	v_and_or_b32 v174, v6, s79, v2
	s_waitcnt vmcnt(33)
	v_bfe_u32 v2, v26, 16, 1
	v_add3_u32 v2, v26, v2, s78
	s_waitcnt vmcnt(32)
	v_bfe_u32 v6, v34, 16, 1
	v_lshrrev_b32_e32 v2, 16, v2
	v_add3_u32 v6, v34, v6, s78
	v_and_or_b32 v175, v6, s79, v2
	s_waitcnt vmcnt(31)
	v_bfe_u32 v2, v30, 16, 1
	v_add3_u32 v2, v30, v2, s78
	s_waitcnt vmcnt(30)
	v_bfe_u32 v6, v38, 16, 1
	v_lshrrev_b32_e32 v2, 16, v2
	v_add3_u32 v6, v38, v6, s78
	v_and_or_b32 v176, v6, s79, v2
	s_waitcnt vmcnt(29)
	v_bfe_u32 v2, v42, 16, 1
	v_add3_u32 v2, v42, v2, s78
	s_waitcnt vmcnt(28)
	v_bfe_u32 v6, v46, 16, 1
	v_lshrrev_b32_e32 v2, 16, v2
	v_add3_u32 v6, v46, v6, s78
	v_and_or_b32 v177, v6, s79, v2
	s_waitcnt vmcnt(27)
	v_bfe_u32 v2, v50, 16, 1
	v_add3_u32 v2, v50, v2, s78
	s_waitcnt vmcnt(26)
	v_bfe_u32 v6, v54, 16, 1
	v_lshrrev_b32_e32 v2, 16, v2
	v_add3_u32 v6, v54, v6, s78
	v_and_or_b32 v178, v6, s79, v2
	s_waitcnt vmcnt(25)
	v_bfe_u32 v2, v58, 16, 1
	v_add3_u32 v2, v58, v2, s78
	s_waitcnt vmcnt(24)
	v_bfe_u32 v6, v62, 16, 1
	v_lshrrev_b32_e32 v2, 16, v2
	v_add3_u32 v6, v62, v6, s78
	v_and_or_b32 v179, v6, s79, v2
	v_bfe_u32 v2, v3, 16, 1
	v_add3_u32 v2, v3, v2, s78
	v_bfe_u32 v3, v7, 16, 1
	v_lshrrev_b32_e32 v2, 16, v2
	v_add3_u32 v3, v7, v3, s78
	ds_write_b128 v163, v[172:175]
	ds_write_b128 v163, v[176:179] offset:16
	v_and_or_b32 v172, v3, s79, v2
	v_bfe_u32 v2, v11, 16, 1
	v_add3_u32 v2, v11, v2, s78
	v_bfe_u32 v3, v15, 16, 1
	v_lshrrev_b32_e32 v2, 16, v2
	v_add3_u32 v3, v15, v3, s78
	v_and_or_b32 v173, v3, s79, v2
	v_bfe_u32 v2, v19, 16, 1
	v_add3_u32 v2, v19, v2, s78
	v_bfe_u32 v3, v23, 16, 1
	v_lshrrev_b32_e32 v2, 16, v2
	v_add3_u32 v3, v23, v3, s78
	v_and_or_b32 v174, v3, s79, v2
	v_bfe_u32 v2, v27, 16, 1
	v_add3_u32 v2, v27, v2, s78
	v_bfe_u32 v3, v35, 16, 1
	v_lshrrev_b32_e32 v2, 16, v2
	v_add3_u32 v3, v35, v3, s78
	v_and_or_b32 v175, v3, s79, v2
	v_bfe_u32 v2, v31, 16, 1
	v_add3_u32 v2, v31, v2, s78
	v_bfe_u32 v3, v39, 16, 1
	v_lshrrev_b32_e32 v2, 16, v2
	v_add3_u32 v3, v39, v3, s78
	v_and_or_b32 v176, v3, s79, v2
	v_bfe_u32 v2, v43, 16, 1
	v_add3_u32 v2, v43, v2, s78
	v_bfe_u32 v3, v47, 16, 1
	v_lshrrev_b32_e32 v2, 16, v2
	v_add3_u32 v3, v47, v3, s78
	v_and_or_b32 v177, v3, s79, v2
	v_bfe_u32 v2, v51, 16, 1
	v_add3_u32 v2, v51, v2, s78
	v_bfe_u32 v3, v55, 16, 1
	v_lshrrev_b32_e32 v2, 16, v2
	v_add3_u32 v3, v55, v3, s78
	v_and_or_b32 v178, v3, s79, v2
	v_bfe_u32 v2, v59, 16, 1
	v_add3_u32 v2, v59, v2, s78
	v_bfe_u32 v3, v63, 16, 1
	v_lshrrev_b32_e32 v2, 16, v2
	v_add3_u32 v3, v63, v3, s78
	v_and_or_b32 v179, v3, s79, v2
	v_bfe_u32 v2, v4, 16, 1
	v_add3_u32 v2, v4, v2, s78
	v_bfe_u32 v3, v8, 16, 1
	v_lshrrev_b32_e32 v2, 16, v2
	v_add3_u32 v3, v8, v3, s78
	ds_write_b128 v163, v[172:175] offset:144
	ds_write_b128 v163, v[176:179] offset:160
	v_and_or_b32 v172, v3, s79, v2
	v_bfe_u32 v2, v12, 16, 1
	v_add3_u32 v2, v12, v2, s78
	v_bfe_u32 v3, v16, 16, 1
	v_lshrrev_b32_e32 v2, 16, v2
	v_add3_u32 v3, v16, v3, s78
	v_and_or_b32 v173, v3, s79, v2
	v_bfe_u32 v2, v20, 16, 1
	v_add3_u32 v2, v20, v2, s78
	v_bfe_u32 v3, v24, 16, 1
	v_lshrrev_b32_e32 v2, 16, v2
	v_add3_u32 v3, v24, v3, s78
	v_and_or_b32 v174, v3, s79, v2
	v_bfe_u32 v2, v28, 16, 1
	v_add3_u32 v2, v28, v2, s78
	v_bfe_u32 v3, v36, 16, 1
	v_lshrrev_b32_e32 v2, 16, v2
	v_add3_u32 v3, v36, v3, s78
	v_and_or_b32 v175, v3, s79, v2
	v_bfe_u32 v2, v32, 16, 1
	v_add3_u32 v2, v32, v2, s78
	v_bfe_u32 v3, v40, 16, 1
	v_lshrrev_b32_e32 v2, 16, v2
	v_add3_u32 v3, v40, v3, s78
	v_and_or_b32 v176, v3, s79, v2
	v_bfe_u32 v2, v44, 16, 1
	v_add3_u32 v2, v44, v2, s78
	v_bfe_u32 v3, v48, 16, 1
	v_lshrrev_b32_e32 v2, 16, v2
	v_add3_u32 v3, v48, v3, s78
	v_and_or_b32 v177, v3, s79, v2
	v_bfe_u32 v2, v52, 16, 1
	v_add3_u32 v2, v52, v2, s78
	v_bfe_u32 v3, v56, 16, 1
	v_lshrrev_b32_e32 v2, 16, v2
	v_add3_u32 v3, v56, v3, s78
	v_and_or_b32 v178, v3, s79, v2
	v_bfe_u32 v2, v60, 16, 1
	v_add3_u32 v2, v60, v2, s78
	v_bfe_u32 v3, v64, 16, 1
	v_lshrrev_b32_e32 v2, 16, v2
	v_add3_u32 v3, v64, v3, s78
	v_and_or_b32 v179, v3, s79, v2
	v_bfe_u32 v2, v5, 16, 1
	v_add3_u32 v2, v5, v2, s78
	v_bfe_u32 v3, v9, 16, 1
	v_lshrrev_b32_e32 v2, 16, v2
	v_add3_u32 v3, v9, v3, s78
	v_and_or_b32 v2, v3, s79, v2
	v_bfe_u32 v3, v13, 16, 1
	v_add3_u32 v3, v13, v3, s78
	v_bfe_u32 v4, v17, 16, 1
	v_lshrrev_b32_e32 v3, 16, v3
	v_add3_u32 v4, v17, v4, s78
	v_and_or_b32 v3, v4, s79, v3
	v_bfe_u32 v4, v21, 16, 1
	v_add3_u32 v4, v21, v4, s78
	v_bfe_u32 v5, v25, 16, 1
	v_lshrrev_b32_e32 v4, 16, v4
	v_add3_u32 v5, v25, v5, s78
	v_and_or_b32 v4, v5, s79, v4
	v_bfe_u32 v5, v29, 16, 1
	v_add3_u32 v5, v29, v5, s78
	v_bfe_u32 v6, v37, 16, 1
	v_lshrrev_b32_e32 v5, 16, v5
	v_add3_u32 v6, v37, v6, s78
	v_and_or_b32 v5, v6, s79, v5
	v_bfe_u32 v6, v33, 16, 1
	v_add3_u32 v6, v33, v6, s78
	v_bfe_u32 v7, v41, 16, 1
	v_lshrrev_b32_e32 v6, 16, v6
	v_add3_u32 v7, v41, v7, s78
	v_and_or_b32 v6, v7, s79, v6
	v_bfe_u32 v7, v45, 16, 1
	v_add3_u32 v7, v45, v7, s78
	v_bfe_u32 v8, v49, 16, 1
	v_lshrrev_b32_e32 v7, 16, v7
	v_add3_u32 v8, v49, v8, s78
	v_and_or_b32 v7, v8, s79, v7
	v_bfe_u32 v8, v53, 16, 1
	v_add3_u32 v8, v53, v8, s78
	v_bfe_u32 v9, v57, 16, 1
	v_lshrrev_b32_e32 v8, 16, v8
	v_add3_u32 v9, v57, v9, s78
	v_and_or_b32 v8, v9, s79, v8
	v_bfe_u32 v9, v61, 16, 1
	v_add3_u32 v9, v61, v9, s78
	v_bfe_u32 v10, v65, 16, 1
	v_lshrrev_b32_e32 v9, 16, v9
	v_add3_u32 v10, v65, v10, s78
	ds_write_b128 v163, v[172:175] offset:288
	ds_write_b128 v163, v[176:179] offset:304
	v_and_or_b32 v9, v10, s79, v9
	ds_write_b128 v163, v[2:5] offset:432
	ds_write_b128 v163, v[6:9] offset:448
	s_waitcnt lgkmcnt(0)
	ds_read_b128 v[2:5], v171
	ds_read_b128 v[6:9], v171 offset:1152
	ds_read_b128 v[10:13], v171 offset:2304
	s_waitcnt lgkmcnt(2)
	global_store_dwordx4 v[142:143], v[2:5], off offset:128
	s_waitcnt lgkmcnt(1)
	global_store_dwordx4 v[144:145], v[6:9], off offset:128
	s_waitcnt lgkmcnt(0)
	global_store_dwordx4 v[146:147], v[10:13], off offset:128
	ds_read_b128 v[2:5], v171 offset:3456
	ds_read_b128 v[6:9], v171 offset:4608
	ds_read_b128 v[10:13], v171 offset:5760
	ds_read_b128 v[14:17], v171 offset:6912
	ds_read_b128 v[18:21], v171 offset:8064
	s_waitcnt lgkmcnt(4)
	global_store_dwordx4 v[148:149], v[2:5], off offset:128
	s_waitcnt lgkmcnt(3)
	global_store_dwordx4 v[150:151], v[6:9], off offset:128
	s_waitcnt lgkmcnt(2)
	global_store_dwordx4 v[152:153], v[10:13], off offset:128
	s_waitcnt lgkmcnt(1)
	global_store_dwordx4 v[154:155], v[14:17], off offset:128
	s_waitcnt lgkmcnt(0)
	global_store_dwordx4 v[156:157], v[18:21], off offset:128
	v_add_co_u32_e32 v2, vcc, s54, v158
	s_waitcnt lgkmcnt(0)
	s_nop 1
	v_addc_co_u32_e32 v3, vcc, 0, v159, vcc
	v_add_co_u32_e32 v6, vcc, s55, v158
	s_nop 1
	v_addc_co_u32_e32 v7, vcc, 0, v159, vcc
	v_add_co_u32_e32 v10, vcc, s72, v158
	global_load_dwordx4 v[2:5], v[2:3], off nt
	s_nop 0
	global_load_dwordx4 v[6:9], v[6:7], off nt
	v_addc_co_u32_e32 v11, vcc, 0, v159, vcc
	v_add_co_u32_e32 v14, vcc, s73, v158
	s_nop 1
	v_addc_co_u32_e32 v15, vcc, 0, v159, vcc
	v_add_co_u32_e32 v18, vcc, s86, v158
	global_load_dwordx4 v[10:13], v[10:11], off nt
	s_nop 0
	global_load_dwordx4 v[14:17], v[14:15], off nt
	v_addc_co_u32_e32 v19, vcc, 0, v159, vcc
	v_add_co_u32_e32 v22, vcc, s87, v158
	s_nop 1
	v_addc_co_u32_e32 v23, vcc, 0, v159, vcc
	v_add_co_u32_e32 v26, vcc, s64, v158
	global_load_dwordx4 v[18:21], v[18:19], off nt
	s_nop 0
	global_load_dwordx4 v[22:25], v[22:23], off nt
	v_addc_co_u32_e32 v27, vcc, 0, v159, vcc
	v_add_co_u32_e32 v30, vcc, s65, v158
	s_nop 1
	v_addc_co_u32_e32 v31, vcc, 0, v159, vcc
	v_add_co_u32_e32 v34, vcc, s70, v158
	global_load_dwordx4 v[26:29], v[26:27], off nt
	s_nop 0
	global_load_dwordx4 v[30:33], v[30:31], off nt
	v_addc_co_u32_e32 v35, vcc, 0, v159, vcc
	v_add_co_u32_e32 v38, vcc, s71, v158
	s_nop 1
	v_addc_co_u32_e32 v39, vcc, 0, v159, vcc
	v_add_co_u32_e32 v42, vcc, s66, v158
	global_load_dwordx4 v[34:37], v[34:35], off nt
	s_nop 0
	global_load_dwordx4 v[38:41], v[38:39], off nt
	v_addc_co_u32_e32 v43, vcc, 0, v159, vcc
	v_add_co_u32_e32 v46, vcc, s67, v158
	s_nop 1
	v_addc_co_u32_e32 v47, vcc, 0, v159, vcc
	v_add_co_u32_e32 v50, vcc, s52, v158
	global_load_dwordx4 v[42:45], v[42:43], off nt
	s_nop 0
	global_load_dwordx4 v[46:49], v[46:47], off nt
	v_addc_co_u32_e32 v51, vcc, 0, v159, vcc
	v_add_co_u32_e32 v54, vcc, s53, v158
	s_nop 1
	v_addc_co_u32_e32 v55, vcc, 0, v159, vcc
	v_add_co_u32_e32 v58, vcc, s62, v158
	global_load_dwordx4 v[50:53], v[50:51], off nt
	s_nop 0
	global_load_dwordx4 v[54:57], v[54:55], off nt
	v_addc_co_u32_e32 v59, vcc, 0, v159, vcc
	v_add_co_u32_e32 v62, vcc, s63, v158
	s_nop 1
	v_addc_co_u32_e32 v63, vcc, 0, v159, vcc
	global_load_dwordx4 v[58:61], v[58:59], off nt
	s_nop 0
	global_load_dwordx4 v[62:65], v[62:63], off nt
	s_waitcnt vmcnt(39)
	v_bfe_u32 v141, v66, 16, 1
	v_add3_u32 v66, v66, v141, s78
	s_waitcnt vmcnt(38)
	v_bfe_u32 v141, v70, 16, 1
	v_lshrrev_b32_e32 v66, 16, v66
	v_add3_u32 v70, v70, v141, s78
	v_and_or_b32 v172, v70, s79, v66
	s_waitcnt vmcnt(37)
	v_bfe_u32 v66, v74, 16, 1
	v_add3_u32 v66, v74, v66, s78
	s_waitcnt vmcnt(36)
	v_bfe_u32 v70, v78, 16, 1
	v_lshrrev_b32_e32 v66, 16, v66
	v_add3_u32 v70, v78, v70, s78
	v_and_or_b32 v173, v70, s79, v66
	s_waitcnt vmcnt(35)
	v_bfe_u32 v66, v82, 16, 1
	v_add3_u32 v66, v82, v66, s78
	s_waitcnt vmcnt(34)
	v_bfe_u32 v70, v86, 16, 1
	v_lshrrev_b32_e32 v66, 16, v66
	v_add3_u32 v70, v86, v70, s78
	v_and_or_b32 v174, v70, s79, v66
	s_waitcnt vmcnt(33)
	v_bfe_u32 v66, v90, 16, 1
	v_add3_u32 v66, v90, v66, s78
	s_waitcnt vmcnt(32)
	v_bfe_u32 v70, v94, 16, 1
	v_lshrrev_b32_e32 v66, 16, v66
	v_add3_u32 v70, v94, v70, s78
	v_and_or_b32 v175, v70, s79, v66
	s_waitcnt vmcnt(31)
	v_bfe_u32 v66, v98, 16, 1
	v_add3_u32 v66, v98, v66, s78
	s_waitcnt vmcnt(30)
	v_bfe_u32 v70, v102, 16, 1
	v_lshrrev_b32_e32 v66, 16, v66
	v_add3_u32 v70, v102, v70, s78
	v_and_or_b32 v176, v70, s79, v66
	s_waitcnt vmcnt(29)
	v_bfe_u32 v66, v106, 16, 1
	v_add3_u32 v66, v106, v66, s78
	s_waitcnt vmcnt(28)
	v_bfe_u32 v70, v110, 16, 1
	v_lshrrev_b32_e32 v66, 16, v66
	v_add3_u32 v70, v110, v70, s78
	v_and_or_b32 v177, v70, s79, v66
	s_waitcnt vmcnt(27)
	v_bfe_u32 v66, v114, 16, 1
	v_add3_u32 v66, v114, v66, s78
	s_waitcnt vmcnt(26)
	v_bfe_u32 v70, v118, 16, 1
	v_lshrrev_b32_e32 v66, 16, v66
	v_add3_u32 v70, v118, v70, s78
	v_and_or_b32 v178, v70, s79, v66
	s_waitcnt vmcnt(25)
	v_bfe_u32 v66, v122, 16, 1
	v_add3_u32 v66, v122, v66, s78
	s_waitcnt vmcnt(24)
	v_bfe_u32 v70, v126, 16, 1
	v_lshrrev_b32_e32 v66, 16, v66
	v_add3_u32 v70, v126, v70, s78
	v_and_or_b32 v179, v70, s79, v66
	v_bfe_u32 v66, v67, 16, 1
	v_add3_u32 v66, v67, v66, s78
	v_bfe_u32 v67, v71, 16, 1
	v_lshrrev_b32_e32 v66, 16, v66
	v_add3_u32 v67, v71, v67, s78
	ds_write_b128 v163, v[172:175]
	ds_write_b128 v163, v[176:179] offset:16
	v_and_or_b32 v172, v67, s79, v66
	v_bfe_u32 v66, v75, 16, 1
	v_add3_u32 v66, v75, v66, s78
	v_bfe_u32 v67, v79, 16, 1
	v_lshrrev_b32_e32 v66, 16, v66
	v_add3_u32 v67, v79, v67, s78
	v_and_or_b32 v173, v67, s79, v66
	v_bfe_u32 v66, v83, 16, 1
	v_add3_u32 v66, v83, v66, s78
	v_bfe_u32 v67, v87, 16, 1
	v_lshrrev_b32_e32 v66, 16, v66
	v_add3_u32 v67, v87, v67, s78
	v_and_or_b32 v174, v67, s79, v66
	v_bfe_u32 v66, v91, 16, 1
	v_add3_u32 v66, v91, v66, s78
	v_bfe_u32 v67, v95, 16, 1
	v_lshrrev_b32_e32 v66, 16, v66
	v_add3_u32 v67, v95, v67, s78
	v_and_or_b32 v175, v67, s79, v66
	v_bfe_u32 v66, v99, 16, 1
	v_add3_u32 v66, v99, v66, s78
	v_bfe_u32 v67, v103, 16, 1
	v_lshrrev_b32_e32 v66, 16, v66
	v_add3_u32 v67, v103, v67, s78
	v_and_or_b32 v176, v67, s79, v66
	v_bfe_u32 v66, v107, 16, 1
	v_add3_u32 v66, v107, v66, s78
	v_bfe_u32 v67, v111, 16, 1
	v_lshrrev_b32_e32 v66, 16, v66
	v_add3_u32 v67, v111, v67, s78
	v_and_or_b32 v177, v67, s79, v66
	v_bfe_u32 v66, v115, 16, 1
	v_add3_u32 v66, v115, v66, s78
	v_bfe_u32 v67, v119, 16, 1
	v_lshrrev_b32_e32 v66, 16, v66
	v_add3_u32 v67, v119, v67, s78
	v_and_or_b32 v178, v67, s79, v66
	v_bfe_u32 v66, v123, 16, 1
	v_add3_u32 v66, v123, v66, s78
	v_bfe_u32 v67, v127, 16, 1
	v_lshrrev_b32_e32 v66, 16, v66
	v_add3_u32 v67, v127, v67, s78
	v_and_or_b32 v179, v67, s79, v66
	v_bfe_u32 v66, v68, 16, 1
	v_add3_u32 v66, v68, v66, s78
	v_bfe_u32 v67, v72, 16, 1
	v_lshrrev_b32_e32 v66, 16, v66
	v_add3_u32 v67, v72, v67, s78
	ds_write_b128 v163, v[172:175] offset:144
	ds_write_b128 v163, v[176:179] offset:160
	v_and_or_b32 v172, v67, s79, v66
	v_bfe_u32 v66, v76, 16, 1
	v_add3_u32 v66, v76, v66, s78
	v_bfe_u32 v67, v80, 16, 1
	v_lshrrev_b32_e32 v66, 16, v66
	v_add3_u32 v67, v80, v67, s78
	v_and_or_b32 v173, v67, s79, v66
	v_bfe_u32 v66, v84, 16, 1
	v_add3_u32 v66, v84, v66, s78
	v_bfe_u32 v67, v88, 16, 1
	v_lshrrev_b32_e32 v66, 16, v66
	v_add3_u32 v67, v88, v67, s78
	v_and_or_b32 v174, v67, s79, v66
	v_bfe_u32 v66, v92, 16, 1
	v_add3_u32 v66, v92, v66, s78
	v_bfe_u32 v67, v96, 16, 1
	v_lshrrev_b32_e32 v66, 16, v66
	v_add3_u32 v67, v96, v67, s78
	v_and_or_b32 v175, v67, s79, v66
	v_bfe_u32 v66, v100, 16, 1
	v_add3_u32 v66, v100, v66, s78
	v_bfe_u32 v67, v104, 16, 1
	v_lshrrev_b32_e32 v66, 16, v66
	v_add3_u32 v67, v104, v67, s78
	v_and_or_b32 v176, v67, s79, v66
	v_bfe_u32 v66, v108, 16, 1
	v_add3_u32 v66, v108, v66, s78
	v_bfe_u32 v67, v112, 16, 1
	v_lshrrev_b32_e32 v66, 16, v66
	v_add3_u32 v67, v112, v67, s78
	v_and_or_b32 v177, v67, s79, v66
	v_bfe_u32 v66, v116, 16, 1
	v_add3_u32 v66, v116, v66, s78
	v_bfe_u32 v67, v120, 16, 1
	v_lshrrev_b32_e32 v66, 16, v66
	v_add3_u32 v67, v120, v67, s78
	v_and_or_b32 v178, v67, s79, v66
	v_bfe_u32 v66, v124, 16, 1
	v_add3_u32 v66, v124, v66, s78
	v_bfe_u32 v67, v128, 16, 1
	v_lshrrev_b32_e32 v66, 16, v66
	v_add3_u32 v67, v128, v67, s78
	v_and_or_b32 v179, v67, s79, v66
	v_bfe_u32 v66, v69, 16, 1
	v_add3_u32 v66, v69, v66, s78
	v_bfe_u32 v67, v73, 16, 1
	v_lshrrev_b32_e32 v66, 16, v66
	v_add3_u32 v67, v73, v67, s78
	v_and_or_b32 v66, v67, s79, v66
	v_bfe_u32 v67, v77, 16, 1
	v_add3_u32 v67, v77, v67, s78
	v_bfe_u32 v68, v81, 16, 1
	v_lshrrev_b32_e32 v67, 16, v67
	v_add3_u32 v68, v81, v68, s78
	v_and_or_b32 v67, v68, s79, v67
	v_bfe_u32 v68, v85, 16, 1
	v_add3_u32 v68, v85, v68, s78
	v_bfe_u32 v69, v89, 16, 1
	v_lshrrev_b32_e32 v68, 16, v68
	v_add3_u32 v69, v89, v69, s78
	v_and_or_b32 v68, v69, s79, v68
	v_bfe_u32 v69, v93, 16, 1
	v_add3_u32 v69, v93, v69, s78
	v_bfe_u32 v70, v97, 16, 1
	v_lshrrev_b32_e32 v69, 16, v69
	v_add3_u32 v70, v97, v70, s78
	v_and_or_b32 v69, v70, s79, v69
	v_bfe_u32 v70, v101, 16, 1
	v_add3_u32 v70, v101, v70, s78
	v_bfe_u32 v71, v105, 16, 1
	v_lshrrev_b32_e32 v70, 16, v70
	v_add3_u32 v71, v105, v71, s78
	v_and_or_b32 v70, v71, s79, v70
	v_bfe_u32 v71, v109, 16, 1
	v_add3_u32 v71, v109, v71, s78
	v_bfe_u32 v72, v113, 16, 1
	v_lshrrev_b32_e32 v71, 16, v71
	v_add3_u32 v72, v113, v72, s78
	v_and_or_b32 v71, v72, s79, v71
	v_bfe_u32 v72, v117, 16, 1
	v_add3_u32 v72, v117, v72, s78
	v_bfe_u32 v73, v121, 16, 1
	v_lshrrev_b32_e32 v72, 16, v72
	v_add3_u32 v73, v121, v73, s78
	v_and_or_b32 v72, v73, s79, v72
	v_bfe_u32 v73, v125, 16, 1
	v_add3_u32 v73, v125, v73, s78
	v_bfe_u32 v74, v129, 16, 1
	v_lshrrev_b32_e32 v73, 16, v73
	v_add3_u32 v74, v129, v74, s78
	ds_write_b128 v163, v[172:175] offset:288
	ds_write_b128 v163, v[176:179] offset:304
	v_and_or_b32 v73, v74, s79, v73
	ds_write_b128 v163, v[66:69] offset:432
	ds_write_b128 v163, v[70:73] offset:448
	s_waitcnt lgkmcnt(0)
	ds_read_b128 v[66:69], v171
	ds_read_b128 v[70:73], v171 offset:1152
	ds_read_b128 v[74:77], v171 offset:2304
	s_waitcnt lgkmcnt(2)
	global_store_dwordx4 v[142:143], v[66:69], off offset:256
	s_waitcnt lgkmcnt(1)
	global_store_dwordx4 v[144:145], v[70:73], off offset:256
	s_waitcnt lgkmcnt(0)
	global_store_dwordx4 v[146:147], v[74:77], off offset:256
	ds_read_b128 v[66:69], v171 offset:3456
	ds_read_b128 v[70:73], v171 offset:4608
	ds_read_b128 v[74:77], v171 offset:5760
	ds_read_b128 v[78:81], v171 offset:6912
	ds_read_b128 v[82:85], v171 offset:8064
	s_waitcnt lgkmcnt(4)
	global_store_dwordx4 v[148:149], v[66:69], off offset:256
	s_waitcnt lgkmcnt(3)
	global_store_dwordx4 v[150:151], v[70:73], off offset:256
	s_waitcnt lgkmcnt(2)
	global_store_dwordx4 v[152:153], v[74:77], off offset:256
	s_waitcnt lgkmcnt(1)
	global_store_dwordx4 v[154:155], v[78:81], off offset:256
	s_waitcnt lgkmcnt(0)
	global_store_dwordx4 v[156:157], v[82:85], off offset:256
	s_waitcnt vmcnt(23)
	v_bfe_u32 v66, v2, 16, 1
	v_add3_u32 v2, v2, v66, s78
	s_waitcnt vmcnt(22)
	v_bfe_u32 v66, v6, 16, 1
	v_lshrrev_b32_e32 v2, 16, v2
	v_add3_u32 v6, v6, v66, s78
	v_and_or_b32 v66, v6, s79, v2
	s_waitcnt vmcnt(21)
	v_bfe_u32 v2, v10, 16, 1
	v_add3_u32 v2, v10, v2, s78
	s_waitcnt vmcnt(20)
	v_bfe_u32 v6, v14, 16, 1
	v_lshrrev_b32_e32 v2, 16, v2
	v_add3_u32 v6, v14, v6, s78
	v_and_or_b32 v67, v6, s79, v2
	s_waitcnt vmcnt(19)
	v_bfe_u32 v2, v18, 16, 1
	v_add3_u32 v2, v18, v2, s78
	s_waitcnt vmcnt(18)
	v_bfe_u32 v6, v22, 16, 1
	v_lshrrev_b32_e32 v2, 16, v2
	v_add3_u32 v6, v22, v6, s78
	v_and_or_b32 v68, v6, s79, v2
	s_waitcnt vmcnt(17)
	v_bfe_u32 v2, v26, 16, 1
	v_add3_u32 v2, v26, v2, s78
	s_waitcnt vmcnt(16)
	v_bfe_u32 v6, v30, 16, 1
	v_lshrrev_b32_e32 v2, 16, v2
	v_add3_u32 v6, v30, v6, s78
	v_and_or_b32 v69, v6, s79, v2
	s_waitcnt vmcnt(15)
	v_bfe_u32 v2, v34, 16, 1
	v_add3_u32 v2, v34, v2, s78
	s_waitcnt vmcnt(14)
	v_bfe_u32 v6, v38, 16, 1
	v_lshrrev_b32_e32 v2, 16, v2
	v_add3_u32 v6, v38, v6, s78
	v_and_or_b32 v70, v6, s79, v2
	s_waitcnt vmcnt(13)
	v_bfe_u32 v2, v42, 16, 1
	v_add3_u32 v2, v42, v2, s78
	s_waitcnt vmcnt(12)
	v_bfe_u32 v6, v46, 16, 1
	v_lshrrev_b32_e32 v2, 16, v2
	v_add3_u32 v6, v46, v6, s78
	v_and_or_b32 v71, v6, s79, v2
	s_waitcnt vmcnt(11)
	v_bfe_u32 v2, v50, 16, 1
	v_add3_u32 v2, v50, v2, s78
	s_waitcnt vmcnt(10)
	v_bfe_u32 v6, v54, 16, 1
	v_lshrrev_b32_e32 v2, 16, v2
	v_add3_u32 v6, v54, v6, s78
	v_and_or_b32 v72, v6, s79, v2
	s_waitcnt vmcnt(9)
	v_bfe_u32 v2, v58, 16, 1
	v_add3_u32 v2, v58, v2, s78
	s_waitcnt vmcnt(8)
	v_bfe_u32 v6, v62, 16, 1
	v_lshrrev_b32_e32 v2, 16, v2
	v_add3_u32 v6, v62, v6, s78
	v_and_or_b32 v73, v6, s79, v2
	v_bfe_u32 v2, v3, 16, 1
	v_add3_u32 v2, v3, v2, s78
	v_bfe_u32 v3, v7, 16, 1
	s_waitcnt lgkmcnt(0)
	v_lshrrev_b32_e32 v2, 16, v2
	v_add3_u32 v3, v7, v3, s78
	ds_write_b128 v163, v[66:69]
	ds_write_b128 v163, v[70:73] offset:16
	v_and_or_b32 v66, v3, s79, v2
	v_bfe_u32 v2, v11, 16, 1
	v_add3_u32 v2, v11, v2, s78
	v_bfe_u32 v3, v15, 16, 1
	v_lshrrev_b32_e32 v2, 16, v2
	v_add3_u32 v3, v15, v3, s78
	v_and_or_b32 v67, v3, s79, v2
	v_bfe_u32 v2, v19, 16, 1
	v_add3_u32 v2, v19, v2, s78
	v_bfe_u32 v3, v23, 16, 1
	v_lshrrev_b32_e32 v2, 16, v2
	v_add3_u32 v3, v23, v3, s78
	v_and_or_b32 v68, v3, s79, v2
	v_bfe_u32 v2, v27, 16, 1
	v_add3_u32 v2, v27, v2, s78
	v_bfe_u32 v3, v31, 16, 1
	v_lshrrev_b32_e32 v2, 16, v2
	v_add3_u32 v3, v31, v3, s78
	v_and_or_b32 v69, v3, s79, v2
	v_bfe_u32 v2, v35, 16, 1
	v_add3_u32 v2, v35, v2, s78
	v_bfe_u32 v3, v39, 16, 1
	v_lshrrev_b32_e32 v2, 16, v2
	v_add3_u32 v3, v39, v3, s78
	v_and_or_b32 v70, v3, s79, v2
	v_bfe_u32 v2, v43, 16, 1
	v_add3_u32 v2, v43, v2, s78
	v_bfe_u32 v3, v47, 16, 1
	v_lshrrev_b32_e32 v2, 16, v2
	v_add3_u32 v3, v47, v3, s78
	v_and_or_b32 v71, v3, s79, v2
	v_bfe_u32 v2, v51, 16, 1
	v_add3_u32 v2, v51, v2, s78
	v_bfe_u32 v3, v55, 16, 1
	v_lshrrev_b32_e32 v2, 16, v2
	v_add3_u32 v3, v55, v3, s78
	v_and_or_b32 v72, v3, s79, v2
	v_bfe_u32 v2, v59, 16, 1
	v_add3_u32 v2, v59, v2, s78
	v_bfe_u32 v3, v63, 16, 1
	v_lshrrev_b32_e32 v2, 16, v2
	v_add3_u32 v3, v63, v3, s78
	v_and_or_b32 v73, v3, s79, v2
	v_bfe_u32 v2, v4, 16, 1
	v_add3_u32 v2, v4, v2, s78
	v_bfe_u32 v3, v8, 16, 1
	v_lshrrev_b32_e32 v2, 16, v2
	v_add3_u32 v3, v8, v3, s78
	ds_write_b128 v163, v[66:69] offset:144
	ds_write_b128 v163, v[70:73] offset:160
	v_and_or_b32 v66, v3, s79, v2
	v_bfe_u32 v2, v12, 16, 1
	v_add3_u32 v2, v12, v2, s78
	v_bfe_u32 v3, v16, 16, 1
	v_lshrrev_b32_e32 v2, 16, v2
	v_add3_u32 v3, v16, v3, s78
	v_and_or_b32 v67, v3, s79, v2
	v_bfe_u32 v2, v20, 16, 1
	v_add3_u32 v2, v20, v2, s78
	v_bfe_u32 v3, v24, 16, 1
	v_lshrrev_b32_e32 v2, 16, v2
	v_add3_u32 v3, v24, v3, s78
	v_and_or_b32 v68, v3, s79, v2
	v_bfe_u32 v2, v28, 16, 1
	v_add3_u32 v2, v28, v2, s78
	v_bfe_u32 v3, v32, 16, 1
	v_lshrrev_b32_e32 v2, 16, v2
	v_add3_u32 v3, v32, v3, s78
	v_and_or_b32 v69, v3, s79, v2
	v_bfe_u32 v2, v36, 16, 1
	v_add3_u32 v2, v36, v2, s78
	v_bfe_u32 v3, v40, 16, 1
	v_lshrrev_b32_e32 v2, 16, v2
	v_add3_u32 v3, v40, v3, s78
	v_and_or_b32 v70, v3, s79, v2
	v_bfe_u32 v2, v44, 16, 1
	v_add3_u32 v2, v44, v2, s78
	v_bfe_u32 v3, v48, 16, 1
	v_lshrrev_b32_e32 v2, 16, v2
	v_add3_u32 v3, v48, v3, s78
	v_and_or_b32 v71, v3, s79, v2
	v_bfe_u32 v2, v52, 16, 1
	v_add3_u32 v2, v52, v2, s78
	v_bfe_u32 v3, v56, 16, 1
	v_lshrrev_b32_e32 v2, 16, v2
	v_add3_u32 v3, v56, v3, s78
	v_and_or_b32 v72, v3, s79, v2
	v_bfe_u32 v2, v60, 16, 1
	v_add3_u32 v2, v60, v2, s78
	v_bfe_u32 v3, v64, 16, 1
	v_lshrrev_b32_e32 v2, 16, v2
	v_add3_u32 v3, v64, v3, s78
	v_and_or_b32 v73, v3, s79, v2
	v_bfe_u32 v2, v5, 16, 1
	v_add3_u32 v2, v5, v2, s78
	v_bfe_u32 v3, v9, 16, 1
	v_lshrrev_b32_e32 v2, 16, v2
	v_add3_u32 v3, v9, v3, s78
	v_and_or_b32 v2, v3, s79, v2
	v_bfe_u32 v3, v13, 16, 1
	v_add3_u32 v3, v13, v3, s78
	v_bfe_u32 v4, v17, 16, 1
	v_lshrrev_b32_e32 v3, 16, v3
	v_add3_u32 v4, v17, v4, s78
	v_and_or_b32 v3, v4, s79, v3
	v_bfe_u32 v4, v21, 16, 1
	v_add3_u32 v4, v21, v4, s78
	v_bfe_u32 v5, v25, 16, 1
	v_lshrrev_b32_e32 v4, 16, v4
	v_add3_u32 v5, v25, v5, s78
	v_and_or_b32 v4, v5, s79, v4
	v_bfe_u32 v5, v29, 16, 1
	v_add3_u32 v5, v29, v5, s78
	v_bfe_u32 v6, v33, 16, 1
	v_lshrrev_b32_e32 v5, 16, v5
	v_add3_u32 v6, v33, v6, s78
	v_and_or_b32 v5, v6, s79, v5
	v_bfe_u32 v6, v37, 16, 1
	v_add3_u32 v6, v37, v6, s78
	v_bfe_u32 v7, v41, 16, 1
	v_lshrrev_b32_e32 v6, 16, v6
	v_add3_u32 v7, v41, v7, s78
	v_and_or_b32 v6, v7, s79, v6
	v_bfe_u32 v7, v45, 16, 1
	v_add3_u32 v7, v45, v7, s78
	v_bfe_u32 v8, v49, 16, 1
	v_lshrrev_b32_e32 v7, 16, v7
	v_add3_u32 v8, v49, v8, s78
	v_and_or_b32 v7, v8, s79, v7
	v_bfe_u32 v8, v53, 16, 1
	v_add3_u32 v8, v53, v8, s78
	v_bfe_u32 v9, v57, 16, 1
	v_lshrrev_b32_e32 v8, 16, v8
	v_add3_u32 v9, v57, v9, s78
	v_and_or_b32 v8, v9, s79, v8
	v_bfe_u32 v9, v61, 16, 1
	v_add3_u32 v9, v61, v9, s78
	v_bfe_u32 v10, v65, 16, 1
	v_lshrrev_b32_e32 v9, 16, v9
	v_add3_u32 v10, v65, v10, s78
	ds_write_b128 v163, v[66:69] offset:288
	ds_write_b128 v163, v[70:73] offset:304
	v_and_or_b32 v9, v10, s79, v9
	ds_write_b128 v163, v[2:5] offset:432
	ds_write_b128 v163, v[6:9] offset:448
	s_waitcnt lgkmcnt(0)
	ds_read_b128 v[2:5], v171
	ds_read_b128 v[6:9], v171 offset:1152
	ds_read_b128 v[10:13], v171 offset:2304
	s_waitcnt lgkmcnt(2)
	global_store_dwordx4 v[142:143], v[2:5], off offset:384
	s_waitcnt lgkmcnt(1)
	global_store_dwordx4 v[144:145], v[6:9], off offset:384
	s_waitcnt lgkmcnt(0)
	global_store_dwordx4 v[146:147], v[10:13], off offset:384
	ds_read_b128 v[2:5], v171 offset:3456
	ds_read_b128 v[6:9], v171 offset:4608
	ds_read_b128 v[10:13], v171 offset:5760
	ds_read_b128 v[14:17], v171 offset:6912
	ds_read_b128 v[18:21], v171 offset:8064
	s_waitcnt lgkmcnt(4)
	global_store_dwordx4 v[148:149], v[2:5], off offset:384
	s_waitcnt lgkmcnt(3)
	global_store_dwordx4 v[150:151], v[6:9], off offset:384
	s_waitcnt lgkmcnt(2)
	global_store_dwordx4 v[152:153], v[10:13], off offset:384
	s_waitcnt lgkmcnt(1)
	global_store_dwordx4 v[154:155], v[14:17], off offset:384
	s_waitcnt lgkmcnt(0)
	global_store_dwordx4 v[156:157], v[18:21], off offset:384
	s_waitcnt lgkmcnt(0)
	s_mov_b32 s8, 51
